# v8 plus nt hint on the read-once f32 weight loads of the transpose loops
# speedup vs baseline: 1.0251x; 1.0251x over previous
; __global__ void __launch_bounds__(NTHREADS, 2) fwd_megakernel(Args a) {
;     ...
;     cg::grid_group grid = cg::this_grid();
;     if (gridDim.x == 0x7fffffffu) grid.sync();
.LBB0_9:
	s_or_b64 exec, exec, s[8:9]
	v_mov_b32_e32 v2, 0
	global_load_dword v3, v2, s[6:7] offset:32 sc1 nt
	v_and_b32_e32 v1, 0xffff0000, v1
	s_waitcnt vmcnt(0)
	v_and_b32_e32 v3, 0xffff0000, v3
	v_cmp_eq_u32_e32 vcc, v3, v1
	s_and_b64 exec, exec, vcc
	s_cbranch_execz .LBB0_12
	s_mov_b64 s[8:9], 0
.LBB0_11:
	s_sleep 1
	global_load_dword v3, v2, s[6:7] offset:32 sc1 nt
	s_waitcnt vmcnt(0)
	v_and_b32_e32 v3, 0xffff0000, v3
	v_cmp_ne_u32_e32 vcc, v3, v1
	s_or_b64 s[8:9], vcc, s[8:9]
	s_andn2_b64 exec, exec, s[8:9]
	s_cbranch_execnz .LBB0_11

; #define LAS __attribute__((address_space(3)))
; template <int MODE>
; __device__ __forceinline__ void transpose_weight(const float* W, int K, int N, bf16_t* WT, LAS float* scr, int gw, int NGW, int lane, const float* gk = nullptr) {
;     const int nblk = N / 32, nitems = (K / 64) * nblk;
;     const int c = lane & 7;
;     float cur[32], nxt[32];
;     f32x4 gc0 = {1.f, 1.f, 1.f, 1.f}, gc1 = gc0, gn0 = gc0, gn1 = gc0;
;     int it = gw;
;     if (it < nitems) TW_LOAD(it, cur, gc0, gc1);
; __global__ void __launch_bounds__(NTHREADS, 2) fwd_megakernel(Args a) {
;     ...
;     transpose_weight<0>(ap->in[4], DM, NIN, (bf16_t*)(ws + WS_WIN), scr, gw, NGW, lane);
.LBB0_19:
	s_or_b64 exec, exec, s[4:5]
	v_mov_b32_e32 v11, v220
	s_mov_b64 s[14:15], s[0:1]
	s_load_dwordx2 s[12:13], s[14:15], 0xf0
	v_readfirstlane_b32 s4, v11
	s_ashr_i32 s4, s4, 6
	s_lshl_b32 s71, s2, 3
	s_add_i32 s6, s4, s71
	s_lshl_b32 s4, s4, 14
	s_lshl_b32 s69, s44, 3
	v_and_b32_e32 v92, 63, v11
	s_add_i32 s7, s4, 0
	v_and_b32_e32 v10, 7, v11
	s_cmpk_gt_i32 s6, 0xf3f
	v_lshrrev_b32_e32 v93, 5, v92
	v_lshlrev_b32_e32 v12, 2, v11
	v_lshrrev_b32_e32 v94, 3, v92
	v_lshlrev_b32_e32 v0, 4, v10
	s_cbranch_scc1 .LBB0_24
	s_mul_hi_i32 s8, s6, 0x4325c53f
	s_lshr_b32 s9, s8, 31
	s_ashr_i32 s8, s8, 5
	s_add_i32 s9, s8, s9
	s_load_dwordx2 s[4:5], s[14:15], 0x20
	s_mul_i32 s8, s9, 0x7a
	s_sub_i32 s8, s6, s8
	s_lshl_b32 s8, s8, 5
	v_lshl_or_b32 v1, s9, 6, v93
	s_ashr_i32 s9, s8, 31
	s_lshl_b64 s[8:9], s[8:9], 2
	s_waitcnt lgkmcnt(0)
	s_add_u32 s8, s4, s8
	s_addc_u32 s9, s5, s9
	v_and_b32_e32 v4, 0x7c, v12
	v_mov_b32_e32 v5, 0
	v_lshl_add_u64 v[2:3], s[8:9], 0, v[4:5]
	s_movk_i32 s8, 0x3d00
	v_or_b32_e32 v8, 2, v1
	v_mad_i64_i32 v[20:21], s[10:11], v8, s8, v[2:3]
	v_or_b32_e32 v8, 4, v1
	v_mad_i64_i32 v[22:23], s[10:11], v8, s8, v[2:3]
	v_or_b32_e32 v8, 6, v1
	v_mad_i64_i32 v[24:25], s[10:11], v8, s8, v[2:3]
	v_or_b32_e32 v8, 8, v1
	v_mad_i64_i32 v[26:27], s[10:11], v8, s8, v[2:3]
	v_or_b32_e32 v8, 10, v1
	v_mad_i64_i32 v[28:29], s[10:11], v8, s8, v[2:3]
	v_or_b32_e32 v8, 12, v1
	v_mad_i64_i32 v[6:7], s[10:11], v1, s8, v[2:3]
	v_mad_i64_i32 v[30:31], s[10:11], v8, s8, v[2:3]
	v_or_b32_e32 v8, 14, v1
	v_or_b32_e32 v19, 18, v1
	v_mad_i64_i32 v[32:33], s[10:11], v8, s8, v[2:3]
	global_load_dword v8, v[6:7], off nt
	global_load_dword v9, v[20:21], off nt
	global_load_dword v13, v[22:23], off nt
	global_load_dword v14, v[24:25], off nt
	global_load_dword v15, v[26:27], off nt
	global_load_dword v16, v[28:29], off nt
	global_load_dword v17, v[30:31], off nt
	global_load_dword v18, v[32:33], off nt
	v_mad_i64_i32 v[28:29], s[10:11], v19, s8, v[2:3]
	v_or_b32_e32 v19, 20, v1
	v_mad_i64_i32 v[30:31], s[10:11], v19, s8, v[2:3]
	v_or_b32_e32 v19, 22, v1
	v_mad_i64_i32 v[32:33], s[10:11], v19, s8, v[2:3]
	v_or_b32_e32 v19, 24, v1
	v_mad_i64_i32 v[34:35], s[10:11], v19, s8, v[2:3]
	v_or_b32_e32 v19, 26, v1
	v_or_b32_e32 v6, 16, v1
	v_mad_i64_i32 v[36:37], s[10:11], v19, s8, v[2:3]
	v_or_b32_e32 v19, 28, v1
	v_mad_i64_i32 v[6:7], s[10:11], v6, s8, v[2:3]
	v_mad_i64_i32 v[38:39], s[10:11], v19, s8, v[2:3]
	v_or_b32_e32 v19, 30, v1
	v_or_b32_e32 v27, 34, v1
	v_mad_i64_i32 v[40:41], s[10:11], v19, s8, v[2:3]
	global_load_dword v19, v[6:7], off nt
	global_load_dword v20, v[28:29], off nt
	global_load_dword v21, v[30:31], off nt
	global_load_dword v22, v[32:33], off nt
	global_load_dword v23, v[34:35], off nt
	global_load_dword v24, v[36:37], off nt
	global_load_dword v25, v[38:39], off nt
	global_load_dword v26, v[40:41], off nt
	v_mad_i64_i32 v[28:29], s[10:11], v27, s8, v[2:3]
	v_or_b32_e32 v27, 36, v1
	v_mad_i64_i32 v[30:31], s[10:11], v27, s8, v[2:3]
	v_or_b32_e32 v27, 38, v1
	v_mad_i64_i32 v[32:33], s[10:11], v27, s8, v[2:3]
	v_or_b32_e32 v27, 40, v1
	v_mad_i64_i32 v[44:45], s[10:11], v27, s8, v[2:3]
	v_or_b32_e32 v27, 42, v1
	v_mad_i64_i32 v[46:47], s[10:11], v27, s8, v[2:3]
	v_or_b32_e32 v27, 44, v1
	v_or_b32_e32 v6, 32, v1
	v_mad_i64_i32 v[48:49], s[10:11], v27, s8, v[2:3]
	v_or_b32_e32 v27, 46, v1
	v_mad_i64_i32 v[6:7], s[10:11], v6, s8, v[2:3]
	v_mad_i64_i32 v[50:51], s[10:11], v27, s8, v[2:3]
	v_or_b32_e32 v27, 50, v1
	global_load_dword v35, v[6:7], off nt
	global_load_dword v36, v[28:29], off nt
	global_load_dword v37, v[30:31], off nt
	global_load_dword v38, v[32:33], off nt
	global_load_dword v39, v[44:45], off nt
	global_load_dword v40, v[46:47], off nt
	global_load_dword v41, v[48:49], off nt
	global_load_dword v42, v[50:51], off nt
	v_mad_i64_i32 v[28:29], s[10:11], v27, s8, v[2:3]
	v_or_b32_e32 v27, 52, v1
	v_mad_i64_i32 v[30:31], s[10:11], v27, s8, v[2:3]
	v_or_b32_e32 v27, 54, v1
	v_mad_i64_i32 v[32:33], s[10:11], v27, s8, v[2:3]
	v_or_b32_e32 v27, 56, v1
	v_or_b32_e32 v6, 48, v1
	v_mad_i64_i32 v[44:45], s[10:11], v27, s8, v[2:3]
	v_or_b32_e32 v27, 58, v1
	v_mad_i64_i32 v[6:7], s[10:11], v6, s8, v[2:3]
	v_mad_i64_i32 v[46:47], s[10:11], v27, s8, v[2:3]
	v_or_b32_e32 v27, 60, v1
	v_or_b32_e32 v1, 62, v1
	v_mad_i64_i32 v[48:49], s[10:11], v27, s8, v[2:3]
	v_mad_i64_i32 v[2:3], s[10:11], v1, s8, v[2:3]
	global_load_dword v58, v[6:7], off nt
	global_load_dword v59, v[28:29], off nt
	global_load_dword v60, v[30:31], off nt
	global_load_dword v61, v[32:33], off nt
	global_load_dword v62, v[44:45], off nt
	global_load_dword v63, v[46:47], off nt
	global_load_dword v64, v[48:49], off nt
	global_load_dword v65, v[2:3], off nt
	v_lshrrev_b32_e32 v6, 3, v92
	v_mov_b32_e32 v1, v5
	v_lshl_add_u64 v[2:3], s[4:5], 0, v[4:5]
	v_add_u32_e32 v7, s7, v4
	v_mul_u32_u24_e32 v27, 0x420, v10
	v_lshl_add_u64 v[4:5], s[12:13], 0, v[0:1]
	s_mov_b64 s[4:5], 0x8300000
	v_mul_u32_u24_e32 v28, 0x84, v93
	v_lshlrev_b32_e32 v1, 2, v6
	s_lshl_b32 s10, s69, 5
	v_lshl_add_u64 v[4:5], v[4:5], 0, s[4:5]
	v_add3_u32 v1, s7, v27, v1
	s_lshl_b32 s9, s6, 5
	v_add_u32_e32 v7, v7, v28
	s_mov_b32 s11, s10
	s_mov_b32 s19, s6
	s_branch .LBB0_22

; template <int MODE>
; __device__ __forceinline__ void transpose_weight(const float* W, int K, int N, bf16_t* WT, LAS float* scr, int gw, int NGW, int lane, const float* gk = nullptr) {
;     ...
;     while (it < nitems) {
;         const int itn = it + NGW;
;         if (itn < nitems) TW_LOAD(itn, nxt, gn0, gn1);
;         const int kb = it / nblk, nb = it % nblk, k0 = 64 * kb, n0 = 32 * nb;
;         int drow = n0;
;         if (MODE == 1) { if (n0 < 2048) drow = 4096 + n0; else if (n0 < 4096) { const int cc = n0 - 2048; drow = (cc >> 7) * 256 + (cc & 127); } else { const int cc = n0 - 4096; drow = (cc >> 7) * 256 + 128 + (cc & 127); } }
; #pragma unroll
;         for (int i = 0; i < 32; ++i) { const int kk = 2 * i + (lane >> 5); scr[kk * 33 + (lane & 31)] = cur[i]; }
.LBB0_22:
	s_add_i32 s18, s19, s69
	s_cmpk_gt_i32 s18, 0xf3f
	s_cselect_b64 s[4:5], -1, 0
	s_and_b64 vcc, exec, s[4:5]
	s_cbranch_vccnz .LBB0_21
	s_mul_hi_i32 s20, s18, 0x4325c53f
	s_lshr_b32 s21, s20, 31
	s_ashr_i32 s20, s20, 5
	s_add_i32 s21, s20, s21
	s_mul_i32 s20, s21, 0xfffff0c0
	s_add_i32 s22, s9, s11
	s_add_i32 s20, s22, s20
	v_lshl_or_b32 v90, s21, 6, v93
	s_ashr_i32 s21, s20, 31
	v_lshl_add_u64 v[68:69], s[20:21], 2, v[2:3]
	v_or_b32_e32 v27, 2, v90
	v_mad_i64_i32 v[46:47], s[20:21], v27, s8, v[68:69]
	v_or_b32_e32 v27, 4, v90
	v_mad_i64_i32 v[48:49], s[20:21], v27, s8, v[68:69]
	v_or_b32_e32 v27, 6, v90
	v_mad_i64_i32 v[50:51], s[20:21], v27, s8, v[68:69]
	v_or_b32_e32 v27, 8, v90
	v_mad_i64_i32 v[52:53], s[20:21], v27, s8, v[68:69]
	v_or_b32_e32 v27, 10, v90
	v_mad_i64_i32 v[54:55], s[20:21], v27, s8, v[68:69]
	v_or_b32_e32 v27, 12, v90
	v_mad_i64_i32 v[44:45], s[20:21], v90, s8, v[68:69]
	v_mad_i64_i32 v[56:57], s[20:21], v27, s8, v[68:69]
	v_or_b32_e32 v27, 14, v90
	v_or_b32_e32 v43, 16, v90
	v_mad_i64_i32 v[66:67], s[20:21], v27, s8, v[68:69]
	global_load_dword v34, v[44:45], off nt
	global_load_dword v33, v[46:47], off nt
	global_load_dword v32, v[48:49], off nt
	global_load_dword v31, v[50:51], off nt
	global_load_dword v30, v[52:53], off nt
	global_load_dword v29, v[54:55], off nt
	global_load_dword v28, v[56:57], off nt
	global_load_dword v27, v[66:67], off nt
	v_mad_i64_i32 v[52:53], s[20:21], v43, s8, v[68:69]
	v_or_b32_e32 v43, 18, v90
	v_mad_i64_i32 v[54:55], s[20:21], v43, s8, v[68:69]
	v_or_b32_e32 v43, 20, v90
	v_mad_i64_i32 v[56:57], s[20:21], v43, s8, v[68:69]
	v_or_b32_e32 v43, 22, v90
	v_mad_i64_i32 v[66:67], s[20:21], v43, s8, v[68:69]
	v_or_b32_e32 v43, 24, v90
	v_mad_i64_i32 v[70:71], s[20:21], v43, s8, v[68:69]
	v_or_b32_e32 v43, 26, v90
	v_mad_i64_i32 v[72:73], s[20:21], v43, s8, v[68:69]
	v_or_b32_e32 v43, 28, v90
	v_mad_i64_i32 v[74:75], s[20:21], v43, s8, v[68:69]
	v_or_b32_e32 v43, 30, v90
	v_or_b32_e32 v51, 32, v90
	v_mad_i64_i32 v[76:77], s[20:21], v43, s8, v[68:69]
	global_load_dword v50, v[52:53], off nt
	global_load_dword v49, v[54:55], off nt
	global_load_dword v48, v[56:57], off nt
	global_load_dword v47, v[66:67], off nt
	global_load_dword v46, v[70:71], off nt
	global_load_dword v45, v[72:73], off nt
	global_load_dword v44, v[74:75], off nt
	global_load_dword v43, v[76:77], off nt
	v_mad_i64_i32 v[70:71], s[20:21], v51, s8, v[68:69]
	v_or_b32_e32 v51, 34, v90
	v_mad_i64_i32 v[72:73], s[20:21], v51, s8, v[68:69]
	v_or_b32_e32 v51, 36, v90
	v_mad_i64_i32 v[74:75], s[20:21], v51, s8, v[68:69]
	v_or_b32_e32 v51, 38, v90
	v_mad_i64_i32 v[76:77], s[20:21], v51, s8, v[68:69]
	v_or_b32_e32 v51, 40, v90
	v_mad_i64_i32 v[78:79], s[20:21], v51, s8, v[68:69]
	v_or_b32_e32 v51, 42, v90
	v_mad_i64_i32 v[80:81], s[20:21], v51, s8, v[68:69]
	v_or_b32_e32 v51, 44, v90
	v_mad_i64_i32 v[82:83], s[20:21], v51, s8, v[68:69]
	v_or_b32_e32 v51, 46, v90
	v_or_b32_e32 v67, 48, v90
	v_mad_i64_i32 v[84:85], s[20:21], v51, s8, v[68:69]
	global_load_dword v66, v[70:71], off nt
	global_load_dword v57, v[72:73], off nt
	global_load_dword v56, v[74:75], off nt
	global_load_dword v55, v[76:77], off nt
	global_load_dword v54, v[78:79], off nt
	global_load_dword v53, v[80:81], off nt
	global_load_dword v52, v[82:83], off nt
	global_load_dword v51, v[84:85], off nt
	v_mad_i64_i32 v[76:77], s[20:21], v67, s8, v[68:69]
	v_or_b32_e32 v67, 50, v90
	v_mad_i64_i32 v[78:79], s[20:21], v67, s8, v[68:69]
	v_or_b32_e32 v67, 52, v90
	v_mad_i64_i32 v[80:81], s[20:21], v67, s8, v[68:69]
	v_or_b32_e32 v67, 54, v90
	v_mad_i64_i32 v[82:83], s[20:21], v67, s8, v[68:69]
	v_or_b32_e32 v67, 56, v90
	v_mad_i64_i32 v[84:85], s[20:21], v67, s8, v[68:69]
	v_or_b32_e32 v67, 58, v90
	v_mad_i64_i32 v[86:87], s[20:21], v67, s8, v[68:69]
	v_or_b32_e32 v67, 60, v90
	v_mad_i64_i32 v[88:89], s[20:21], v67, s8, v[68:69]
	v_or_b32_e32 v67, 62, v90
	v_mad_i64_i32 v[90:91], s[20:21], v67, s8, v[68:69]
	global_load_dword v74, v[76:77], off nt
	global_load_dword v73, v[78:79], off nt
	global_load_dword v72, v[80:81], off nt
	global_load_dword v71, v[82:83], off nt
	global_load_dword v70, v[84:85], off nt
	global_load_dword v69, v[86:87], off nt
	global_load_dword v68, v[88:89], off nt
	global_load_dword v67, v[90:91], off nt
	s_waitcnt vmcnt(62)
	ds_write2_b32 v7, v8, v9 offset1:66
	s_waitcnt vmcnt(60)
	ds_write2_b32 v7, v13, v14 offset0:132 offset1:198
	v_add_u32_e32 v8, 0x400, v7
	s_waitcnt vmcnt(58)
	ds_write2_b32 v8, v15, v16 offset0:8 offset1:74
	s_waitcnt vmcnt(56)
	ds_write2_b32 v8, v17, v18 offset0:140 offset1:206
	v_add_u32_e32 v8, 0x800, v7
	s_waitcnt vmcnt(54)
	ds_write2_b32 v8, v19, v20 offset0:16 offset1:82
	s_waitcnt vmcnt(52)
	ds_write2_b32 v8, v21, v22 offset0:148 offset1:214
	v_add_u32_e32 v8, 0xc00, v7
	s_waitcnt vmcnt(50)
	ds_write2_b32 v8, v23, v24 offset0:24 offset1:90
	s_waitcnt vmcnt(48)
	ds_write2_b32 v8, v25, v26 offset0:156 offset1:222
	v_add_u32_e32 v8, 0x1000, v7
	s_waitcnt vmcnt(46)
	ds_write2_b32 v8, v35, v36 offset0:32 offset1:98
	s_waitcnt vmcnt(44)
	ds_write2_b32 v8, v37, v38 offset0:164 offset1:230
	v_add_u32_e32 v8, 0x1400, v7
	s_waitcnt vmcnt(42)
	ds_write2_b32 v8, v39, v40 offset0:40 offset1:106
	s_waitcnt vmcnt(40)
	ds_write2_b32 v8, v41, v42 offset0:172 offset1:238
	v_add_u32_e32 v8, 0x1800, v7
	s_waitcnt vmcnt(38)
	ds_write2_b32 v8, v58, v59 offset0:48 offset1:114
	s_waitcnt vmcnt(36)
	ds_write2_b32 v8, v60, v61 offset0:180 offset1:246
	v_add_u32_e32 v8, 0x1c00, v7
	s_mul_hi_i32 s19, s19, 0x4325c53f
	s_waitcnt vmcnt(34)
	ds_write2_b32 v8, v62, v63 offset0:56 offset1:122
	s_waitcnt vmcnt(32)
	s_branch .Ltw_join_0
; #define LAS __attribute__((address_space(3)))
; template <int MODE>
; __device__ __forceinline__ void transpose_weight(const float* W, int K, int N, bf16_t* WT, LAS float* scr, int gw, int NGW, int lane, const float* gk = nullptr) {
;     const int nblk = N / 32, nitems = (K / 64) * nblk;
;     const int c = lane & 7;
;     float cur[32], nxt[32];
;     f32x4 gc0 = {1.f, 1.f, 1.f, 1.f}, gc1 = gc0, gn0 = gc0, gn1 = gc0;
;     int it = gw;
;     if (it < nitems) TW_LOAD(it, cur, gc0, gc1);
; __global__ void __launch_bounds__(NTHREADS, 2) fwd_megakernel(Args a) {
;     ...
;     transpose_weight<0>(ap->in[13], 512, 1536, (bf16_t*)(ws + WS_WUQ), scr, gw, NGW, lane);
.LBB0_24:
	s_cmpk_gt_i32 s6, 0x17f
	s_cbranch_scc1 .LBB0_29
	s_mul_hi_i32 s8, s6, 0x2aaaaaab
	s_lshr_b32 s9, s8, 31
	s_ashr_i32 s8, s8, 3
	s_add_i32 s9, s8, s9
	s_load_dwordx2 s[4:5], s[14:15], 0x68
	s_mul_i32 s8, s9, 48
	s_sub_i32 s8, s6, s8
	s_lshl_b32 s8, s8, 5
	v_lshl_or_b32 v1, s9, 6, v93
	s_ashr_i32 s9, s8, 31
	s_lshl_b64 s[8:9], s[8:9], 2
	s_waitcnt lgkmcnt(0)
	s_add_u32 s8, s4, s8
	s_addc_u32 s9, s5, s9
	v_and_b32_e32 v4, 0x7c, v12
	v_mov_b32_e32 v5, 0
	v_lshl_add_u64 v[2:3], s[8:9], 0, v[4:5]
	s_movk_i32 s8, 0x1800
	v_or_b32_e32 v8, 2, v1
	v_mad_i64_i32 v[20:21], s[10:11], v8, s8, v[2:3]
	v_or_b32_e32 v8, 4, v1
	v_mad_i64_i32 v[22:23], s[10:11], v8, s8, v[2:3]
	v_or_b32_e32 v8, 6, v1
	v_mad_i64_i32 v[24:25], s[10:11], v8, s8, v[2:3]
	v_or_b32_e32 v8, 8, v1
	v_mad_i64_i32 v[26:27], s[10:11], v8, s8, v[2:3]
	v_or_b32_e32 v8, 10, v1
	v_mad_i64_i32 v[28:29], s[10:11], v8, s8, v[2:3]
	v_or_b32_e32 v8, 12, v1
	v_mad_i64_i32 v[6:7], s[10:11], v1, s8, v[2:3]
	v_mad_i64_i32 v[30:31], s[10:11], v8, s8, v[2:3]
	v_or_b32_e32 v8, 14, v1
	v_or_b32_e32 v19, 18, v1
	v_mad_i64_i32 v[32:33], s[10:11], v8, s8, v[2:3]
	global_load_dword v8, v[6:7], off nt
	global_load_dword v9, v[20:21], off nt
	global_load_dword v13, v[22:23], off nt
	global_load_dword v14, v[24:25], off nt
	global_load_dword v15, v[26:27], off nt
	global_load_dword v16, v[28:29], off nt
	global_load_dword v17, v[30:31], off nt
	global_load_dword v18, v[32:33], off nt
	v_mad_i64_i32 v[28:29], s[10:11], v19, s8, v[2:3]
	v_or_b32_e32 v19, 20, v1
	v_mad_i64_i32 v[30:31], s[10:11], v19, s8, v[2:3]
	v_or_b32_e32 v19, 22, v1
	v_mad_i64_i32 v[32:33], s[10:11], v19, s8, v[2:3]
	v_or_b32_e32 v19, 24, v1
	v_mad_i64_i32 v[34:35], s[10:11], v19, s8, v[2:3]
	v_or_b32_e32 v19, 26, v1
	v_or_b32_e32 v6, 16, v1
	v_mad_i64_i32 v[36:37], s[10:11], v19, s8, v[2:3]
	v_or_b32_e32 v19, 28, v1
	v_mad_i64_i32 v[6:7], s[10:11], v6, s8, v[2:3]
	v_mad_i64_i32 v[38:39], s[10:11], v19, s8, v[2:3]
	v_or_b32_e32 v19, 30, v1
	v_or_b32_e32 v27, 34, v1
	v_mad_i64_i32 v[40:41], s[10:11], v19, s8, v[2:3]
	global_load_dword v19, v[6:7], off nt
	global_load_dword v20, v[28:29], off nt
	global_load_dword v21, v[30:31], off nt
	global_load_dword v22, v[32:33], off nt
	global_load_dword v23, v[34:35], off nt
	global_load_dword v24, v[36:37], off nt
	global_load_dword v25, v[38:39], off nt
	global_load_dword v26, v[40:41], off nt
	v_mad_i64_i32 v[28:29], s[10:11], v27, s8, v[2:3]
	v_or_b32_e32 v27, 36, v1
	v_mad_i64_i32 v[30:31], s[10:11], v27, s8, v[2:3]
	v_or_b32_e32 v27, 38, v1
	v_mad_i64_i32 v[32:33], s[10:11], v27, s8, v[2:3]
	v_or_b32_e32 v27, 40, v1
	v_mad_i64_i32 v[42:43], s[10:11], v27, s8, v[2:3]
	v_or_b32_e32 v27, 42, v1
	v_mad_i64_i32 v[44:45], s[10:11], v27, s8, v[2:3]
	v_or_b32_e32 v27, 44, v1
	v_or_b32_e32 v6, 32, v1
	v_mad_i64_i32 v[46:47], s[10:11], v27, s8, v[2:3]
	v_or_b32_e32 v27, 46, v1
	v_mad_i64_i32 v[6:7], s[10:11], v6, s8, v[2:3]
	v_mad_i64_i32 v[52:53], s[10:11], v27, s8, v[2:3]
	v_or_b32_e32 v27, 50, v1
	global_load_dword v35, v[6:7], off nt
	global_load_dword v36, v[28:29], off nt
	global_load_dword v37, v[30:31], off nt
	global_load_dword v38, v[32:33], off nt
	global_load_dword v39, v[42:43], off nt
	global_load_dword v40, v[44:45], off nt
	global_load_dword v49, v[46:47], off nt
	global_load_dword v50, v[52:53], off nt
	v_mad_i64_i32 v[28:29], s[10:11], v27, s8, v[2:3]
	v_or_b32_e32 v27, 52, v1
	v_mad_i64_i32 v[30:31], s[10:11], v27, s8, v[2:3]
	v_or_b32_e32 v27, 54, v1
	v_mad_i64_i32 v[32:33], s[10:11], v27, s8, v[2:3]
	v_or_b32_e32 v27, 56, v1
	v_or_b32_e32 v6, 48, v1
	v_mad_i64_i32 v[42:43], s[10:11], v27, s8, v[2:3]
	v_or_b32_e32 v27, 58, v1
	v_mad_i64_i32 v[6:7], s[10:11], v6, s8, v[2:3]
	v_mad_i64_i32 v[44:45], s[10:11], v27, s8, v[2:3]
	v_or_b32_e32 v27, 60, v1
	v_or_b32_e32 v1, 62, v1
	v_mad_i64_i32 v[46:47], s[10:11], v27, s8, v[2:3]
	v_mad_i64_i32 v[2:3], s[10:11], v1, s8, v[2:3]
	global_load_dword v59, v[6:7], off nt
	global_load_dword v60, v[28:29], off nt
	global_load_dword v61, v[30:31], off nt
	global_load_dword v62, v[32:33], off nt
	global_load_dword v63, v[42:43], off nt
	global_load_dword v64, v[44:45], off nt
	global_load_dword v65, v[46:47], off nt
	global_load_dword v66, v[2:3], off nt
	v_lshrrev_b32_e32 v6, 3, v92
	v_mov_b32_e32 v1, v5
	v_lshl_add_u64 v[2:3], s[4:5], 0, v[4:5]
	v_add_u32_e32 v7, s7, v4
	v_mul_u32_u24_e32 v27, 0x420, v10
	v_lshl_add_u64 v[4:5], s[12:13], 0, v[0:1]
	s_mov_b64 s[4:5], 0x9300000
	v_mul_u32_u24_e32 v28, 0x84, v93
	v_lshlrev_b32_e32 v1, 2, v6
	s_lshl_b32 s10, s69, 5
	v_lshl_add_u64 v[4:5], v[4:5], 0, s[4:5]
	v_add3_u32 v1, s7, v27, v1
	s_lshl_b32 s9, s6, 5
	v_add_u32_e32 v7, v7, v28
	s_mov_b32 s11, s10
	s_mov_b32 s19, s6
	s_branch .LBB0_27

; template <int MODE>
; __device__ __forceinline__ void transpose_weight(const float* W, int K, int N, bf16_t* WT, LAS float* scr, int gw, int NGW, int lane, const float* gk = nullptr) {
;     ...
;     while (it < nitems) {
;         const int itn = it + NGW;
;         if (itn < nitems) TW_LOAD(itn, nxt, gn0, gn1);
;         const int kb = it / nblk, nb = it % nblk, k0 = 64 * kb, n0 = 32 * nb;
;         int drow = n0;
;         if (MODE == 1) { if (n0 < 2048) drow = 4096 + n0; else if (n0 < 4096) { const int cc = n0 - 2048; drow = (cc >> 7) * 256 + (cc & 127); } else { const int cc = n0 - 4096; drow = (cc >> 7) * 256 + 128 + (cc & 127); } }
; #pragma unroll
;         for (int i = 0; i < 32; ++i) { const int kk = 2 * i + (lane >> 5); scr[kk * 33 + (lane & 31)] = cur[i]; }
.LBB0_27:
	s_add_i32 s18, s19, s69
	s_cmpk_gt_i32 s18, 0x17f
	s_cselect_b64 s[4:5], -1, 0
	s_and_b64 vcc, exec, s[4:5]
	s_cbranch_vccnz .LBB0_26
	s_mul_hi_i32 s20, s18, 0x2aaaaaab
	s_lshr_b32 s21, s20, 31
	s_ashr_i32 s20, s20, 3
	s_add_i32 s21, s20, s21
	s_mul_i32 s20, s21, 0xfffffa00
	s_add_i32 s22, s9, s11
	s_add_i32 s20, s22, s20
	v_lshl_or_b32 v67, s21, 6, v93
	s_ashr_i32 s21, s20, 31
	v_lshl_add_u64 v[68:69], s[20:21], 2, v[2:3]
	v_or_b32_e32 v27, 2, v67
	v_mad_i64_i32 v[44:45], s[20:21], v27, s8, v[68:69]
	v_or_b32_e32 v27, 4, v67
	v_mad_i64_i32 v[46:47], s[20:21], v27, s8, v[68:69]
	v_or_b32_e32 v27, 6, v67
	v_mad_i64_i32 v[52:53], s[20:21], v27, s8, v[68:69]
	v_or_b32_e32 v27, 8, v67
	v_mad_i64_i32 v[54:55], s[20:21], v27, s8, v[68:69]
	v_or_b32_e32 v27, 10, v67
	v_mad_i64_i32 v[56:57], s[20:21], v27, s8, v[68:69]
	v_or_b32_e32 v27, 12, v67
	v_mad_i64_i32 v[42:43], s[20:21], v67, s8, v[68:69]
	v_mad_i64_i32 v[70:71], s[20:21], v27, s8, v[68:69]
	v_or_b32_e32 v27, 14, v67
	v_or_b32_e32 v41, 16, v67
	v_mad_i64_i32 v[72:73], s[20:21], v27, s8, v[68:69]
	global_load_dword v34, v[42:43], off nt
	global_load_dword v33, v[44:45], off nt
	global_load_dword v32, v[46:47], off nt
	global_load_dword v31, v[52:53], off nt
	global_load_dword v30, v[54:55], off nt
	global_load_dword v29, v[56:57], off nt
	global_load_dword v28, v[70:71], off nt
	global_load_dword v27, v[72:73], off nt
	v_mad_i64_i32 v[52:53], s[20:21], v41, s8, v[68:69]
	v_or_b32_e32 v41, 18, v67
	v_mad_i64_i32 v[54:55], s[20:21], v41, s8, v[68:69]
	v_or_b32_e32 v41, 20, v67
	v_mad_i64_i32 v[56:57], s[20:21], v41, s8, v[68:69]
	v_or_b32_e32 v41, 22, v67
	v_mad_i64_i32 v[70:71], s[20:21], v41, s8, v[68:69]
	v_or_b32_e32 v41, 24, v67
	v_mad_i64_i32 v[72:73], s[20:21], v41, s8, v[68:69]
	v_or_b32_e32 v41, 26, v67
	v_mad_i64_i32 v[74:75], s[20:21], v41, s8, v[68:69]
	v_or_b32_e32 v41, 28, v67
	v_mad_i64_i32 v[76:77], s[20:21], v41, s8, v[68:69]
	v_or_b32_e32 v41, 30, v67
	v_or_b32_e32 v51, 32, v67
	v_mad_i64_i32 v[78:79], s[20:21], v41, s8, v[68:69]
	global_load_dword v48, v[52:53], off nt
	global_load_dword v47, v[54:55], off nt
	global_load_dword v46, v[56:57], off nt
	global_load_dword v45, v[70:71], off nt
	global_load_dword v44, v[72:73], off nt
	global_load_dword v43, v[74:75], off nt
	global_load_dword v42, v[76:77], off nt
	global_load_dword v41, v[78:79], off nt
	v_mad_i64_i32 v[70:71], s[20:21], v51, s8, v[68:69]
	v_or_b32_e32 v51, 34, v67
	v_mad_i64_i32 v[72:73], s[20:21], v51, s8, v[68:69]
	v_or_b32_e32 v51, 36, v67
	v_mad_i64_i32 v[74:75], s[20:21], v51, s8, v[68:69]
	v_or_b32_e32 v51, 38, v67
	v_mad_i64_i32 v[76:77], s[20:21], v51, s8, v[68:69]
	v_or_b32_e32 v51, 40, v67
	v_mad_i64_i32 v[78:79], s[20:21], v51, s8, v[68:69]
	v_or_b32_e32 v51, 42, v67
	v_mad_i64_i32 v[80:81], s[20:21], v51, s8, v[68:69]
	v_or_b32_e32 v51, 44, v67
	v_mad_i64_i32 v[82:83], s[20:21], v51, s8, v[68:69]
	v_or_b32_e32 v51, 46, v67
	v_mad_i64_i32 v[84:85], s[20:21], v51, s8, v[68:69]
	global_load_dword v58, v[70:71], off nt
	global_load_dword v57, v[72:73], off nt
	global_load_dword v56, v[74:75], off nt
	global_load_dword v55, v[76:77], off nt
	global_load_dword v54, v[78:79], off nt
	global_load_dword v53, v[80:81], off nt
	global_load_dword v52, v[82:83], off nt
	global_load_dword v51, v[84:85], off nt
	v_or_b32_e32 v70, 48, v67
	v_mad_i64_i32 v[76:77], s[20:21], v70, s8, v[68:69]
	v_or_b32_e32 v70, 50, v67
	v_mad_i64_i32 v[78:79], s[20:21], v70, s8, v[68:69]
	v_or_b32_e32 v70, 52, v67
	v_mad_i64_i32 v[80:81], s[20:21], v70, s8, v[68:69]
	v_or_b32_e32 v70, 54, v67
	v_mad_i64_i32 v[82:83], s[20:21], v70, s8, v[68:69]
	v_or_b32_e32 v70, 56, v67
	v_mad_i64_i32 v[84:85], s[20:21], v70, s8, v[68:69]
	v_or_b32_e32 v70, 58, v67
	v_mad_i64_i32 v[86:87], s[20:21], v70, s8, v[68:69]
	v_or_b32_e32 v70, 60, v67
	v_or_b32_e32 v67, 62, v67
	v_mad_i64_i32 v[88:89], s[20:21], v70, s8, v[68:69]
	v_mad_i64_i32 v[90:91], s[20:21], v67, s8, v[68:69]
	global_load_dword v74, v[76:77], off nt
	global_load_dword v73, v[78:79], off nt
	global_load_dword v72, v[80:81], off nt
	global_load_dword v71, v[82:83], off nt
	global_load_dword v70, v[84:85], off nt
	global_load_dword v69, v[86:87], off nt
	global_load_dword v68, v[88:89], off nt
	global_load_dword v67, v[90:91], off nt
	s_waitcnt vmcnt(62)
	ds_write2_b32 v7, v8, v9 offset1:66
	s_waitcnt vmcnt(60)
	ds_write2_b32 v7, v13, v14 offset0:132 offset1:198
	v_add_u32_e32 v8, 0x400, v7
	s_waitcnt vmcnt(58)
	ds_write2_b32 v8, v15, v16 offset0:8 offset1:74
	s_waitcnt vmcnt(56)
	ds_write2_b32 v8, v17, v18 offset0:140 offset1:206
	v_add_u32_e32 v8, 0x800, v7
	s_waitcnt vmcnt(54)
	ds_write2_b32 v8, v19, v20 offset0:16 offset1:82
	s_waitcnt vmcnt(52)
	ds_write2_b32 v8, v21, v22 offset0:148 offset1:214
	v_add_u32_e32 v8, 0xc00, v7
	s_waitcnt vmcnt(50)
	ds_write2_b32 v8, v23, v24 offset0:24 offset1:90
	s_waitcnt vmcnt(48)
	ds_write2_b32 v8, v25, v26 offset0:156 offset1:222
	v_add_u32_e32 v8, 0x1000, v7
	s_waitcnt vmcnt(46)
	ds_write2_b32 v8, v35, v36 offset0:32 offset1:98
	s_waitcnt vmcnt(44)
	ds_write2_b32 v8, v37, v38 offset0:164 offset1:230
	v_add_u32_e32 v8, 0x1400, v7
	s_waitcnt vmcnt(42)
	ds_write2_b32 v8, v39, v40 offset0:40 offset1:106
	s_waitcnt vmcnt(40)
	ds_write2_b32 v8, v49, v50 offset0:172 offset1:238
	v_add_u32_e32 v8, 0x1800, v7
	s_waitcnt vmcnt(38)
	ds_write2_b32 v8, v59, v60 offset0:48 offset1:114
	s_waitcnt vmcnt(36)
	ds_write2_b32 v8, v61, v62 offset0:180 offset1:246
	v_add_u32_e32 v8, 0x1c00, v7
	s_mul_hi_i32 s19, s19, 0x2aaaaaab
	s_waitcnt vmcnt(34)
	ds_write2_b32 v8, v63, v64 offset0:56 offset1:122
	s_waitcnt vmcnt(32)
	s_branch .Ltw_join_1
; #define LAS __attribute__((address_space(3)))
; template <int MODE>
; __device__ __forceinline__ void transpose_weight(const float* W, int K, int N, bf16_t* WT, LAS float* scr, int gw, int NGW, int lane, const float* gk = nullptr) {
;     const int nblk = N / 32, nitems = (K / 64) * nblk;
;     const int c = lane & 7;
;     float cur[32], nxt[32];
;     f32x4 gc0 = {1.f, 1.f, 1.f, 1.f}, gc1 = gc0, gn0 = gc0, gn1 = gc0;
;     int it = gw;
;     if (it < nitems) TW_LOAD(it, cur, gc0, gc1);
; __global__ void __launch_bounds__(NTHREADS, 2) fwd_megakernel(Args a) {
;     ...
;     transpose_weight<0>(ap->in[15], 256, 2048, (bf16_t*)(ws + WS_WUKV), scr, gw, NGW, lane);
.LBB0_29:
	s_cmpk_gt_i32 s6, 0xff
	s_cbranch_scc1 .LBB0_34
	s_ashr_i32 s8, s6, 31
	s_lshr_b32 s8, s8, 26
	s_add_i32 s8, s6, s8
	s_load_dwordx2 s[4:5], s[14:15], 0x78
	s_and_b32 s9, s8, 0xffffffc0
	s_sub_i32 s8, s6, s9
	s_lshl_b32 s8, s8, 5
	v_or_b32_e32 v2, s9, v93
	s_ashr_i32 s9, s8, 31
	s_lshl_b64 s[8:9], s[8:9], 2
	s_waitcnt lgkmcnt(0)
	s_add_u32 s8, s4, s8
	v_or_b32_e32 v14, 2, v2
	s_addc_u32 s9, s5, s9
	v_and_b32_e32 v4, 0x7c, v12
	v_mov_b32_e32 v5, 0
	v_ashrrev_i32_e32 v15, 31, v14
	v_lshl_add_u64 v[6:7], s[8:9], 0, v[4:5]
	v_lshlrev_b64 v[14:15], 13, v[14:15]
	v_lshl_add_u64 v[22:23], v[6:7], 0, v[14:15]
	v_or_b32_e32 v14, 4, v2
	v_ashrrev_i32_e32 v15, 31, v14
	v_lshlrev_b64 v[14:15], 13, v[14:15]
	v_lshl_add_u64 v[24:25], v[6:7], 0, v[14:15]
	v_or_b32_e32 v14, 6, v2
	v_ashrrev_i32_e32 v15, 31, v14
	v_lshlrev_b64 v[14:15], 13, v[14:15]
	v_lshl_add_u64 v[26:27], v[6:7], 0, v[14:15]
	v_or_b32_e32 v14, 8, v2
	v_ashrrev_i32_e32 v15, 31, v14
	v_lshlrev_b64 v[14:15], 13, v[14:15]
	v_lshl_add_u64 v[28:29], v[6:7], 0, v[14:15]
	v_or_b32_e32 v14, 10, v2
	v_ashrrev_i32_e32 v15, 31, v14
	v_lshlrev_b64 v[14:15], 13, v[14:15]
	v_lshl_add_u64 v[30:31], v[6:7], 0, v[14:15]
	v_or_b32_e32 v14, 12, v2
	v_ashrrev_i32_e32 v15, 31, v14
	v_lshlrev_b64 v[14:15], 13, v[14:15]
	v_ashrrev_i32_e32 v3, 31, v2
	v_lshl_add_u64 v[32:33], v[6:7], 0, v[14:15]
	v_or_b32_e32 v14, 14, v2
	v_lshlrev_b64 v[8:9], 13, v[2:3]
	v_ashrrev_i32_e32 v15, 31, v14
	v_lshl_add_u64 v[8:9], v[6:7], 0, v[8:9]
	v_lshlrev_b64 v[14:15], 13, v[14:15]
	v_lshl_add_u64 v[34:35], v[6:7], 0, v[14:15]
	global_load_dword v13, v[8:9], off nt
	global_load_dword v14, v[22:23], off nt
	global_load_dword v15, v[24:25], off nt
	global_load_dword v16, v[26:27], off nt
	global_load_dword v17, v[28:29], off nt
	global_load_dword v18, v[30:31], off nt
	global_load_dword v19, v[32:33], off nt
	global_load_dword v20, v[34:35], off nt
	v_or_b32_e32 v22, 18, v2
	v_ashrrev_i32_e32 v23, 31, v22
	v_lshlrev_b64 v[22:23], 13, v[22:23]
	v_lshl_add_u64 v[30:31], v[6:7], 0, v[22:23]
	v_or_b32_e32 v22, 20, v2
	v_ashrrev_i32_e32 v23, 31, v22
	v_lshlrev_b64 v[22:23], 13, v[22:23]
	v_lshl_add_u64 v[32:33], v[6:7], 0, v[22:23]
	v_or_b32_e32 v22, 22, v2
	v_ashrrev_i32_e32 v23, 31, v22
	v_lshlrev_b64 v[22:23], 13, v[22:23]
	v_lshl_add_u64 v[34:35], v[6:7], 0, v[22:23]
	v_or_b32_e32 v22, 24, v2
	v_ashrrev_i32_e32 v23, 31, v22
	v_lshlrev_b64 v[22:23], 13, v[22:23]
	v_lshl_add_u64 v[36:37], v[6:7], 0, v[22:23]
	v_or_b32_e32 v22, 26, v2
	v_ashrrev_i32_e32 v23, 31, v22
	v_lshlrev_b64 v[22:23], 13, v[22:23]
	v_lshl_add_u64 v[38:39], v[6:7], 0, v[22:23]
	v_or_b32_e32 v22, 28, v2
	v_ashrrev_i32_e32 v23, 31, v22
	v_or_b32_e32 v8, 16, v2
	v_lshlrev_b64 v[22:23], 13, v[22:23]
	v_ashrrev_i32_e32 v9, 31, v8
	v_lshl_add_u64 v[40:41], v[6:7], 0, v[22:23]
	v_or_b32_e32 v22, 30, v2
	v_lshlrev_b64 v[8:9], 13, v[8:9]
	v_ashrrev_i32_e32 v23, 31, v22
	v_lshl_add_u64 v[8:9], v[6:7], 0, v[8:9]
	v_lshlrev_b64 v[22:23], 13, v[22:23]
	v_lshl_add_u64 v[42:43], v[6:7], 0, v[22:23]
	global_load_dword v22, v[8:9], off nt
	global_load_dword v23, v[30:31], off nt
	global_load_dword v24, v[32:33], off nt
	global_load_dword v25, v[34:35], off nt
	global_load_dword v26, v[36:37], off nt
	global_load_dword v27, v[38:39], off nt
	global_load_dword v28, v[40:41], off nt
	global_load_dword v29, v[42:43], off nt
	v_or_b32_e32 v30, 34, v2
	v_ashrrev_i32_e32 v31, 31, v30
	v_lshlrev_b64 v[30:31], 13, v[30:31]
	v_lshl_add_u64 v[40:41], v[6:7], 0, v[30:31]
	v_or_b32_e32 v30, 36, v2
	v_ashrrev_i32_e32 v31, 31, v30
	v_lshlrev_b64 v[30:31], 13, v[30:31]
	v_lshl_add_u64 v[42:43], v[6:7], 0, v[30:31]
	v_or_b32_e32 v30, 38, v2
	v_ashrrev_i32_e32 v31, 31, v30
	v_lshlrev_b64 v[30:31], 13, v[30:31]
	v_lshl_add_u64 v[44:45], v[6:7], 0, v[30:31]
	v_or_b32_e32 v30, 40, v2
	v_ashrrev_i32_e32 v31, 31, v30
	v_lshlrev_b64 v[30:31], 13, v[30:31]
	v_lshl_add_u64 v[46:47], v[6:7], 0, v[30:31]
	v_or_b32_e32 v30, 42, v2
	v_ashrrev_i32_e32 v31, 31, v30
	v_lshlrev_b64 v[30:31], 13, v[30:31]
	v_lshl_add_u64 v[48:49], v[6:7], 0, v[30:31]
	v_or_b32_e32 v30, 44, v2
	v_ashrrev_i32_e32 v31, 31, v30
	v_or_b32_e32 v8, 32, v2
	v_lshlrev_b64 v[30:31], 13, v[30:31]
	v_ashrrev_i32_e32 v9, 31, v8
	v_lshl_add_u64 v[50:51], v[6:7], 0, v[30:31]
	v_or_b32_e32 v30, 46, v2
	v_lshlrev_b64 v[8:9], 13, v[8:9]
	v_ashrrev_i32_e32 v31, 31, v30
	v_lshl_add_u64 v[8:9], v[6:7], 0, v[8:9]
	v_lshlrev_b64 v[30:31], 13, v[30:31]
	v_lshl_add_u64 v[52:53], v[6:7], 0, v[30:31]
	global_load_dword v31, v[8:9], off nt
	global_load_dword v32, v[40:41], off nt
	global_load_dword v33, v[42:43], off nt
	global_load_dword v34, v[44:45], off nt
	global_load_dword v35, v[46:47], off nt
	global_load_dword v36, v[48:49], off nt
	global_load_dword v37, v[50:51], off nt
	global_load_dword v38, v[52:53], off nt
	v_or_b32_e32 v46, 56, v2
	v_ashrrev_i32_e32 v47, 31, v46
	v_lshlrev_b64 v[46:47], 13, v[46:47]
	v_lshl_add_u64 v[54:55], v[6:7], 0, v[46:47]
	v_or_b32_e32 v46, 58, v2
	v_ashrrev_i32_e32 v47, 31, v46
	v_or_b32_e32 v8, 48, v2
	v_lshlrev_b64 v[46:47], 13, v[46:47]
	v_ashrrev_i32_e32 v9, 31, v8
	v_or_b32_e32 v40, 50, v2
	v_or_b32_e32 v42, 52, v2
	v_or_b32_e32 v44, 54, v2
	v_lshl_add_u64 v[56:57], v[6:7], 0, v[46:47]
	v_or_b32_e32 v46, 60, v2
	v_or_b32_e32 v2, 62, v2
	v_lshlrev_b64 v[8:9], 13, v[8:9]
	v_ashrrev_i32_e32 v41, 31, v40
	v_ashrrev_i32_e32 v43, 31, v42
	v_ashrrev_i32_e32 v45, 31, v44
	v_ashrrev_i32_e32 v47, 31, v46
	v_ashrrev_i32_e32 v3, 31, v2
	v_lshl_add_u64 v[8:9], v[6:7], 0, v[8:9]
	v_lshlrev_b64 v[40:41], 13, v[40:41]
	v_lshlrev_b64 v[42:43], 13, v[42:43]
	v_lshlrev_b64 v[44:45], 13, v[44:45]
	v_lshlrev_b64 v[46:47], 13, v[46:47]
	v_lshlrev_b64 v[2:3], 13, v[2:3]
	v_lshl_add_u64 v[40:41], v[6:7], 0, v[40:41]
	v_lshl_add_u64 v[42:43], v[6:7], 0, v[42:43]
	v_lshl_add_u64 v[44:45], v[6:7], 0, v[44:45]
	v_lshl_add_u64 v[58:59], v[6:7], 0, v[46:47]
	v_lshl_add_u64 v[2:3], v[6:7], 0, v[2:3]
	global_load_dword v46, v[8:9], off nt
	global_load_dword v47, v[40:41], off nt
	global_load_dword v48, v[42:43], off nt
	global_load_dword v49, v[44:45], off nt
	global_load_dword v50, v[54:55], off nt
	global_load_dword v51, v[56:57], off nt
	global_load_dword v52, v[58:59], off nt
	global_load_dword v53, v[2:3], off nt
	v_lshrrev_b32_e32 v21, 3, v92
	v_mov_b32_e32 v1, v5
	v_lshl_add_u64 v[2:3], s[4:5], 0, v[4:5]
	v_add_u32_e32 v6, s7, v4
	v_mul_u32_u24_e32 v7, 0x420, v10
	v_lshl_add_u64 v[4:5], s[12:13], 0, v[0:1]
	s_mov_b64 s[4:5], 0x9500000
	v_mul_u32_u24_e32 v8, 0x84, v93
	v_lshlrev_b32_e32 v1, 2, v21
	s_lshl_b32 s9, s69, 5
	v_lshl_add_u64 v[4:5], v[4:5], 0, s[4:5]
	v_add3_u32 v1, s7, v7, v1
	s_lshl_b32 s8, s6, 5
	v_add_u32_e32 v30, v6, v8
	s_mov_b32 s10, s9
	s_mov_b32 s18, s6
	s_branch .LBB0_32

; template <int MODE>
; __device__ __forceinline__ void transpose_weight(const float* W, int K, int N, bf16_t* WT, LAS float* scr, int gw, int NGW, int lane, const float* gk = nullptr) {
;     ...
;     while (it < nitems) {
;         const int itn = it + NGW;
;         if (itn < nitems) TW_LOAD(itn, nxt, gn0, gn1);
;         const int kb = it / nblk, nb = it % nblk, k0 = 64 * kb, n0 = 32 * nb;
.LBB0_32:
	s_add_i32 s11, s18, s69
	s_cmpk_gt_i32 s11, 0xff
	s_cselect_b64 s[4:5], -1, 0
	s_and_b64 vcc, exec, s[4:5]
	s_cbranch_vccnz .LBB0_31
	s_ashr_i32 s19, s11, 31
	s_lshr_b32 s19, s19, 26
	s_add_i32 s19, s11, s19
	s_and_b32 s21, s19, 0xffffffc0
	s_lshl_b32 s19, s19, 5
	s_add_i32 s20, s8, s10
	s_and_b32 s19, s19, 0xfffff800
	s_sub_i32 s20, s20, s19
	v_or_b32_e32 v8, s21, v93
	s_ashr_i32 s21, s20, 31
	v_ashrrev_i32_e32 v9, 31, v8
	v_lshl_add_u64 v[6:7], s[20:21], 2, v[2:3]
	v_lshlrev_b64 v[40:41], 13, v[8:9]
	v_lshl_add_u64 v[54:55], v[6:7], 0, v[40:41]
	v_or_b32_e32 v40, 2, v8
	v_ashrrev_i32_e32 v41, 31, v40
	v_lshlrev_b64 v[40:41], 13, v[40:41]
	v_lshl_add_u64 v[56:57], v[6:7], 0, v[40:41]
	v_or_b32_e32 v40, 4, v8
	v_ashrrev_i32_e32 v41, 31, v40
	v_lshlrev_b64 v[40:41], 13, v[40:41]
	v_lshl_add_u64 v[58:59], v[6:7], 0, v[40:41]
	v_or_b32_e32 v40, 6, v8
	v_ashrrev_i32_e32 v41, 31, v40
	v_lshlrev_b64 v[40:41], 13, v[40:41]
	v_lshl_add_u64 v[60:61], v[6:7], 0, v[40:41]
	v_or_b32_e32 v40, 8, v8
	v_ashrrev_i32_e32 v41, 31, v40
	v_lshlrev_b64 v[40:41], 13, v[40:41]
	v_lshl_add_u64 v[62:63], v[6:7], 0, v[40:41]
	v_or_b32_e32 v40, 10, v8
	v_ashrrev_i32_e32 v41, 31, v40
	v_lshlrev_b64 v[40:41], 13, v[40:41]
	v_lshl_add_u64 v[64:65], v[6:7], 0, v[40:41]
	v_or_b32_e32 v40, 12, v8
	v_ashrrev_i32_e32 v41, 31, v40
	v_lshlrev_b64 v[40:41], 13, v[40:41]
	v_lshl_add_u64 v[66:67], v[6:7], 0, v[40:41]
	v_or_b32_e32 v40, 14, v8
	v_ashrrev_i32_e32 v41, 31, v40
	v_lshlrev_b64 v[40:41], 13, v[40:41]
	v_lshl_add_u64 v[68:69], v[6:7], 0, v[40:41]
	global_load_dword v45, v[54:55], off nt
	global_load_dword v44, v[56:57], off nt
	global_load_dword v43, v[58:59], off nt
	global_load_dword v42, v[60:61], off nt
	global_load_dword v41, v[62:63], off nt
	global_load_dword v40, v[64:65], off nt
	global_load_dword v39, v[66:67], off nt
	global_load_dword v9, v[68:69], off nt
	v_or_b32_e32 v54, 16, v8
	v_ashrrev_i32_e32 v55, 31, v54
	v_lshlrev_b64 v[54:55], 13, v[54:55]
	v_lshl_add_u64 v[62:63], v[6:7], 0, v[54:55]
	v_or_b32_e32 v54, 18, v8
	v_ashrrev_i32_e32 v55, 31, v54
	v_lshlrev_b64 v[54:55], 13, v[54:55]
	v_lshl_add_u64 v[64:65], v[6:7], 0, v[54:55]
	v_or_b32_e32 v54, 20, v8
	v_ashrrev_i32_e32 v55, 31, v54
	v_lshlrev_b64 v[54:55], 13, v[54:55]
	v_lshl_add_u64 v[66:67], v[6:7], 0, v[54:55]
	v_or_b32_e32 v54, 22, v8
	v_ashrrev_i32_e32 v55, 31, v54
	v_lshlrev_b64 v[54:55], 13, v[54:55]
	v_lshl_add_u64 v[68:69], v[6:7], 0, v[54:55]
	v_or_b32_e32 v54, 24, v8
	v_ashrrev_i32_e32 v55, 31, v54
	v_lshlrev_b64 v[54:55], 13, v[54:55]
	v_lshl_add_u64 v[70:71], v[6:7], 0, v[54:55]
	v_or_b32_e32 v54, 26, v8
	v_ashrrev_i32_e32 v55, 31, v54
	v_lshlrev_b64 v[54:55], 13, v[54:55]
	v_lshl_add_u64 v[72:73], v[6:7], 0, v[54:55]
	v_or_b32_e32 v54, 28, v8
	v_ashrrev_i32_e32 v55, 31, v54
	v_lshlrev_b64 v[54:55], 13, v[54:55]
	v_lshl_add_u64 v[74:75], v[6:7], 0, v[54:55]
	v_or_b32_e32 v54, 30, v8
	v_ashrrev_i32_e32 v55, 31, v54
	v_lshlrev_b64 v[54:55], 13, v[54:55]
	v_lshl_add_u64 v[76:77], v[6:7], 0, v[54:55]
	global_load_dword v61, v[62:63], off nt
	global_load_dword v60, v[64:65], off nt
	global_load_dword v59, v[66:67], off nt
	global_load_dword v58, v[68:69], off nt
	global_load_dword v57, v[70:71], off nt
	global_load_dword v56, v[72:73], off nt
	global_load_dword v55, v[74:75], off nt
	global_load_dword v54, v[76:77], off nt
	v_or_b32_e32 v62, 32, v8
	v_ashrrev_i32_e32 v63, 31, v62
	v_lshlrev_b64 v[62:63], 13, v[62:63]
	v_lshl_add_u64 v[70:71], v[6:7], 0, v[62:63]
	v_or_b32_e32 v62, 34, v8
	v_ashrrev_i32_e32 v63, 31, v62
	v_lshlrev_b64 v[62:63], 13, v[62:63]
	v_lshl_add_u64 v[72:73], v[6:7], 0, v[62:63]
	v_or_b32_e32 v62, 36, v8
	v_ashrrev_i32_e32 v63, 31, v62
	v_lshlrev_b64 v[62:63], 13, v[62:63]
	v_lshl_add_u64 v[74:75], v[6:7], 0, v[62:63]
	v_or_b32_e32 v62, 38, v8
	v_ashrrev_i32_e32 v63, 31, v62
	v_lshlrev_b64 v[62:63], 13, v[62:63]
	v_lshl_add_u64 v[76:77], v[6:7], 0, v[62:63]
	v_or_b32_e32 v62, 40, v8
	v_ashrrev_i32_e32 v63, 31, v62
	v_lshlrev_b64 v[62:63], 13, v[62:63]
	v_lshl_add_u64 v[78:79], v[6:7], 0, v[62:63]
	v_or_b32_e32 v62, 42, v8
	v_ashrrev_i32_e32 v63, 31, v62
	v_lshlrev_b64 v[62:63], 13, v[62:63]
	v_lshl_add_u64 v[80:81], v[6:7], 0, v[62:63]
	v_or_b32_e32 v62, 44, v8
	v_ashrrev_i32_e32 v63, 31, v62
	v_lshlrev_b64 v[62:63], 13, v[62:63]
	v_lshl_add_u64 v[82:83], v[6:7], 0, v[62:63]
	v_or_b32_e32 v62, 46, v8
	v_ashrrev_i32_e32 v63, 31, v62
	v_lshlrev_b64 v[62:63], 13, v[62:63]
	v_lshl_add_u64 v[84:85], v[6:7], 0, v[62:63]
	global_load_dword v69, v[70:71], off nt
	global_load_dword v68, v[72:73], off nt
	global_load_dword v67, v[74:75], off nt
	global_load_dword v66, v[76:77], off nt
	global_load_dword v65, v[78:79], off nt
	global_load_dword v64, v[80:81], off nt
	global_load_dword v63, v[82:83], off nt
	global_load_dword v62, v[84:85], off nt
	v_or_b32_e32 v70, 48, v8
	v_ashrrev_i32_e32 v71, 31, v70
	v_lshlrev_b64 v[70:71], 13, v[70:71]
	v_lshl_add_u64 v[76:77], v[6:7], 0, v[70:71]
	v_or_b32_e32 v70, 50, v8
	v_ashrrev_i32_e32 v71, 31, v70
	v_lshlrev_b64 v[70:71], 13, v[70:71]
	v_lshl_add_u64 v[78:79], v[6:7], 0, v[70:71]
	v_or_b32_e32 v70, 52, v8
	v_ashrrev_i32_e32 v71, 31, v70
	v_lshlrev_b64 v[70:71], 13, v[70:71]
	v_lshl_add_u64 v[80:81], v[6:7], 0, v[70:71]
	v_or_b32_e32 v70, 54, v8
	v_ashrrev_i32_e32 v71, 31, v70
	v_lshlrev_b64 v[70:71], 13, v[70:71]
	v_lshl_add_u64 v[82:83], v[6:7], 0, v[70:71]
	v_or_b32_e32 v70, 56, v8
	v_ashrrev_i32_e32 v71, 31, v70
	v_lshlrev_b64 v[70:71], 13, v[70:71]
	v_lshl_add_u64 v[84:85], v[6:7], 0, v[70:71]
	v_or_b32_e32 v70, 58, v8
	v_ashrrev_i32_e32 v71, 31, v70
	v_lshlrev_b64 v[70:71], 13, v[70:71]
	v_lshl_add_u64 v[86:87], v[6:7], 0, v[70:71]
	v_or_b32_e32 v70, 60, v8
	v_ashrrev_i32_e32 v71, 31, v70
	v_lshlrev_b64 v[70:71], 13, v[70:71]
	v_lshl_add_u64 v[88:89], v[6:7], 0, v[70:71]
	v_or_b32_e32 v70, 62, v8
	v_ashrrev_i32_e32 v71, 31, v70
	v_lshlrev_b64 v[70:71], 13, v[70:71]
	v_lshl_add_u64 v[90:91], v[6:7], 0, v[70:71]
	global_load_dword v74, v[76:77], off nt
	global_load_dword v73, v[78:79], off nt
	global_load_dword v72, v[80:81], off nt
	global_load_dword v71, v[82:83], off nt
	global_load_dword v70, v[84:85], off nt
	global_load_dword v8, v[86:87], off nt
	global_load_dword v7, v[88:89], off nt
	global_load_dword v6, v[90:91], off nt
	s_waitcnt vmcnt(62)
; #define LDS_WAIT() asm volatile("s_waitcnt lgkmcnt(0)" ::: "memory")
; template <int MODE>
; __device__ __forceinline__ void transpose_weight(const float* W, int K, int N, bf16_t* WT, LAS float* scr, int gw, int NGW, int lane, const float* gk = nullptr) {
;     ...
; #pragma unroll
;         for (int i = 0; i < 32; ++i) { const int kk = 2 * i + (lane >> 5); scr[kk * 33 + (lane & 31)] = cur[i]; }
;         LDS_WAIT(); asm volatile("" ::: "memory");
	ds_write2_b32 v30, v13, v14 offset1:66
	s_waitcnt vmcnt(60)
	ds_write2_b32 v30, v15, v16 offset0:132 offset1:198
	v_add_u32_e32 v13, 0x400, v30
	s_waitcnt vmcnt(58)
	ds_write2_b32 v13, v17, v18 offset0:8 offset1:74
	s_waitcnt vmcnt(56)
	ds_write2_b32 v13, v19, v20 offset0:140 offset1:206
	v_add_u32_e32 v13, 0x800, v30
	s_waitcnt vmcnt(54)
	ds_write2_b32 v13, v22, v23 offset0:16 offset1:82
	s_waitcnt vmcnt(52)
	ds_write2_b32 v13, v24, v25 offset0:148 offset1:214
	v_add_u32_e32 v13, 0xc00, v30
	s_waitcnt vmcnt(50)
	ds_write2_b32 v13, v26, v27 offset0:24 offset1:90
	s_waitcnt vmcnt(48)
	ds_write2_b32 v13, v28, v29 offset0:156 offset1:222
	v_add_u32_e32 v13, 0x1000, v30
	s_waitcnt vmcnt(46)
	ds_write2_b32 v13, v31, v32 offset0:32 offset1:98
	s_waitcnt vmcnt(44)
	ds_write2_b32 v13, v33, v34 offset0:164 offset1:230
	v_add_u32_e32 v13, 0x1400, v30
	s_ashr_i32 s19, s18, 31
	s_waitcnt vmcnt(42)
	ds_write2_b32 v13, v35, v36 offset0:40 offset1:106
	s_waitcnt vmcnt(40)
	ds_write2_b32 v13, v37, v38 offset0:172 offset1:238
	v_add_u32_e32 v13, 0x1800, v30
	s_lshr_b32 s19, s19, 26
	s_waitcnt vmcnt(38)
	ds_write2_b32 v13, v46, v47 offset0:48 offset1:114
	s_waitcnt vmcnt(36)
	ds_write2_b32 v13, v48, v49 offset0:180 offset1:246
	v_add_u32_e32 v13, 0x1c00, v30
	s_add_i32 s20, s18, s19
	s_waitcnt vmcnt(34)
	ds_write2_b32 v13, v50, v51 offset0:56 offset1:122
	s_waitcnt vmcnt(32)
	s_branch .Ltw_join_2
; #define LAS __attribute__((address_space(3)))
; template <int MODE>
; __device__ __forceinline__ void transpose_weight(const float* W, int K, int N, bf16_t* WT, LAS float* scr, int gw, int NGW, int lane, const float* gk = nullptr) {
;     const int nblk = N / 32, nitems = (K / 64) * nblk;
;     const int c = lane & 7;
;     float cur[32], nxt[32];
;     f32x4 gc0 = {1.f, 1.f, 1.f, 1.f}, gc1 = gc0, gn0 = gc0, gn1 = gc0;
;     int it = gw;
;     if (it < nitems) TW_LOAD(it, cur, gc0, gc1);
; __global__ void __launch_bounds__(NTHREADS, 2) fwd_megakernel(Args a) {
;     ...
;     transpose_weight<0>(ap->in[18], DM, DM, (bf16_t*)(ws + WS_WOUT), scr, gw, NGW, lane);
.LBB0_34:
	s_cmpk_gt_i32 s6, 0x7ff
	s_cbranch_scc1 .LBB0_39
	s_ashr_i32 s8, s6, 31
	s_lshr_b32 s8, s8, 26
	s_add_i32 s8, s6, s8
	s_load_dwordx2 s[4:5], s[14:15], 0x90
	s_and_b32 s9, s8, 0xffffffc0
	s_sub_i32 s8, s6, s9
	s_lshl_b32 s8, s8, 5
	v_or_b32_e32 v2, s9, v93
	s_ashr_i32 s9, s8, 31
	s_lshl_b64 s[8:9], s[8:9], 2
	s_waitcnt lgkmcnt(0)
	s_add_u32 s8, s4, s8
	s_addc_u32 s9, s5, s9
	v_and_b32_e32 v4, 0x7c, v12
	v_mov_b32_e32 v5, 0
	v_ashrrev_i32_e32 v3, 31, v2
	v_lshl_add_u64 v[6:7], s[8:9], 0, v[4:5]
	v_lshlrev_b64 v[8:9], 13, v[2:3]
	v_lshl_add_u64 v[18:19], v[6:7], 0, v[8:9]
	v_or_b32_e32 v8, 2, v2
	v_ashrrev_i32_e32 v9, 31, v8
	v_lshlrev_b64 v[8:9], 13, v[8:9]
	v_lshl_add_u64 v[20:21], v[6:7], 0, v[8:9]
	v_or_b32_e32 v8, 4, v2
	v_ashrrev_i32_e32 v9, 31, v8
	v_lshlrev_b64 v[8:9], 13, v[8:9]
	v_lshl_add_u64 v[22:23], v[6:7], 0, v[8:9]
	v_or_b32_e32 v8, 6, v2
	v_ashrrev_i32_e32 v9, 31, v8
	v_lshlrev_b64 v[8:9], 13, v[8:9]
	v_lshl_add_u64 v[24:25], v[6:7], 0, v[8:9]
	v_or_b32_e32 v8, 8, v2
	v_ashrrev_i32_e32 v9, 31, v8
	v_lshlrev_b64 v[8:9], 13, v[8:9]
	v_lshl_add_u64 v[26:27], v[6:7], 0, v[8:9]
	v_or_b32_e32 v8, 10, v2
	v_ashrrev_i32_e32 v9, 31, v8
	v_lshlrev_b64 v[8:9], 13, v[8:9]
	v_lshl_add_u64 v[28:29], v[6:7], 0, v[8:9]
	v_or_b32_e32 v8, 12, v2
	v_ashrrev_i32_e32 v9, 31, v8
	v_lshlrev_b64 v[8:9], 13, v[8:9]
	v_lshl_add_u64 v[30:31], v[6:7], 0, v[8:9]
	v_or_b32_e32 v8, 14, v2
	v_ashrrev_i32_e32 v9, 31, v8
	v_lshlrev_b64 v[8:9], 13, v[8:9]
	v_lshl_add_u64 v[32:33], v[6:7], 0, v[8:9]
	global_load_dword v8, v[18:19], off nt
	global_load_dword v9, v[20:21], off nt
	global_load_dword v12, v[22:23], off nt
	global_load_dword v13, v[24:25], off nt
	global_load_dword v14, v[26:27], off nt
	global_load_dword v15, v[28:29], off nt
	global_load_dword v16, v[30:31], off nt
	global_load_dword v17, v[32:33], off nt
	v_or_b32_e32 v18, 16, v2
	v_ashrrev_i32_e32 v19, 31, v18
	v_lshlrev_b64 v[18:19], 13, v[18:19]
	v_lshl_add_u64 v[28:29], v[6:7], 0, v[18:19]
	v_or_b32_e32 v18, 18, v2
	v_ashrrev_i32_e32 v19, 31, v18
	v_lshlrev_b64 v[18:19], 13, v[18:19]
	v_lshl_add_u64 v[30:31], v[6:7], 0, v[18:19]
	v_or_b32_e32 v18, 20, v2
	v_ashrrev_i32_e32 v19, 31, v18
	v_lshlrev_b64 v[18:19], 13, v[18:19]
	v_lshl_add_u64 v[32:33], v[6:7], 0, v[18:19]
	v_or_b32_e32 v18, 22, v2
	v_ashrrev_i32_e32 v19, 31, v18
	v_lshlrev_b64 v[18:19], 13, v[18:19]
	v_lshl_add_u64 v[34:35], v[6:7], 0, v[18:19]
	v_or_b32_e32 v18, 24, v2
	v_ashrrev_i32_e32 v19, 31, v18
	v_lshlrev_b64 v[18:19], 13, v[18:19]
	v_lshl_add_u64 v[36:37], v[6:7], 0, v[18:19]
	v_or_b32_e32 v18, 26, v2
	v_ashrrev_i32_e32 v19, 31, v18
	v_lshlrev_b64 v[18:19], 13, v[18:19]
	v_lshl_add_u64 v[38:39], v[6:7], 0, v[18:19]
	v_or_b32_e32 v18, 28, v2
	v_ashrrev_i32_e32 v19, 31, v18
	v_lshlrev_b64 v[18:19], 13, v[18:19]
	v_lshl_add_u64 v[40:41], v[6:7], 0, v[18:19]
	v_or_b32_e32 v18, 30, v2
	v_ashrrev_i32_e32 v19, 31, v18
	v_lshlrev_b64 v[18:19], 13, v[18:19]
	v_lshl_add_u64 v[42:43], v[6:7], 0, v[18:19]
	global_load_dword v19, v[28:29], off nt
	global_load_dword v20, v[30:31], off nt
	global_load_dword v21, v[32:33], off nt
	global_load_dword v22, v[34:35], off nt
	global_load_dword v23, v[36:37], off nt
	global_load_dword v24, v[38:39], off nt
	global_load_dword v26, v[40:41], off nt
	global_load_dword v27, v[42:43], off nt
	v_or_b32_e32 v28, 32, v2
	v_ashrrev_i32_e32 v29, 31, v28
	v_lshlrev_b64 v[28:29], 13, v[28:29]
	v_lshl_add_u64 v[38:39], v[6:7], 0, v[28:29]
	v_or_b32_e32 v28, 34, v2
	v_ashrrev_i32_e32 v29, 31, v28
	v_lshlrev_b64 v[28:29], 13, v[28:29]
	v_lshl_add_u64 v[40:41], v[6:7], 0, v[28:29]
	v_or_b32_e32 v28, 36, v2
	v_ashrrev_i32_e32 v29, 31, v28
	v_lshlrev_b64 v[28:29], 13, v[28:29]
	v_lshl_add_u64 v[42:43], v[6:7], 0, v[28:29]
	v_or_b32_e32 v28, 38, v2
	v_ashrrev_i32_e32 v29, 31, v28
	v_lshlrev_b64 v[28:29], 13, v[28:29]
	v_lshl_add_u64 v[44:45], v[6:7], 0, v[28:29]
	v_or_b32_e32 v28, 40, v2
	v_ashrrev_i32_e32 v29, 31, v28
	v_lshlrev_b64 v[28:29], 13, v[28:29]
	v_lshl_add_u64 v[46:47], v[6:7], 0, v[28:29]
	v_or_b32_e32 v28, 42, v2
	v_ashrrev_i32_e32 v29, 31, v28
	v_lshlrev_b64 v[28:29], 13, v[28:29]
	v_lshl_add_u64 v[48:49], v[6:7], 0, v[28:29]
	v_or_b32_e32 v28, 44, v2
	v_ashrrev_i32_e32 v29, 31, v28
	v_lshlrev_b64 v[28:29], 13, v[28:29]
	v_lshl_add_u64 v[50:51], v[6:7], 0, v[28:29]
	v_or_b32_e32 v28, 46, v2
	v_ashrrev_i32_e32 v29, 31, v28
	v_lshlrev_b64 v[28:29], 13, v[28:29]
	v_lshl_add_u64 v[52:53], v[6:7], 0, v[28:29]
	global_load_dword v29, v[38:39], off nt
	global_load_dword v30, v[40:41], off nt
	global_load_dword v31, v[42:43], off nt
	global_load_dword v32, v[44:45], off nt
	global_load_dword v33, v[46:47], off nt
	global_load_dword v34, v[48:49], off nt
	global_load_dword v35, v[50:51], off nt
	global_load_dword v36, v[52:53], off nt
	v_or_b32_e32 v44, 54, v2
	v_ashrrev_i32_e32 v45, 31, v44
	v_lshlrev_b64 v[44:45], 13, v[44:45]
	v_lshl_add_u64 v[52:53], v[6:7], 0, v[44:45]
	v_or_b32_e32 v44, 56, v2
	v_ashrrev_i32_e32 v45, 31, v44
	v_lshlrev_b64 v[44:45], 13, v[44:45]
	v_lshl_add_u64 v[54:55], v[6:7], 0, v[44:45]
	v_or_b32_e32 v44, 58, v2
	v_ashrrev_i32_e32 v45, 31, v44
	v_or_b32_e32 v38, 48, v2
	v_lshlrev_b64 v[44:45], 13, v[44:45]
	v_ashrrev_i32_e32 v39, 31, v38
	v_or_b32_e32 v40, 50, v2
	v_or_b32_e32 v42, 52, v2
	v_lshl_add_u64 v[56:57], v[6:7], 0, v[44:45]
	v_or_b32_e32 v44, 60, v2
	v_or_b32_e32 v2, 62, v2
	v_lshlrev_b64 v[38:39], 13, v[38:39]
	v_ashrrev_i32_e32 v41, 31, v40
	v_ashrrev_i32_e32 v43, 31, v42
	v_ashrrev_i32_e32 v45, 31, v44
	v_ashrrev_i32_e32 v3, 31, v2
	v_lshl_add_u64 v[38:39], v[6:7], 0, v[38:39]
	v_lshlrev_b64 v[40:41], 13, v[40:41]
	v_lshlrev_b64 v[42:43], 13, v[42:43]
	v_lshlrev_b64 v[44:45], 13, v[44:45]
	v_lshlrev_b64 v[2:3], 13, v[2:3]
	v_lshl_add_u64 v[40:41], v[6:7], 0, v[40:41]
	v_lshl_add_u64 v[42:43], v[6:7], 0, v[42:43]
	v_lshl_add_u64 v[58:59], v[6:7], 0, v[44:45]
	v_lshl_add_u64 v[2:3], v[6:7], 0, v[2:3]
	global_load_dword v44, v[38:39], off nt
	global_load_dword v45, v[40:41], off nt
	global_load_dword v46, v[42:43], off nt
	global_load_dword v47, v[52:53], off nt
	global_load_dword v48, v[54:55], off nt
	global_load_dword v49, v[56:57], off nt
	global_load_dword v50, v[58:59], off nt
	global_load_dword v51, v[2:3], off nt
	v_lshrrev_b32_e32 v18, 3, v92
	v_mov_b32_e32 v1, v5
	v_lshl_add_u64 v[2:3], s[4:5], 0, v[4:5]
	v_add_u32_e32 v4, s7, v4
	v_mul_u32_u24_e32 v6, 0x420, v10
	v_lshl_add_u64 v[0:1], s[12:13], 0, v[0:1]
	s_mov_b64 s[4:5], 0x9600000
	v_mul_u32_u24_e32 v5, 0x84, v93
	v_lshlrev_b32_e32 v7, 2, v18
	s_lshl_b32 s9, s69, 5
	v_lshl_add_u64 v[0:1], v[0:1], 0, s[4:5]
	v_add3_u32 v25, s7, v6, v7
	s_lshl_b32 s8, s6, 5
	v_add_u32_e32 v28, v4, v5
	s_mov_b32 s10, s9
	s_mov_b32 s18, s6
	s_branch .LBB0_37

; template <int MODE>
; __device__ __forceinline__ void transpose_weight(const float* W, int K, int N, bf16_t* WT, LAS float* scr, int gw, int NGW, int lane, const float* gk = nullptr) {
;     ...
;     while (it < nitems) {
;         const int itn = it + NGW;
;         if (itn < nitems) TW_LOAD(itn, nxt, gn0, gn1);
.LBB0_37:
	s_add_i32 s11, s18, s69
	s_cmpk_gt_i32 s11, 0x7ff
	s_cselect_b64 s[4:5], -1, 0
	s_and_b64 vcc, exec, s[4:5]
	s_cbranch_vccnz .LBB0_36
	s_ashr_i32 s19, s11, 31
	s_lshr_b32 s19, s19, 26
	s_add_i32 s19, s11, s19
	s_and_b32 s21, s19, 0xffffffc0
	s_lshl_b32 s19, s19, 5
	s_add_i32 s20, s8, s10
	s_and_b32 s19, s19, 0xfffff800
	s_sub_i32 s20, s20, s19
	v_or_b32_e32 v6, s21, v93
	s_ashr_i32 s21, s20, 31
	v_ashrrev_i32_e32 v7, 31, v6
	v_lshl_add_u64 v[4:5], s[20:21], 2, v[2:3]
	v_lshlrev_b64 v[38:39], 13, v[6:7]
	v_lshl_add_u64 v[52:53], v[4:5], 0, v[38:39]
	v_or_b32_e32 v38, 2, v6
	v_ashrrev_i32_e32 v39, 31, v38
	v_lshlrev_b64 v[38:39], 13, v[38:39]
	v_lshl_add_u64 v[54:55], v[4:5], 0, v[38:39]
	v_or_b32_e32 v38, 4, v6
	v_ashrrev_i32_e32 v39, 31, v38
	v_lshlrev_b64 v[38:39], 13, v[38:39]
	v_lshl_add_u64 v[56:57], v[4:5], 0, v[38:39]
	v_or_b32_e32 v38, 6, v6
	v_ashrrev_i32_e32 v39, 31, v38
	v_lshlrev_b64 v[38:39], 13, v[38:39]
	v_lshl_add_u64 v[58:59], v[4:5], 0, v[38:39]
	v_or_b32_e32 v38, 8, v6
	v_ashrrev_i32_e32 v39, 31, v38
	v_lshlrev_b64 v[38:39], 13, v[38:39]
	v_lshl_add_u64 v[60:61], v[4:5], 0, v[38:39]
	v_or_b32_e32 v38, 10, v6
	v_ashrrev_i32_e32 v39, 31, v38
	v_lshlrev_b64 v[38:39], 13, v[38:39]
	v_lshl_add_u64 v[62:63], v[4:5], 0, v[38:39]
	v_or_b32_e32 v38, 12, v6
	v_ashrrev_i32_e32 v39, 31, v38
	v_lshlrev_b64 v[38:39], 13, v[38:39]
	v_lshl_add_u64 v[64:65], v[4:5], 0, v[38:39]
	v_or_b32_e32 v38, 14, v6
	v_ashrrev_i32_e32 v39, 31, v38
	v_lshlrev_b64 v[38:39], 13, v[38:39]
	v_lshl_add_u64 v[66:67], v[4:5], 0, v[38:39]
	global_load_dword v43, v[52:53], off nt
	global_load_dword v42, v[54:55], off nt
	global_load_dword v41, v[56:57], off nt
	global_load_dword v40, v[58:59], off nt
	global_load_dword v39, v[60:61], off nt
	global_load_dword v38, v[62:63], off nt
	global_load_dword v37, v[64:65], off nt
	global_load_dword v7, v[66:67], off nt
	v_or_b32_e32 v52, 16, v6
	v_ashrrev_i32_e32 v53, 31, v52
	v_lshlrev_b64 v[52:53], 13, v[52:53]
	v_lshl_add_u64 v[60:61], v[4:5], 0, v[52:53]
	v_or_b32_e32 v52, 18, v6
	v_ashrrev_i32_e32 v53, 31, v52
	v_lshlrev_b64 v[52:53], 13, v[52:53]
	v_lshl_add_u64 v[62:63], v[4:5], 0, v[52:53]
	v_or_b32_e32 v52, 20, v6
	v_ashrrev_i32_e32 v53, 31, v52
	v_lshlrev_b64 v[52:53], 13, v[52:53]
	v_lshl_add_u64 v[64:65], v[4:5], 0, v[52:53]
	v_or_b32_e32 v52, 22, v6
	v_ashrrev_i32_e32 v53, 31, v52
	v_lshlrev_b64 v[52:53], 13, v[52:53]
	v_lshl_add_u64 v[66:67], v[4:5], 0, v[52:53]
	v_or_b32_e32 v52, 24, v6
	v_ashrrev_i32_e32 v53, 31, v52
	v_lshlrev_b64 v[52:53], 13, v[52:53]
	v_lshl_add_u64 v[68:69], v[4:5], 0, v[52:53]
	v_or_b32_e32 v52, 26, v6
	v_ashrrev_i32_e32 v53, 31, v52
	v_lshlrev_b64 v[52:53], 13, v[52:53]
	v_lshl_add_u64 v[70:71], v[4:5], 0, v[52:53]
	v_or_b32_e32 v52, 28, v6
	v_ashrrev_i32_e32 v53, 31, v52
	v_lshlrev_b64 v[52:53], 13, v[52:53]
	v_lshl_add_u64 v[72:73], v[4:5], 0, v[52:53]
	v_or_b32_e32 v52, 30, v6
	v_ashrrev_i32_e32 v53, 31, v52
	v_lshlrev_b64 v[52:53], 13, v[52:53]
	v_lshl_add_u64 v[74:75], v[4:5], 0, v[52:53]
	global_load_dword v59, v[60:61], off nt
	global_load_dword v58, v[62:63], off nt
	global_load_dword v57, v[64:65], off nt
	global_load_dword v56, v[66:67], off nt
	global_load_dword v55, v[68:69], off nt
	global_load_dword v54, v[70:71], off nt
	global_load_dword v53, v[72:73], off nt
	global_load_dword v52, v[74:75], off nt
	v_or_b32_e32 v60, 32, v6
	v_ashrrev_i32_e32 v61, 31, v60
	v_lshlrev_b64 v[60:61], 13, v[60:61]
	v_lshl_add_u64 v[68:69], v[4:5], 0, v[60:61]
	v_or_b32_e32 v60, 34, v6
	v_ashrrev_i32_e32 v61, 31, v60
	v_lshlrev_b64 v[60:61], 13, v[60:61]
	v_lshl_add_u64 v[70:71], v[4:5], 0, v[60:61]
	v_or_b32_e32 v60, 36, v6
	v_ashrrev_i32_e32 v61, 31, v60
	v_lshlrev_b64 v[60:61], 13, v[60:61]
	v_lshl_add_u64 v[72:73], v[4:5], 0, v[60:61]
	v_or_b32_e32 v60, 38, v6
	v_ashrrev_i32_e32 v61, 31, v60
	v_lshlrev_b64 v[60:61], 13, v[60:61]
	v_lshl_add_u64 v[74:75], v[4:5], 0, v[60:61]
	v_or_b32_e32 v60, 40, v6
	v_ashrrev_i32_e32 v61, 31, v60
	v_lshlrev_b64 v[60:61], 13, v[60:61]
	v_lshl_add_u64 v[76:77], v[4:5], 0, v[60:61]
	v_or_b32_e32 v60, 42, v6
	v_ashrrev_i32_e32 v61, 31, v60
	v_lshlrev_b64 v[60:61], 13, v[60:61]
	v_lshl_add_u64 v[78:79], v[4:5], 0, v[60:61]
	v_or_b32_e32 v60, 44, v6
	v_ashrrev_i32_e32 v61, 31, v60
	v_lshlrev_b64 v[60:61], 13, v[60:61]
	v_lshl_add_u64 v[80:81], v[4:5], 0, v[60:61]
	v_or_b32_e32 v60, 46, v6
	v_ashrrev_i32_e32 v61, 31, v60
	v_lshlrev_b64 v[60:61], 13, v[60:61]
	v_lshl_add_u64 v[82:83], v[4:5], 0, v[60:61]
	global_load_dword v67, v[68:69], off nt
	global_load_dword v66, v[70:71], off nt
	global_load_dword v65, v[72:73], off nt
	global_load_dword v64, v[74:75], off nt
	global_load_dword v63, v[76:77], off nt
	global_load_dword v62, v[78:79], off nt
	global_load_dword v61, v[80:81], off nt
	global_load_dword v60, v[82:83], off nt
	v_or_b32_e32 v68, 48, v6
	v_ashrrev_i32_e32 v69, 31, v68
	v_lshlrev_b64 v[68:69], 13, v[68:69]
	v_lshl_add_u64 v[74:75], v[4:5], 0, v[68:69]
	v_or_b32_e32 v68, 50, v6
	v_ashrrev_i32_e32 v69, 31, v68
	v_lshlrev_b64 v[68:69], 13, v[68:69]
	v_lshl_add_u64 v[76:77], v[4:5], 0, v[68:69]
	v_or_b32_e32 v68, 52, v6
	v_ashrrev_i32_e32 v69, 31, v68
	v_lshlrev_b64 v[68:69], 13, v[68:69]
	v_lshl_add_u64 v[78:79], v[4:5], 0, v[68:69]
	v_or_b32_e32 v68, 54, v6
	v_ashrrev_i32_e32 v69, 31, v68
	v_lshlrev_b64 v[68:69], 13, v[68:69]
	v_lshl_add_u64 v[80:81], v[4:5], 0, v[68:69]
	v_or_b32_e32 v68, 56, v6
	v_ashrrev_i32_e32 v69, 31, v68
	v_lshlrev_b64 v[68:69], 13, v[68:69]
	v_lshl_add_u64 v[82:83], v[4:5], 0, v[68:69]
	v_or_b32_e32 v68, 58, v6
	v_ashrrev_i32_e32 v69, 31, v68
	v_lshlrev_b64 v[68:69], 13, v[68:69]
	v_lshl_add_u64 v[84:85], v[4:5], 0, v[68:69]
	v_or_b32_e32 v68, 60, v6
	v_ashrrev_i32_e32 v69, 31, v68
	v_lshlrev_b64 v[68:69], 13, v[68:69]
	v_lshl_add_u64 v[86:87], v[4:5], 0, v[68:69]
	v_or_b32_e32 v68, 62, v6
	v_ashrrev_i32_e32 v69, 31, v68
	v_lshlrev_b64 v[68:69], 13, v[68:69]
	v_lshl_add_u64 v[88:89], v[4:5], 0, v[68:69]
	global_load_dword v72, v[74:75], off nt
	global_load_dword v71, v[76:77], off nt
	global_load_dword v70, v[78:79], off nt
	global_load_dword v69, v[80:81], off nt
	global_load_dword v68, v[82:83], off nt
	global_load_dword v6, v[84:85], off nt
	global_load_dword v5, v[86:87], off nt
	global_load_dword v4, v[88:89], off nt
	s_waitcnt vmcnt(62)
; #define LDS_WAIT() asm volatile("s_waitcnt lgkmcnt(0)" ::: "memory")
; template <int MODE>
; __device__ __forceinline__ void transpose_weight(const float* W, int K, int N, bf16_t* WT, LAS float* scr, int gw, int NGW, int lane, const float* gk = nullptr) {
;     ...
; #pragma unroll
;         for (int i = 0; i < 32; ++i) { const int kk = 2 * i + (lane >> 5); scr[kk * 33 + (lane & 31)] = cur[i]; }
;         LDS_WAIT(); asm volatile("" ::: "memory");
	ds_write2_b32 v28, v8, v9 offset1:66
	s_waitcnt vmcnt(60)
	ds_write2_b32 v28, v12, v13 offset0:132 offset1:198
	v_add_u32_e32 v8, 0x400, v28
	s_waitcnt vmcnt(58)
	ds_write2_b32 v8, v14, v15 offset0:8 offset1:74
	s_waitcnt vmcnt(56)
	ds_write2_b32 v8, v16, v17 offset0:140 offset1:206
	v_add_u32_e32 v8, 0x800, v28
	s_waitcnt vmcnt(54)
	ds_write2_b32 v8, v19, v20 offset0:16 offset1:82
	s_waitcnt vmcnt(52)
	ds_write2_b32 v8, v21, v22 offset0:148 offset1:214
	v_add_u32_e32 v8, 0xc00, v28
	s_waitcnt vmcnt(50)
	ds_write2_b32 v8, v23, v24 offset0:24 offset1:90
	s_waitcnt vmcnt(48)
	ds_write2_b32 v8, v26, v27 offset0:156 offset1:222
	v_add_u32_e32 v8, 0x1000, v28
	s_waitcnt vmcnt(46)
	ds_write2_b32 v8, v29, v30 offset0:32 offset1:98
	s_waitcnt vmcnt(44)
	ds_write2_b32 v8, v31, v32 offset0:164 offset1:230
	v_add_u32_e32 v8, 0x1400, v28
	s_ashr_i32 s19, s18, 31
	s_waitcnt vmcnt(42)
	ds_write2_b32 v8, v33, v34 offset0:40 offset1:106
	s_waitcnt vmcnt(40)
	ds_write2_b32 v8, v35, v36 offset0:172 offset1:238
	v_add_u32_e32 v8, 0x1800, v28
	s_lshr_b32 s19, s19, 26
	s_waitcnt vmcnt(38)
	ds_write2_b32 v8, v44, v45 offset0:48 offset1:114
	s_waitcnt vmcnt(36)
	ds_write2_b32 v8, v46, v47 offset0:180 offset1:246
	v_add_u32_e32 v8, 0x1c00, v28
	s_add_i32 s20, s18, s19
	s_waitcnt vmcnt(34)
	ds_write2_b32 v8, v48, v49 offset0:56 offset1:122
	s_waitcnt vmcnt(32)
	s_branch .Ltw_join_3
; #define LAS __attribute__((address_space(3)))
; template <int MODE>
; __device__ __forceinline__ void transpose_weight(const float* W, int K, int N, bf16_t* WT, LAS float* scr, int gw, int NGW, int lane, const float* gk = nullptr) {
;     const int nblk = N / 32, nitems = (K / 64) * nblk;
;     const int c = lane & 7;
;     float cur[32], nxt[32];
;     f32x4 gc0 = {1.f, 1.f, 1.f, 1.f}, gc1 = gc0, gn0 = gc0, gn1 = gc0;
;     int it = gw;
;     if (it < nitems) TW_LOAD(it, cur, gc0, gc1);
; __global__ void __launch_bounds__(NTHREADS, 2) fwd_megakernel(Args a) {
;     ...
;     transpose_weight<0>(ap->in[24], DM, DFF, WG, scr, gw, NGW, lane, ap->in[23]);
.LBB0_39:
	s_cmpk_gt_i32 s6, 0x15ff
	s_mul_i32 s70, s69, 0x2c000
	s_cbranch_scc1 .LBB0_61
	s_mul_hi_i32 s4, s6, 0x2e8ba2e9
	s_lshr_b32 s5, s4, 31
	s_ashr_i32 s4, s4, 5
	s_add_i32 s4, s4, s5
	s_load_dwordx4 s[8:11], s[14:15], 0xb8
	s_mul_i32 s5, s4, 0xb0
	s_sub_i32 s5, s6, s5
	s_lshl_b32 s18, s4, 6
	s_lshl_b32 s4, s5, 5
	s_ashr_i32 s5, s4, 31
	s_lshl_b64 s[4:5], s[4:5], 2
	v_and_b32_e32 v0, 31, v11
	s_waitcnt lgkmcnt(0)
	s_add_u32 s20, s10, s4
	v_or_b32_e32 v22, s18, v93
	v_mov_b32_e32 v17, 0
	s_addc_u32 s21, s11, s5
	v_lshlrev_b32_e32 v16, 2, v0
	v_lshl_add_u64 v[0:1], s[20:21], 0, v[16:17]
	s_movk_i32 s19, 0x5800
	v_or_b32_e32 v28, 14, v22
	v_mad_i64_i32 v[2:3], s[20:21], v22, s19, v[0:1]
	v_or_b32_e32 v11, 2, v22
	v_or_b32_e32 v23, 4, v22
	v_or_b32_e32 v24, 6, v22
	v_or_b32_e32 v25, 8, v22
	v_or_b32_e32 v26, 10, v22
	v_or_b32_e32 v27, 12, v22
	v_mad_i64_i32 v[20:21], s[20:21], v28, s19, v[0:1]
	v_or_b32_e32 v29, 16, v22
	v_or_b32_e32 v36, 30, v22
	v_mad_i64_i32 v[4:5], s[20:21], v11, s19, v[0:1]
	v_mad_i64_i32 v[6:7], s[20:21], v23, s19, v[0:1]
	v_mad_i64_i32 v[8:9], s[20:21], v24, s19, v[0:1]
	v_mad_i64_i32 v[12:13], s[20:21], v25, s19, v[0:1]
	v_mad_i64_i32 v[14:15], s[20:21], v26, s19, v[0:1]
	v_mad_i64_i32 v[18:19], s[20:21], v27, s19, v[0:1]
	global_load_dword v97, v[2:3], off nt
	global_load_dword v98, v[4:5], off nt
	global_load_dword v99, v[6:7], off nt
	global_load_dword v100, v[8:9], off nt
	global_load_dword v101, v[12:13], off nt
	global_load_dword v102, v[14:15], off nt
	global_load_dword v103, v[18:19], off nt
	global_load_dword v104, v[20:21], off nt
	v_mad_i64_i32 v[2:3], s[20:21], v29, s19, v[0:1]
	v_or_b32_e32 v30, 18, v22
	v_or_b32_e32 v31, 20, v22
	v_or_b32_e32 v32, 22, v22
	v_or_b32_e32 v33, 24, v22
	v_or_b32_e32 v34, 26, v22
	v_or_b32_e32 v35, 28, v22
	v_mad_i64_i32 v[20:21], s[20:21], v36, s19, v[0:1]
	v_or_b32_e32 v37, 32, v22
	v_or_b32_e32 v88, 46, v22
	v_mad_i64_i32 v[4:5], s[20:21], v30, s19, v[0:1]
	v_mad_i64_i32 v[6:7], s[20:21], v31, s19, v[0:1]
	v_mad_i64_i32 v[8:9], s[20:21], v32, s19, v[0:1]
	v_mad_i64_i32 v[12:13], s[20:21], v33, s19, v[0:1]
	v_mad_i64_i32 v[14:15], s[20:21], v34, s19, v[0:1]
	v_mad_i64_i32 v[18:19], s[20:21], v35, s19, v[0:1]
	global_load_dword v105, v[2:3], off nt
	global_load_dword v106, v[4:5], off nt
	global_load_dword v107, v[6:7], off nt
	global_load_dword v108, v[8:9], off nt
	global_load_dword v109, v[12:13], off nt
	global_load_dword v110, v[14:15], off nt
	global_load_dword v111, v[18:19], off nt
	global_load_dword v112, v[20:21], off nt
	v_mad_i64_i32 v[2:3], s[20:21], v37, s19, v[0:1]
	v_or_b32_e32 v38, 34, v22
	v_or_b32_e32 v39, 36, v22
	v_or_b32_e32 v40, 38, v22
	v_or_b32_e32 v41, 40, v22
	v_or_b32_e32 v42, 42, v22
	v_or_b32_e32 v43, 44, v22
	v_mad_i64_i32 v[20:21], s[20:21], v88, s19, v[0:1]
	v_mad_i64_i32 v[4:5], s[20:21], v38, s19, v[0:1]
	v_mad_i64_i32 v[6:7], s[20:21], v39, s19, v[0:1]
	v_mad_i64_i32 v[8:9], s[20:21], v40, s19, v[0:1]
	v_mad_i64_i32 v[12:13], s[20:21], v41, s19, v[0:1]
	v_mad_i64_i32 v[14:15], s[20:21], v42, s19, v[0:1]
	v_mad_i64_i32 v[18:19], s[20:21], v43, s19, v[0:1]
	global_load_dword v113, v[2:3], off nt
	global_load_dword v114, v[4:5], off nt
	global_load_dword v115, v[6:7], off nt
	global_load_dword v116, v[8:9], off nt
	global_load_dword v117, v[12:13], off nt
	global_load_dword v118, v[14:15], off nt
	global_load_dword v119, v[18:19], off nt
	global_load_dword v120, v[20:21], off nt
	v_or_b32_e32 v20, 48, v22
	v_mad_i64_i32 v[2:3], s[20:21], v20, s19, v[0:1]
	v_or_b32_e32 v21, 50, v22
	v_or_b32_e32 v89, 52, v22
	v_or_b32_e32 v90, 54, v22
	v_or_b32_e32 v91, 56, v22
	v_or_b32_e32 v95, 58, v22
	v_or_b32_e32 v96, 60, v22
	v_or_b32_e32 v121, 62, v22
	v_mad_i64_i32 v[4:5], s[20:21], v21, s19, v[0:1]
	v_mad_i64_i32 v[6:7], s[20:21], v89, s19, v[0:1]
	v_mad_i64_i32 v[8:9], s[20:21], v90, s19, v[0:1]
	v_mad_i64_i32 v[12:13], s[20:21], v91, s19, v[0:1]
	v_mad_i64_i32 v[14:15], s[20:21], v95, s19, v[0:1]
	v_mad_i64_i32 v[18:19], s[20:21], v96, s19, v[0:1]
	v_mad_i64_i32 v[0:1], s[20:21], v121, s19, v[0:1]
	global_load_dword v125, v[2:3], off nt
	global_load_dword v126, v[4:5], off nt
	global_load_dword v128, v[6:7], off nt
	global_load_dword v129, v[8:9], off nt
	global_load_dword v130, v[12:13], off nt
	global_load_dword v132, v[14:15], off nt
	global_load_dword v133, v[18:19], off nt
	global_load_dword v135, v[0:1], off nt
	v_mad_i64_i32 v[86:87], s[20:21], v22, s19, 0
	v_mad_i64_i32 v[84:85], s[20:21], v11, s19, 0
	v_mad_i64_i32 v[82:83], s[20:21], v23, s19, 0
	v_mad_i64_i32 v[80:81], s[20:21], v24, s19, 0
	v_mad_i64_i32 v[78:79], s[20:21], v25, s19, 0
	v_mad_i64_i32 v[76:77], s[20:21], v26, s19, 0
	v_mad_i64_i32 v[74:75], s[20:21], v27, s19, 0
	v_mad_i64_i32 v[72:73], s[20:21], v28, s19, 0
	v_mad_i64_i32 v[70:71], s[20:21], v29, s19, 0
	v_mad_i64_i32 v[68:69], s[20:21], v30, s19, 0
	v_mad_i64_i32 v[66:67], s[20:21], v31, s19, 0
	v_mad_i64_i32 v[64:65], s[20:21], v32, s19, 0
	v_mad_i64_i32 v[62:63], s[20:21], v33, s19, 0
	v_mad_i64_i32 v[60:61], s[20:21], v34, s19, 0
	v_mad_i64_i32 v[58:59], s[20:21], v35, s19, 0
	v_mad_i64_i32 v[56:57], s[20:21], v36, s19, 0
	v_mad_i64_i32 v[54:55], s[20:21], v37, s19, 0
	v_mad_i64_i32 v[52:53], s[20:21], v38, s19, 0
	v_mad_i64_i32 v[50:51], s[20:21], v39, s19, 0
	v_mad_i64_i32 v[48:49], s[20:21], v40, s19, 0
	v_mad_i64_i32 v[46:47], s[20:21], v41, s19, 0
	v_mad_i64_i32 v[44:45], s[20:21], v42, s19, 0
	v_mad_i64_i32 v[42:43], s[20:21], v43, s19, 0
	v_mad_i64_i32 v[40:41], s[20:21], v88, s19, 0
	s_cmp_lg_u64 s[8:9], 0
	s_cselect_b64 s[20:21], -1, 0
	s_mov_b64 s[22:23], 0
	s_and_b64 vcc, exec, s[20:21]
	v_mad_i64_i32 v[38:39], s[24:25], v20, s19, 0
	v_mad_i64_i32 v[36:37], s[24:25], v21, s19, 0
	v_mad_i64_i32 v[34:35], s[24:25], v89, s19, 0
	v_mad_i64_i32 v[32:33], s[24:25], v90, s19, 0
	v_mad_i64_i32 v[30:31], s[24:25], v91, s19, 0
	v_mad_i64_i32 v[28:29], s[24:25], v95, s19, 0
	v_mad_i64_i32 v[26:27], s[24:25], v96, s19, 0
	v_mad_i64_i32 v[24:25], s[24:25], v121, s19, 0
	v_lshlrev_b32_e32 v22, 3, v10
	s_cbranch_vccz .LBB0_50
	s_ashr_i32 s19, s18, 31
	s_lshl_b64 s[24:25], s[18:19], 2
	s_add_u32 s24, s8, s24
	s_addc_u32 s25, s9, s25
	v_lshlrev_b32_e32 v8, 5, v10
	global_load_dwordx4 v[0:3], v8, s[24:25] offset:16
	global_load_dwordx4 v[4:7], v8, s[24:25]
	v_mov_b32_e32 v23, v17
	s_andn2_b64 vcc, exec, s[22:23]
	s_cbranch_vccnz .LBB0_43

; template <int MODE>
; __device__ __forceinline__ void transpose_weight(const float* W, int K, int N, bf16_t* WT, LAS float* scr, int gw, int NGW, int lane, const float* gk = nullptr) {
;     ...
;     while (it < nitems) {
;         const int itn = it + NGW;
;         if (itn < nitems) TW_LOAD(itn, nxt, gn0, gn1);
;         const int kb = it / nblk, nb = it % nblk, k0 = 64 * kb, n0 = 32 * nb;
;         int drow = n0;
;         if (MODE == 1) { if (n0 < 2048) drow = 4096 + n0; else if (n0 < 4096) { const int cc = n0 - 2048; drow = (cc >> 7) * 256 + (cc & 127); } else { const int cc = n0 - 4096; drow = (cc >> 7) * 256 + 128 + (cc & 127); } }
; #pragma unroll
;         for (int i = 0; i < 32; ++i) { const int kk = 2 * i + (lane >> 5); scr[kk * 33 + (lane & 31)] = cur[i]; }
.LBB0_45:
	s_add_i32 s26, s27, s69
	s_cmpk_gt_i32 s26, 0x15ff
	s_cselect_b64 s[10:11], -1, 0
	s_and_b64 vcc, exec, s[10:11]
	s_cbranch_vccnz .LBB0_44
	s_mul_hi_i32 s22, s26, 0x2e8ba2e9
	s_lshr_b32 s23, s22, 31
	s_ashr_i32 s22, s22, 5
	s_add_i32 s23, s22, s23
	s_lshl_b32 s22, s23, 6
	s_mulk_i32 s23, 0xea00
	s_add_i32 s28, s24, s25
	s_add_i32 s28, s28, s23
	s_ashr_i32 s29, s28, 31
	v_or_b32_e32 v164, s22, v93
	v_lshl_add_u64 v[160:161], s[28:29], 2, v[88:89]
	v_mad_i64_i32 v[122:123], s[28:29], v164, s19, v[160:161]
	global_load_dword v121, v[122:123], off nt
	v_or_b32_e32 v122, 2, v164
	v_mad_i64_i32 v[122:123], s[28:29], v122, s19, v[160:161]
	global_load_dword v122, v[122:123], off nt
	v_or_b32_e32 v123, 4, v164
	v_mad_i64_i32 v[136:137], s[28:29], v123, s19, v[160:161]
	v_or_b32_e32 v124, 6, v164
	global_load_dword v123, v[136:137], off nt
	v_mad_i64_i32 v[136:137], s[28:29], v124, s19, v[160:161]
	v_or_b32_e32 v127, 8, v164
	global_load_dword v124, v[136:137], off nt
	v_mad_i64_i32 v[136:137], s[28:29], v127, s19, v[160:161]
	v_or_b32_e32 v131, 10, v164
	global_load_dword v127, v[136:137], off nt
	v_mad_i64_i32 v[136:137], s[28:29], v131, s19, v[160:161]
	v_or_b32_e32 v134, 12, v164
	global_load_dword v131, v[136:137], off nt
	v_mad_i64_i32 v[136:137], s[28:29], v134, s19, v[160:161]
	global_load_dword v134, v[136:137], off nt
	v_or_b32_e32 v136, 14, v164
	v_mad_i64_i32 v[136:137], s[28:29], v136, s19, v[160:161]
	global_load_dword v136, v[136:137], off nt
	v_or_b32_e32 v137, 16, v164
	v_mad_i64_i32 v[138:139], s[28:29], v137, s19, v[160:161]
	global_load_dword v137, v[138:139], off nt
	v_or_b32_e32 v138, 18, v164
	v_mad_i64_i32 v[138:139], s[28:29], v138, s19, v[160:161]
	global_load_dword v138, v[138:139], off nt
	v_or_b32_e32 v139, 20, v164
	v_mad_i64_i32 v[140:141], s[28:29], v139, s19, v[160:161]
	global_load_dword v139, v[140:141], off nt
	v_or_b32_e32 v140, 22, v164
	v_mad_i64_i32 v[140:141], s[28:29], v140, s19, v[160:161]
	global_load_dword v140, v[140:141], off nt
	v_or_b32_e32 v141, 24, v164
	v_mad_i64_i32 v[142:143], s[28:29], v141, s19, v[160:161]
	global_load_dword v141, v[142:143], off nt
	v_or_b32_e32 v142, 26, v164
	v_mad_i64_i32 v[142:143], s[28:29], v142, s19, v[160:161]
	global_load_dword v142, v[142:143], off nt
	v_or_b32_e32 v143, 28, v164
	v_mad_i64_i32 v[144:145], s[28:29], v143, s19, v[160:161]
	global_load_dword v143, v[144:145], off nt
	v_or_b32_e32 v144, 30, v164
	v_mad_i64_i32 v[144:145], s[28:29], v144, s19, v[160:161]
	global_load_dword v144, v[144:145], off nt
	v_or_b32_e32 v145, 32, v164
	v_mad_i64_i32 v[146:147], s[28:29], v145, s19, v[160:161]
	global_load_dword v145, v[146:147], off nt
	v_or_b32_e32 v146, 34, v164
	v_mad_i64_i32 v[146:147], s[28:29], v146, s19, v[160:161]
	global_load_dword v146, v[146:147], off nt
	v_or_b32_e32 v147, 36, v164
	v_mad_i64_i32 v[148:149], s[28:29], v147, s19, v[160:161]
	global_load_dword v147, v[148:149], off nt
	v_or_b32_e32 v148, 38, v164
	v_mad_i64_i32 v[148:149], s[28:29], v148, s19, v[160:161]
	global_load_dword v148, v[148:149], off nt
	v_or_b32_e32 v149, 40, v164
	v_mad_i64_i32 v[150:151], s[28:29], v149, s19, v[160:161]
	global_load_dword v149, v[150:151], off nt
	v_or_b32_e32 v150, 42, v164
	v_mad_i64_i32 v[150:151], s[28:29], v150, s19, v[160:161]
	global_load_dword v150, v[150:151], off nt
	v_or_b32_e32 v151, 44, v164
	v_mad_i64_i32 v[152:153], s[28:29], v151, s19, v[160:161]
	global_load_dword v151, v[152:153], off nt
	v_or_b32_e32 v152, 46, v164
	v_mad_i64_i32 v[152:153], s[28:29], v152, s19, v[160:161]
	global_load_dword v152, v[152:153], off nt
	v_or_b32_e32 v153, 48, v164
	v_mad_i64_i32 v[154:155], s[28:29], v153, s19, v[160:161]
	global_load_dword v153, v[154:155], off nt
	v_or_b32_e32 v154, 50, v164
	v_mad_i64_i32 v[154:155], s[28:29], v154, s19, v[160:161]
	global_load_dword v154, v[154:155], off nt
	v_or_b32_e32 v155, 52, v164
	v_mad_i64_i32 v[156:157], s[28:29], v155, s19, v[160:161]
	global_load_dword v155, v[156:157], off nt
	v_or_b32_e32 v156, 54, v164
	v_mad_i64_i32 v[156:157], s[28:29], v156, s19, v[160:161]
	global_load_dword v156, v[156:157], off nt
	v_or_b32_e32 v157, 56, v164
	v_mad_i64_i32 v[158:159], s[28:29], v157, s19, v[160:161]
	global_load_dword v157, v[158:159], off nt
	v_or_b32_e32 v158, 58, v164
	v_mad_i64_i32 v[158:159], s[28:29], v158, s19, v[160:161]
	global_load_dword v158, v[158:159], off nt
	v_or_b32_e32 v159, 60, v164
	v_mad_i64_i32 v[162:163], s[28:29], v159, s19, v[160:161]
	global_load_dword v159, v[162:163], off nt
	v_or_b32_e32 v162, 62, v164
	v_mad_i64_i32 v[160:161], s[28:29], v162, s19, v[160:161]
	global_load_dword v160, v[160:161], off nt
	s_andn2_b64 vcc, exec, s[20:21]
	s_cbranch_vccnz .LBB0_44
	s_ashr_i32 s23, s22, 31
	v_lshl_add_u64 v[8:9], s[22:23], 2, v[20:21]
	global_load_dwordx4 v[12:15], v[8:9], off offset:16
	s_nop 0
	global_load_dwordx4 v[8:11], v[8:9], off
	s_waitcnt vmcnt(63)
	ds_write2_b32 v95, v97, v98 offset1:66
	s_waitcnt vmcnt(62)
	ds_write2_b32 v95, v99, v100 offset0:132 offset1:198
	v_add_u32_e32 v97, 0x400, v95
	s_waitcnt vmcnt(60)
	ds_write2_b32 v97, v101, v102 offset0:8 offset1:74
	s_waitcnt vmcnt(58)
	ds_write2_b32 v97, v103, v104 offset0:140 offset1:206
	v_add_u32_e32 v97, 0x800, v95
	s_waitcnt vmcnt(56)
	ds_write2_b32 v97, v105, v106 offset0:16 offset1:82
	s_waitcnt vmcnt(54)
	ds_write2_b32 v97, v107, v108 offset0:148 offset1:214
	v_add_u32_e32 v97, 0xc00, v95
	s_waitcnt vmcnt(52)
	ds_write2_b32 v97, v109, v110 offset0:24 offset1:90
	s_waitcnt vmcnt(50)
	ds_write2_b32 v97, v111, v112 offset0:156 offset1:222
	v_add_u32_e32 v97, 0x1000, v95
	s_waitcnt vmcnt(48)
	ds_write2_b32 v97, v113, v114 offset0:32 offset1:98
	s_waitcnt vmcnt(46)
	ds_write2_b32 v97, v115, v116 offset0:164 offset1:230
	v_add_u32_e32 v97, 0x1400, v95
	s_waitcnt vmcnt(44)
	ds_write2_b32 v97, v117, v118 offset0:40 offset1:106
	s_waitcnt vmcnt(42)
	ds_write2_b32 v97, v119, v120 offset0:172 offset1:238
	v_add_u32_e32 v97, 0x1800, v95
	s_waitcnt vmcnt(40)
	ds_write2_b32 v97, v125, v126 offset0:48 offset1:114
	s_waitcnt vmcnt(38)
	ds_write2_b32 v97, v128, v129 offset0:180 offset1:246
	v_add_u32_e32 v97, 0x1c00, v95
	s_waitcnt vmcnt(36)
	ds_write2_b32 v97, v130, v132 offset0:56 offset1:122
	s_waitcnt vmcnt(34)
	s_branch .Ltw_join_4
; #define LAS __attribute__((address_space(3)))
; template <int MODE>
; __device__ __forceinline__ void transpose_weight(const float* W, int K, int N, bf16_t* WT, LAS float* scr, int gw, int NGW, int lane, const float* gk = nullptr) {
;     const int nblk = N / 32, nitems = (K / 64) * nblk;
;     const int c = lane & 7;
;     float cur[32], nxt[32];
;     f32x4 gc0 = {1.f, 1.f, 1.f, 1.f}, gc1 = gc0, gn0 = gc0, gn1 = gc0;
;     int it = gw;
;     if (it < nitems) TW_LOAD(it, cur, gc0, gc1);
; __global__ void __launch_bounds__(NTHREADS, 2) fwd_megakernel(Args a) {
;     ...
;     transpose_weight<0>(ap->in[25], DM, DFF, WU, scr, gw, NGW, lane, ap->in[23]);
.LBB0_48:
	s_load_dwordx2 s[10:11], s[14:15], 0xc8
	v_mov_b32_e32 v17, 0
	s_waitcnt lgkmcnt(0)
	s_add_u32 s4, s10, s4
	s_addc_u32 s5, s11, s5
	v_lshl_add_u64 v[0:1], s[4:5], 0, v[16:17]
	v_lshl_add_u64 v[2:3], v[0:1], 0, v[86:87]
	v_lshl_add_u64 v[4:5], v[0:1], 0, v[84:85]
	v_lshl_add_u64 v[6:7], v[0:1], 0, v[82:83]
	v_lshl_add_u64 v[8:9], v[0:1], 0, v[80:81]
	v_lshl_add_u64 v[10:11], v[0:1], 0, v[78:79]
	v_lshl_add_u64 v[12:13], v[0:1], 0, v[76:77]
	v_lshl_add_u64 v[14:15], v[0:1], 0, v[74:75]
	v_lshl_add_u64 v[80:81], v[0:1], 0, v[72:73]
	global_load_dword v72, v[2:3], off nt
	global_load_dword v73, v[4:5], off nt
	global_load_dword v74, v[6:7], off nt
	global_load_dword v75, v[8:9], off nt
	global_load_dword v76, v[10:11], off nt
	global_load_dword v77, v[12:13], off nt
	global_load_dword v78, v[14:15], off nt
	global_load_dword v79, v[80:81], off nt
	v_lshl_add_u64 v[2:3], v[0:1], 0, v[70:71]
	v_lshl_add_u64 v[4:5], v[0:1], 0, v[68:69]
	v_lshl_add_u64 v[6:7], v[0:1], 0, v[66:67]
	v_lshl_add_u64 v[8:9], v[0:1], 0, v[64:65]
	v_lshl_add_u64 v[10:11], v[0:1], 0, v[62:63]
	v_lshl_add_u64 v[12:13], v[0:1], 0, v[60:61]
	v_lshl_add_u64 v[14:15], v[0:1], 0, v[58:59]
	v_lshl_add_u64 v[64:65], v[0:1], 0, v[56:57]
	global_load_dword v56, v[2:3], off nt
	global_load_dword v57, v[4:5], off nt
	global_load_dword v58, v[6:7], off nt
	global_load_dword v59, v[8:9], off nt
	global_load_dword v60, v[10:11], off nt
	global_load_dword v61, v[12:13], off nt
	global_load_dword v62, v[14:15], off nt
	global_load_dword v63, v[64:65], off nt
	v_lshl_add_u64 v[2:3], v[0:1], 0, v[54:55]
	v_lshl_add_u64 v[4:5], v[0:1], 0, v[52:53]
	v_lshl_add_u64 v[6:7], v[0:1], 0, v[50:51]
	v_lshl_add_u64 v[8:9], v[0:1], 0, v[48:49]
	v_lshl_add_u64 v[10:11], v[0:1], 0, v[46:47]
	v_lshl_add_u64 v[12:13], v[0:1], 0, v[44:45]
	v_lshl_add_u64 v[14:15], v[0:1], 0, v[42:43]
	v_lshl_add_u64 v[40:41], v[0:1], 0, v[40:41]
	global_load_dword v66, v[2:3], off nt
	global_load_dword v67, v[4:5], off nt
	global_load_dword v68, v[6:7], off nt
	global_load_dword v69, v[8:9], off nt
	global_load_dword v70, v[10:11], off nt
	global_load_dword v71, v[12:13], off nt
	global_load_dword v80, v[14:15], off nt
	global_load_dword v81, v[40:41], off nt
	v_lshl_add_u64 v[2:3], v[0:1], 0, v[38:39]
	v_lshl_add_u64 v[4:5], v[0:1], 0, v[36:37]
	v_lshl_add_u64 v[6:7], v[0:1], 0, v[34:35]
	v_lshl_add_u64 v[8:9], v[0:1], 0, v[32:33]
	v_lshl_add_u64 v[10:11], v[0:1], 0, v[30:31]
	v_lshl_add_u64 v[12:13], v[0:1], 0, v[28:29]
	v_lshl_add_u64 v[14:15], v[0:1], 0, v[26:27]
	v_lshl_add_u64 v[0:1], v[0:1], 0, v[24:25]
	global_load_dword v82, v[2:3], off nt
	global_load_dword v83, v[4:5], off nt
	global_load_dword v84, v[6:7], off nt
	global_load_dword v85, v[8:9], off nt
	global_load_dword v86, v[10:11], off nt
	global_load_dword v87, v[12:13], off nt
	global_load_dword v88, v[14:15], off nt
	global_load_dword v89, v[0:1], off nt
	v_cndmask_b32_e64 v0, 0, 1, s[20:21]
	v_cmp_ne_u32_e64 s[4:5], 1, v0
	s_andn2_b64 vcc, exec, s[20:21]
	s_cbranch_vccnz .LBB0_51
	s_ashr_i32 s19, s18, 31
	s_lshl_b64 s[18:19], s[18:19], 2
	s_add_u32 s8, s8, s18
	s_addc_u32 s9, s9, s19
	v_lshl_add_u64 v[0:1], v[22:23], 2, s[8:9]
	global_load_dwordx4 v[4:7], v[0:1], off offset:16
	global_load_dwordx4 v[8:11], v[0:1], off
	s_branch .LBB0_52

; template <int MODE>
; __device__ __forceinline__ void transpose_weight(const float* W, int K, int N, bf16_t* WT, LAS float* scr, int gw, int NGW, int lane, const float* gk = nullptr) {
;     ...
;     while (it < nitems) {
;         const int itn = it + NGW;
;         if (itn < nitems) TW_LOAD(itn, nxt, gn0, gn1);
;         const int kb = it / nblk, nb = it % nblk, k0 = 64 * kb, n0 = 32 * nb;
;         int drow = n0;
;         if (MODE == 1) { if (n0 < 2048) drow = 4096 + n0; else if (n0 < 4096) { const int cc = n0 - 2048; drow = (cc >> 7) * 256 + (cc & 127); } else { const int cc = n0 - 4096; drow = (cc >> 7) * 256 + 128 + (cc & 127); } }
; #pragma unroll
;         for (int i = 0; i < 32; ++i) { const int kk = 2 * i + (lane >> 5); scr[kk * 33 + (lane & 31)] = cur[i]; }
.LBB0_54:
	s_add_i32 s20, s21, s69
	s_cmpk_gt_i32 s20, 0x15ff
	s_cselect_b64 s[8:9], -1, 0
	s_and_b64 vcc, exec, s[8:9]
	s_cbranch_vccnz .LBB0_53
	s_mul_hi_i32 s10, s20, 0x2e8ba2e9
	s_lshr_b32 s11, s10, 31
	s_ashr_i32 s10, s10, 5
	s_add_i32 s11, s10, s11
	s_lshl_b32 s10, s11, 6
	s_mulk_i32 s11, 0xea00
	s_add_i32 s22, s24, s19
	s_add_i32 s22, s22, s11
	v_or_b32_e32 v97, s10, v93
	s_ashr_i32 s23, s22, 31
	v_lshl_add_u64 v[50:51], s[22:23], 2, v[22:23]
	v_or_b32_e32 v26, 2, v97
	v_mad_i64_i32 v[36:37], s[22:23], v26, s18, v[50:51]
	v_or_b32_e32 v26, 4, v97
	v_mad_i64_i32 v[38:39], s[22:23], v26, s18, v[50:51]
	v_or_b32_e32 v26, 6, v97
	v_mad_i64_i32 v[40:41], s[22:23], v26, s18, v[50:51]
	v_or_b32_e32 v26, 8, v97
	v_mad_i64_i32 v[42:43], s[22:23], v26, s18, v[50:51]
	v_or_b32_e32 v26, 10, v97
	v_mad_i64_i32 v[44:45], s[22:23], v26, s18, v[50:51]
	v_or_b32_e32 v26, 12, v97
	v_mad_i64_i32 v[34:35], s[22:23], v97, s18, v[50:51]
	v_mad_i64_i32 v[46:47], s[22:23], v26, s18, v[50:51]
	v_or_b32_e32 v26, 14, v97
	v_mad_i64_i32 v[48:49], s[22:23], v26, s18, v[50:51]
	global_load_dword v33, v[34:35], off nt
	global_load_dword v32, v[36:37], off nt
	global_load_dword v31, v[38:39], off nt
	global_load_dword v30, v[40:41], off nt
	global_load_dword v29, v[42:43], off nt
	global_load_dword v28, v[44:45], off nt
	global_load_dword v27, v[46:47], off nt
	global_load_dword v26, v[48:49], off nt
	v_or_b32_e32 v34, 16, v97
	v_mad_i64_i32 v[42:43], s[22:23], v34, s18, v[50:51]
	v_or_b32_e32 v34, 18, v97
	v_mad_i64_i32 v[44:45], s[22:23], v34, s18, v[50:51]
	v_or_b32_e32 v34, 20, v97
	v_mad_i64_i32 v[46:47], s[22:23], v34, s18, v[50:51]
	v_or_b32_e32 v34, 22, v97
	v_mad_i64_i32 v[48:49], s[22:23], v34, s18, v[50:51]
	v_or_b32_e32 v34, 24, v97
	v_mad_i64_i32 v[52:53], s[22:23], v34, s18, v[50:51]
	v_or_b32_e32 v34, 26, v97
	v_mad_i64_i32 v[54:55], s[22:23], v34, s18, v[50:51]
	v_or_b32_e32 v34, 28, v97
	v_mad_i64_i32 v[64:65], s[22:23], v34, s18, v[50:51]
	v_or_b32_e32 v34, 30, v97
	v_mad_i64_i32 v[90:91], s[22:23], v34, s18, v[50:51]
	global_load_dword v41, v[42:43], off nt
	global_load_dword v40, v[44:45], off nt
	global_load_dword v39, v[46:47], off nt
	global_load_dword v38, v[48:49], off nt
	global_load_dword v37, v[52:53], off nt
	global_load_dword v36, v[54:55], off nt
	global_load_dword v35, v[64:65], off nt
	global_load_dword v34, v[90:91], off nt
	v_or_b32_e32 v42, 32, v97
	v_mad_i64_i32 v[52:53], s[22:23], v42, s18, v[50:51]
	v_or_b32_e32 v42, 34, v97
	v_mad_i64_i32 v[54:55], s[22:23], v42, s18, v[50:51]
	v_or_b32_e32 v42, 36, v97
	v_mad_i64_i32 v[64:65], s[22:23], v42, s18, v[50:51]
	v_or_b32_e32 v42, 38, v97
	v_mad_i64_i32 v[90:91], s[22:23], v42, s18, v[50:51]
	v_or_b32_e32 v42, 40, v97
	v_mad_i64_i32 v[98:99], s[22:23], v42, s18, v[50:51]
	v_or_b32_e32 v42, 42, v97
	v_mad_i64_i32 v[100:101], s[22:23], v42, s18, v[50:51]
	v_or_b32_e32 v42, 44, v97
	v_mad_i64_i32 v[102:103], s[22:23], v42, s18, v[50:51]
	v_or_b32_e32 v42, 46, v97
	v_mad_i64_i32 v[104:105], s[22:23], v42, s18, v[50:51]
	global_load_dword v49, v[52:53], off nt
	global_load_dword v48, v[54:55], off nt
	global_load_dword v47, v[64:65], off nt
	global_load_dword v46, v[90:91], off nt
	global_load_dword v45, v[98:99], off nt
	global_load_dword v44, v[100:101], off nt
	global_load_dword v43, v[102:103], off nt
	global_load_dword v42, v[104:105], off nt
	v_or_b32_e32 v52, 48, v97
	v_mad_i64_i32 v[90:91], s[22:23], v52, s18, v[50:51]
	v_or_b32_e32 v52, 50, v97
	v_mad_i64_i32 v[98:99], s[22:23], v52, s18, v[50:51]
	v_or_b32_e32 v52, 52, v97
	v_mad_i64_i32 v[100:101], s[22:23], v52, s18, v[50:51]
	v_or_b32_e32 v52, 54, v97
	v_mad_i64_i32 v[102:103], s[22:23], v52, s18, v[50:51]
	v_or_b32_e32 v52, 56, v97
	v_mad_i64_i32 v[104:105], s[22:23], v52, s18, v[50:51]
	v_or_b32_e32 v52, 58, v97
	v_mad_i64_i32 v[106:107], s[22:23], v52, s18, v[50:51]
	v_or_b32_e32 v52, 60, v97
	v_mad_i64_i32 v[108:109], s[22:23], v52, s18, v[50:51]
	v_or_b32_e32 v52, 62, v97
	v_mad_i64_i32 v[110:111], s[22:23], v52, s18, v[50:51]
	global_load_dword v65, v[90:91], off nt
	global_load_dword v64, v[98:99], off nt
	global_load_dword v55, v[100:101], off nt
	global_load_dword v54, v[102:103], off nt
	global_load_dword v53, v[104:105], off nt
	global_load_dword v52, v[106:107], off nt
	global_load_dword v51, v[108:109], off nt
	global_load_dword v50, v[110:111], off nt
	s_and_b64 vcc, exec, s[4:5]
	s_cbranch_vccnz .LBB0_53
	s_ashr_i32 s11, s10, 31
	v_lshl_add_u64 v[90:91], s[10:11], 2, v[20:21]
	global_load_dwordx4 v[12:15], v[90:91], off offset:16
	global_load_dwordx4 v[0:3], v[90:91], off
	s_waitcnt vmcnt(63)
	ds_write2_b32 v95, v72, v73 offset1:66
	s_waitcnt vmcnt(62)
	ds_write2_b32 v95, v74, v75 offset0:132 offset1:198
	v_add_u32_e32 v72, 0x400, v95
	s_waitcnt vmcnt(60)
	ds_write2_b32 v72, v76, v77 offset0:8 offset1:74
	s_waitcnt vmcnt(58)
	ds_write2_b32 v72, v78, v79 offset0:140 offset1:206
	v_add_u32_e32 v72, 0x800, v95
	s_waitcnt vmcnt(56)
	ds_write2_b32 v72, v56, v57 offset0:16 offset1:82
	s_waitcnt vmcnt(54)
	ds_write2_b32 v72, v58, v59 offset0:148 offset1:214
	v_add_u32_e32 v56, 0xc00, v95
	s_waitcnt vmcnt(52)
	ds_write2_b32 v56, v60, v61 offset0:24 offset1:90
	s_waitcnt vmcnt(50)
	ds_write2_b32 v56, v62, v63 offset0:156 offset1:222
	v_add_u32_e32 v56, 0x1000, v95
	s_waitcnt vmcnt(48)
	ds_write2_b32 v56, v66, v67 offset0:32 offset1:98
	s_waitcnt vmcnt(46)
	ds_write2_b32 v56, v68, v69 offset0:164 offset1:230
	v_add_u32_e32 v56, 0x1400, v95
	s_waitcnt vmcnt(44)
	ds_write2_b32 v56, v70, v71 offset0:40 offset1:106
	s_waitcnt vmcnt(42)
	ds_write2_b32 v56, v80, v81 offset0:172 offset1:238
	v_add_u32_e32 v56, 0x1800, v95
	s_waitcnt vmcnt(40)
	ds_write2_b32 v56, v82, v83 offset0:48 offset1:114
	s_waitcnt vmcnt(38)
	ds_write2_b32 v56, v84, v85 offset0:180 offset1:246
	v_add_u32_e32 v56, 0x1c00, v95
	s_waitcnt vmcnt(36)
	ds_write2_b32 v56, v86, v87 offset0:56 offset1:122
	s_waitcnt vmcnt(34)
	s_branch .Ltw_join_5
; #define LAS __attribute__((address_space(3)))
; template <int MODE>
; __device__ __forceinline__ void transpose_weight(const float* W, int K, int N, bf16_t* WT, LAS float* scr, int gw, int NGW, int lane, const float* gk = nullptr) {
;     const int nblk = N / 32, nitems = (K / 64) * nblk;
;     const int c = lane & 7;
;     float cur[32], nxt[32];
;     f32x4 gc0 = {1.f, 1.f, 1.f, 1.f}, gc1 = gc0, gn0 = gc0, gn1 = gc0;
;     int it = gw;
;     if (it < nitems) TW_LOAD(it, cur, gc0, gc1);
; __global__ void __launch_bounds__(NTHREADS, 2) fwd_megakernel(Args a) {
;     ...
;     transpose_weight<0>(ap->in[28], DFF, DM, WD, scr, gw, NGW, lane);
.LBB0_57:
	s_ashr_i32 s8, s6, 31
	s_lshr_b32 s8, s8, 26
	s_add_i32 s8, s6, s8
	s_load_dwordx2 s[4:5], s[14:15], 0xe0
	s_and_b32 s9, s8, 0xffffffc0
	s_sub_i32 s8, s6, s9
	s_lshl_b32 s8, s8, 5
	v_or_b32_e32 v0, s9, v93
	s_ashr_i32 s9, s8, 31
	s_lshl_b64 s[8:9], s[8:9], 2
	s_waitcnt lgkmcnt(0)
	s_add_u32 s8, s4, s8
	v_or_b32_e32 v8, 4, v0
	s_addc_u32 s9, s5, s9
	v_mov_b32_e32 v17, 0
	v_ashrrev_i32_e32 v9, 31, v8
	v_lshl_add_u64 v[2:3], s[8:9], 0, v[16:17]
	v_lshlrev_b64 v[8:9], 13, v[8:9]
	v_lshl_add_u64 v[20:21], v[2:3], 0, v[8:9]
	v_or_b32_e32 v8, 6, v0
	v_ashrrev_i32_e32 v9, 31, v8
	v_lshlrev_b64 v[8:9], 13, v[8:9]
	v_lshl_add_u64 v[22:23], v[2:3], 0, v[8:9]
	v_or_b32_e32 v8, 8, v0
	v_ashrrev_i32_e32 v9, 31, v8
	v_lshlrev_b64 v[8:9], 13, v[8:9]
	v_lshl_add_u64 v[24:25], v[2:3], 0, v[8:9]
	v_or_b32_e32 v8, 10, v0
	v_ashrrev_i32_e32 v9, 31, v8
	v_lshlrev_b64 v[8:9], 13, v[8:9]
	v_lshl_add_u64 v[26:27], v[2:3], 0, v[8:9]
	v_or_b32_e32 v8, 12, v0
	v_ashrrev_i32_e32 v9, 31, v8
	v_lshlrev_b64 v[8:9], 13, v[8:9]
	v_ashrrev_i32_e32 v1, 31, v0
	v_or_b32_e32 v6, 2, v0
	v_lshl_add_u64 v[28:29], v[2:3], 0, v[8:9]
	v_or_b32_e32 v8, 14, v0
	v_lshlrev_b64 v[4:5], 13, v[0:1]
	v_ashrrev_i32_e32 v7, 31, v6
	v_ashrrev_i32_e32 v9, 31, v8
	v_lshl_add_u64 v[4:5], v[2:3], 0, v[4:5]
	v_lshlrev_b64 v[6:7], 13, v[6:7]
	v_lshlrev_b64 v[8:9], 13, v[8:9]
	v_lshl_add_u64 v[6:7], v[2:3], 0, v[6:7]
	v_lshl_add_u64 v[30:31], v[2:3], 0, v[8:9]
	global_load_dword v8, v[4:5], off nt
	global_load_dword v9, v[6:7], off nt
	global_load_dword v10, v[20:21], off nt
	global_load_dword v11, v[22:23], off nt
	global_load_dword v12, v[24:25], off nt
	global_load_dword v13, v[26:27], off nt
	global_load_dword v14, v[28:29], off nt
	global_load_dword v15, v[30:31], off nt
	v_or_b32_e32 v20, 20, v0
	v_ashrrev_i32_e32 v21, 31, v20
	v_lshlrev_b64 v[20:21], 13, v[20:21]
	v_lshl_add_u64 v[28:29], v[2:3], 0, v[20:21]
	v_or_b32_e32 v20, 22, v0
	v_ashrrev_i32_e32 v21, 31, v20
	v_lshlrev_b64 v[20:21], 13, v[20:21]
	v_lshl_add_u64 v[30:31], v[2:3], 0, v[20:21]
	v_or_b32_e32 v20, 24, v0
	v_ashrrev_i32_e32 v21, 31, v20
	v_lshlrev_b64 v[20:21], 13, v[20:21]
	v_lshl_add_u64 v[32:33], v[2:3], 0, v[20:21]
	v_or_b32_e32 v20, 26, v0
	v_ashrrev_i32_e32 v21, 31, v20
	v_lshlrev_b64 v[20:21], 13, v[20:21]
	v_lshl_add_u64 v[34:35], v[2:3], 0, v[20:21]
	v_or_b32_e32 v20, 28, v0
	v_ashrrev_i32_e32 v21, 31, v20
	v_or_b32_e32 v4, 16, v0
	v_lshlrev_b64 v[20:21], 13, v[20:21]
	v_ashrrev_i32_e32 v5, 31, v4
	v_or_b32_e32 v6, 18, v0
	v_lshl_add_u64 v[36:37], v[2:3], 0, v[20:21]
	v_or_b32_e32 v20, 30, v0
	v_lshlrev_b64 v[4:5], 13, v[4:5]
	v_ashrrev_i32_e32 v7, 31, v6
	v_ashrrev_i32_e32 v21, 31, v20
	v_lshl_add_u64 v[4:5], v[2:3], 0, v[4:5]
	v_lshlrev_b64 v[6:7], 13, v[6:7]
	v_lshlrev_b64 v[20:21], 13, v[20:21]
	v_lshl_add_u64 v[6:7], v[2:3], 0, v[6:7]
	v_lshl_add_u64 v[38:39], v[2:3], 0, v[20:21]
	global_load_dword v20, v[4:5], off nt
	global_load_dword v21, v[6:7], off nt
	global_load_dword v22, v[28:29], off nt
	global_load_dword v23, v[30:31], off nt
	global_load_dword v24, v[32:33], off nt
	global_load_dword v25, v[34:35], off nt
	global_load_dword v26, v[36:37], off nt
	global_load_dword v27, v[38:39], off nt
	v_or_b32_e32 v28, 36, v0
	v_ashrrev_i32_e32 v29, 31, v28
	v_lshlrev_b64 v[28:29], 13, v[28:29]
	v_lshl_add_u64 v[36:37], v[2:3], 0, v[28:29]
	v_or_b32_e32 v28, 38, v0
	v_ashrrev_i32_e32 v29, 31, v28
	v_lshlrev_b64 v[28:29], 13, v[28:29]
	v_lshl_add_u64 v[38:39], v[2:3], 0, v[28:29]
	v_or_b32_e32 v28, 40, v0
	v_ashrrev_i32_e32 v29, 31, v28
	v_lshlrev_b64 v[28:29], 13, v[28:29]
	v_lshl_add_u64 v[40:41], v[2:3], 0, v[28:29]
	v_or_b32_e32 v28, 42, v0
	v_ashrrev_i32_e32 v29, 31, v28
	v_lshlrev_b64 v[28:29], 13, v[28:29]
	v_lshl_add_u64 v[42:43], v[2:3], 0, v[28:29]
	v_or_b32_e32 v28, 44, v0
	v_ashrrev_i32_e32 v29, 31, v28
	v_or_b32_e32 v4, 32, v0
	v_lshlrev_b64 v[28:29], 13, v[28:29]
	v_ashrrev_i32_e32 v5, 31, v4
	v_or_b32_e32 v6, 34, v0
	v_lshl_add_u64 v[44:45], v[2:3], 0, v[28:29]
	v_or_b32_e32 v28, 46, v0
	v_lshlrev_b64 v[4:5], 13, v[4:5]
	v_ashrrev_i32_e32 v7, 31, v6
	v_ashrrev_i32_e32 v29, 31, v28
	v_lshl_add_u64 v[4:5], v[2:3], 0, v[4:5]
	v_lshlrev_b64 v[6:7], 13, v[6:7]
	v_lshlrev_b64 v[28:29], 13, v[28:29]
	v_lshl_add_u64 v[6:7], v[2:3], 0, v[6:7]
	v_lshl_add_u64 v[46:47], v[2:3], 0, v[28:29]
	global_load_dword v28, v[4:5], off nt
	global_load_dword v29, v[6:7], off nt
	global_load_dword v30, v[36:37], off nt
	global_load_dword v31, v[38:39], off nt
	global_load_dword v32, v[40:41], off nt
	global_load_dword v33, v[42:43], off nt
	global_load_dword v34, v[44:45], off nt
	global_load_dword v35, v[46:47], off nt
	v_or_b32_e32 v40, 56, v0
	v_ashrrev_i32_e32 v41, 31, v40
	v_lshlrev_b64 v[40:41], 13, v[40:41]
	v_lshl_add_u64 v[48:49], v[2:3], 0, v[40:41]
	v_or_b32_e32 v40, 58, v0
	v_ashrrev_i32_e32 v41, 31, v40
	v_or_b32_e32 v4, 48, v0
	v_lshlrev_b64 v[40:41], 13, v[40:41]
	v_ashrrev_i32_e32 v5, 31, v4
	v_or_b32_e32 v6, 50, v0
	v_or_b32_e32 v36, 52, v0
	v_or_b32_e32 v38, 54, v0
	v_lshl_add_u64 v[50:51], v[2:3], 0, v[40:41]
	v_or_b32_e32 v40, 60, v0
	v_or_b32_e32 v0, 62, v0
	v_lshlrev_b64 v[4:5], 13, v[4:5]
	v_ashrrev_i32_e32 v7, 31, v6
	v_ashrrev_i32_e32 v37, 31, v36
	v_ashrrev_i32_e32 v39, 31, v38
	v_ashrrev_i32_e32 v41, 31, v40
	v_ashrrev_i32_e32 v1, 31, v0
	v_lshl_add_u64 v[4:5], v[2:3], 0, v[4:5]
	v_lshlrev_b64 v[6:7], 13, v[6:7]
	v_lshlrev_b64 v[36:37], 13, v[36:37]
	v_lshlrev_b64 v[38:39], 13, v[38:39]
	v_lshlrev_b64 v[40:41], 13, v[40:41]
	v_lshlrev_b64 v[0:1], 13, v[0:1]
	v_lshl_add_u64 v[6:7], v[2:3], 0, v[6:7]
	v_lshl_add_u64 v[36:37], v[2:3], 0, v[36:37]
	v_lshl_add_u64 v[38:39], v[2:3], 0, v[38:39]
	v_lshl_add_u64 v[52:53], v[2:3], 0, v[40:41]
	v_lshl_add_u64 v[0:1], v[2:3], 0, v[0:1]
	global_load_dword v40, v[4:5], off nt
	global_load_dword v41, v[6:7], off nt
	global_load_dword v42, v[36:37], off nt
	global_load_dword v43, v[38:39], off nt
	global_load_dword v44, v[48:49], off nt
	global_load_dword v45, v[50:51], off nt
	global_load_dword v46, v[52:53], off nt
	global_load_dword v47, v[0:1], off nt
	v_lshl_add_u64 v[0:1], s[4:5], 0, v[16:17]
	s_mov_b64 s[4:5], 0x2d00000
	v_lshl_add_u64 v[2:3], v[18:19], 0, s[4:5]
	s_mul_i32 s4, s6, 0x2c000
	s_movk_i32 s5, 0x1600
	v_mov_b32_e32 v4, s4
	s_add_i32 s4, s69, s6
	v_mad_u32_u24 v16, v94, s5, v4
	s_lshl_b32 s8, s4, 5
	s_mov_b32 s10, s6
	s_branch .LBB0_59

; template <int MODE>
; __device__ __forceinline__ void transpose_weight(const float* W, int K, int N, bf16_t* WT, LAS float* scr, int gw, int NGW, int lane, const float* gk = nullptr) {
;     ...
;     while (it < nitems) {
;         const int itn = it + NGW;
;         if (itn < nitems) TW_LOAD(itn, nxt, gn0, gn1);
.LBB0_59:
	s_add_i32 s9, s10, s69
	s_cmpk_gt_i32 s9, 0x15ff
	s_cselect_b64 s[4:5], -1, 0
	s_and_b64 vcc, exec, s[4:5]
	s_cbranch_vccnz .LBB0_58
	s_ashr_i32 s11, s9, 31
	s_lshr_b32 s11, s11, 26
	s_add_i32 s11, s9, s11
	s_and_b32 s19, s11, 0xffffffc0
	s_lshl_b32 s11, s11, 5
	s_and_b32 s11, s11, 0xfffff800
	s_sub_i32 s18, s8, s11
	v_or_b32_e32 v6, s19, v93
	s_ashr_i32 s19, s18, 31
	v_ashrrev_i32_e32 v7, 31, v6
	v_lshl_add_u64 v[4:5], s[18:19], 2, v[0:1]
	v_lshlrev_b64 v[18:19], 13, v[6:7]
	v_lshl_add_u64 v[48:49], v[4:5], 0, v[18:19]
	v_or_b32_e32 v18, 2, v6
	v_ashrrev_i32_e32 v19, 31, v18
	v_lshlrev_b64 v[18:19], 13, v[18:19]
	v_lshl_add_u64 v[50:51], v[4:5], 0, v[18:19]
	v_or_b32_e32 v18, 4, v6
	v_ashrrev_i32_e32 v19, 31, v18
	v_lshlrev_b64 v[18:19], 13, v[18:19]
	v_lshl_add_u64 v[52:53], v[4:5], 0, v[18:19]
	v_or_b32_e32 v18, 6, v6
	v_ashrrev_i32_e32 v19, 31, v18
	v_lshlrev_b64 v[18:19], 13, v[18:19]
	v_lshl_add_u64 v[54:55], v[4:5], 0, v[18:19]
	v_or_b32_e32 v18, 8, v6
	v_ashrrev_i32_e32 v19, 31, v18
	v_lshlrev_b64 v[18:19], 13, v[18:19]
	v_lshl_add_u64 v[56:57], v[4:5], 0, v[18:19]
	v_or_b32_e32 v18, 10, v6
	v_ashrrev_i32_e32 v19, 31, v18
	v_lshlrev_b64 v[18:19], 13, v[18:19]
	v_lshl_add_u64 v[58:59], v[4:5], 0, v[18:19]
	v_or_b32_e32 v18, 12, v6
	v_ashrrev_i32_e32 v19, 31, v18
	v_lshlrev_b64 v[18:19], 13, v[18:19]
	v_lshl_add_u64 v[60:61], v[4:5], 0, v[18:19]
	v_or_b32_e32 v18, 14, v6
	v_ashrrev_i32_e32 v19, 31, v18
	v_lshlrev_b64 v[18:19], 13, v[18:19]
	v_lshl_add_u64 v[62:63], v[4:5], 0, v[18:19]
	global_load_dword v39, v[48:49], off nt
	global_load_dword v38, v[50:51], off nt
	global_load_dword v37, v[52:53], off nt
	global_load_dword v36, v[54:55], off nt
	global_load_dword v19, v[56:57], off nt
	global_load_dword v18, v[58:59], off nt
	global_load_dword v17, v[60:61], off nt
	global_load_dword v7, v[62:63], off nt
	v_or_b32_e32 v48, 16, v6
	v_ashrrev_i32_e32 v49, 31, v48
	v_lshlrev_b64 v[48:49], 13, v[48:49]
	v_lshl_add_u64 v[56:57], v[4:5], 0, v[48:49]
	v_or_b32_e32 v48, 18, v6
	v_ashrrev_i32_e32 v49, 31, v48
	v_lshlrev_b64 v[48:49], 13, v[48:49]
	v_lshl_add_u64 v[58:59], v[4:5], 0, v[48:49]
	v_or_b32_e32 v48, 20, v6
	v_ashrrev_i32_e32 v49, 31, v48
	v_lshlrev_b64 v[48:49], 13, v[48:49]
	v_lshl_add_u64 v[60:61], v[4:5], 0, v[48:49]
	v_or_b32_e32 v48, 22, v6
	v_ashrrev_i32_e32 v49, 31, v48
	v_lshlrev_b64 v[48:49], 13, v[48:49]
	v_lshl_add_u64 v[62:63], v[4:5], 0, v[48:49]
	v_or_b32_e32 v48, 24, v6
	v_ashrrev_i32_e32 v49, 31, v48
	v_lshlrev_b64 v[48:49], 13, v[48:49]
	v_lshl_add_u64 v[64:65], v[4:5], 0, v[48:49]
	v_or_b32_e32 v48, 26, v6
	v_ashrrev_i32_e32 v49, 31, v48
	v_lshlrev_b64 v[48:49], 13, v[48:49]
	v_lshl_add_u64 v[66:67], v[4:5], 0, v[48:49]
	v_or_b32_e32 v48, 28, v6
	v_ashrrev_i32_e32 v49, 31, v48
	v_lshlrev_b64 v[48:49], 13, v[48:49]
	v_lshl_add_u64 v[68:69], v[4:5], 0, v[48:49]
	v_or_b32_e32 v48, 30, v6
	v_ashrrev_i32_e32 v49, 31, v48
	v_lshlrev_b64 v[48:49], 13, v[48:49]
	v_lshl_add_u64 v[70:71], v[4:5], 0, v[48:49]
	global_load_dword v55, v[56:57], off nt
	global_load_dword v54, v[58:59], off nt
	global_load_dword v53, v[60:61], off nt
	global_load_dword v52, v[62:63], off nt
	global_load_dword v51, v[64:65], off nt
	global_load_dword v50, v[66:67], off nt
	global_load_dword v49, v[68:69], off nt
	global_load_dword v48, v[70:71], off nt
	v_or_b32_e32 v56, 32, v6
	v_ashrrev_i32_e32 v57, 31, v56
	v_lshlrev_b64 v[56:57], 13, v[56:57]
	v_lshl_add_u64 v[64:65], v[4:5], 0, v[56:57]
	v_or_b32_e32 v56, 34, v6
	v_ashrrev_i32_e32 v57, 31, v56
	v_lshlrev_b64 v[56:57], 13, v[56:57]
	v_lshl_add_u64 v[66:67], v[4:5], 0, v[56:57]
	v_or_b32_e32 v56, 36, v6
	v_ashrrev_i32_e32 v57, 31, v56
	v_lshlrev_b64 v[56:57], 13, v[56:57]
	v_lshl_add_u64 v[68:69], v[4:5], 0, v[56:57]
	v_or_b32_e32 v56, 38, v6
	v_ashrrev_i32_e32 v57, 31, v56
	v_lshlrev_b64 v[56:57], 13, v[56:57]
	v_lshl_add_u64 v[70:71], v[4:5], 0, v[56:57]
	v_or_b32_e32 v56, 40, v6
	v_ashrrev_i32_e32 v57, 31, v56
	v_lshlrev_b64 v[56:57], 13, v[56:57]
	v_lshl_add_u64 v[72:73], v[4:5], 0, v[56:57]
	v_or_b32_e32 v56, 42, v6
	v_ashrrev_i32_e32 v57, 31, v56
	v_lshlrev_b64 v[56:57], 13, v[56:57]
	v_lshl_add_u64 v[74:75], v[4:5], 0, v[56:57]
	v_or_b32_e32 v56, 44, v6
	v_ashrrev_i32_e32 v57, 31, v56
	v_lshlrev_b64 v[56:57], 13, v[56:57]
	v_lshl_add_u64 v[76:77], v[4:5], 0, v[56:57]
	v_or_b32_e32 v56, 46, v6
	v_ashrrev_i32_e32 v57, 31, v56
	v_lshlrev_b64 v[56:57], 13, v[56:57]
	v_lshl_add_u64 v[78:79], v[4:5], 0, v[56:57]
	global_load_dword v63, v[64:65], off nt
	global_load_dword v62, v[66:67], off nt
	global_load_dword v61, v[68:69], off nt
	global_load_dword v60, v[70:71], off nt
	global_load_dword v59, v[72:73], off nt
	global_load_dword v58, v[74:75], off nt
	global_load_dword v57, v[76:77], off nt
	global_load_dword v56, v[78:79], off nt
	v_or_b32_e32 v64, 48, v6
	v_ashrrev_i32_e32 v65, 31, v64
	v_lshlrev_b64 v[64:65], 13, v[64:65]
	v_lshl_add_u64 v[70:71], v[4:5], 0, v[64:65]
	v_or_b32_e32 v64, 50, v6
	v_ashrrev_i32_e32 v65, 31, v64
	v_lshlrev_b64 v[64:65], 13, v[64:65]
	v_lshl_add_u64 v[72:73], v[4:5], 0, v[64:65]
	v_or_b32_e32 v64, 52, v6
	v_ashrrev_i32_e32 v65, 31, v64
	v_lshlrev_b64 v[64:65], 13, v[64:65]
	v_lshl_add_u64 v[74:75], v[4:5], 0, v[64:65]
	v_or_b32_e32 v64, 54, v6
	v_ashrrev_i32_e32 v65, 31, v64
	v_lshlrev_b64 v[64:65], 13, v[64:65]
	v_lshl_add_u64 v[76:77], v[4:5], 0, v[64:65]
	v_or_b32_e32 v64, 56, v6
	v_ashrrev_i32_e32 v65, 31, v64
	v_lshlrev_b64 v[64:65], 13, v[64:65]
	v_lshl_add_u64 v[78:79], v[4:5], 0, v[64:65]
	v_or_b32_e32 v64, 58, v6
	v_ashrrev_i32_e32 v65, 31, v64
	v_lshlrev_b64 v[64:65], 13, v[64:65]
	v_lshl_add_u64 v[80:81], v[4:5], 0, v[64:65]
	v_or_b32_e32 v64, 60, v6
	v_ashrrev_i32_e32 v65, 31, v64
	v_lshlrev_b64 v[64:65], 13, v[64:65]
	v_lshl_add_u64 v[82:83], v[4:5], 0, v[64:65]
	v_or_b32_e32 v64, 62, v6
	v_ashrrev_i32_e32 v65, 31, v64
	v_lshlrev_b64 v[64:65], 13, v[64:65]
	v_lshl_add_u64 v[84:85], v[4:5], 0, v[64:65]
	global_load_dword v68, v[70:71], off nt
	global_load_dword v67, v[72:73], off nt
	global_load_dword v66, v[74:75], off nt
	global_load_dword v65, v[76:77], off nt
	global_load_dword v64, v[78:79], off nt
	global_load_dword v6, v[80:81], off nt
	global_load_dword v5, v[82:83], off nt
	global_load_dword v4, v[84:85], off nt
	s_waitcnt vmcnt(62)
; #define LDS_WAIT() asm volatile("s_waitcnt lgkmcnt(0)" ::: "memory")
; template <int MODE>
; __device__ __forceinline__ void transpose_weight(const float* W, int K, int N, bf16_t* WT, LAS float* scr, int gw, int NGW, int lane, const float* gk = nullptr) {
;     ...
; #pragma unroll
;         for (int i = 0; i < 32; ++i) { const int kk = 2 * i + (lane >> 5); scr[kk * 33 + (lane & 31)] = cur[i]; }
;         LDS_WAIT(); asm volatile("" ::: "memory");
	ds_write2_b32 v95, v8, v9 offset1:66
	s_waitcnt vmcnt(60)
	ds_write2_b32 v95, v10, v11 offset0:132 offset1:198
	v_add_u32_e32 v8, 0x400, v95
	s_waitcnt vmcnt(58)
	ds_write2_b32 v8, v12, v13 offset0:8 offset1:74
	s_waitcnt vmcnt(56)
	ds_write2_b32 v8, v14, v15 offset0:140 offset1:206
	v_add_u32_e32 v8, 0x800, v95
	s_waitcnt vmcnt(54)
	ds_write2_b32 v8, v20, v21 offset0:16 offset1:82
	s_waitcnt vmcnt(52)
	ds_write2_b32 v8, v22, v23 offset0:148 offset1:214
	v_add_u32_e32 v8, 0xc00, v95
	s_waitcnt vmcnt(50)
	ds_write2_b32 v8, v24, v25 offset0:24 offset1:90
	s_waitcnt vmcnt(48)
	ds_write2_b32 v8, v26, v27 offset0:156 offset1:222
	v_add_u32_e32 v8, 0x1000, v95
	s_waitcnt vmcnt(46)
	ds_write2_b32 v8, v28, v29 offset0:32 offset1:98
	s_waitcnt vmcnt(44)
	ds_write2_b32 v8, v30, v31 offset0:164 offset1:230
	v_add_u32_e32 v8, 0x1400, v95
	s_waitcnt vmcnt(42)
	ds_write2_b32 v8, v32, v33 offset0:40 offset1:106
	s_waitcnt vmcnt(40)
	ds_write2_b32 v8, v34, v35 offset0:172 offset1:238
	v_add_u32_e32 v8, 0x1800, v95
	s_waitcnt vmcnt(38)
	ds_write2_b32 v8, v40, v41 offset0:48 offset1:114
	s_waitcnt vmcnt(36)
	ds_write2_b32 v8, v42, v43 offset0:180 offset1:246
	v_add_u32_e32 v8, 0x1c00, v95
	s_waitcnt vmcnt(34)
	ds_write2_b32 v8, v44, v45 offset0:56 offset1:122
	s_waitcnt vmcnt(32)
	s_branch .Ltw_join_6

; #define LAS __attribute__((address_space(3)))
; template <int MODE>
; __device__ __forceinline__ void transpose_weight(const float* W, int K, int N, bf16_t* WT, LAS float* scr, int gw, int NGW, int lane, const float* gk = nullptr) {
;     const int nblk = N / 32, nitems = (K / 64) * nblk;
;     const int c = lane & 7;
;     float cur[32], nxt[32];
;     f32x4 gc0 = {1.f, 1.f, 1.f, 1.f}, gc1 = gc0, gn0 = gc0, gn1 = gc0;
;     int it = gw;
;     if (it < nitems) TW_LOAD(it, cur, gc0, gc1);
; __global__ void __launch_bounds__(NTHREADS, 2) fwd_megakernel(Args a) {
;     ...
;             transpose_weight<1>(ap->in[20], DM, 3 * DM, (bf16_t*)(ws + WS_WCIN), scr, gw, NGW, lane, ap->in[19]);
.LBB0_1207:
	s_or_b64 exec, exec, s[50:51]
	v_mov_b32_e32 v25, v220
	s_waitcnt lgkmcnt(0)
	s_barrier
	s_mov_b64 s[18:19], s[0:1]
	v_readfirstlane_b32 s10, v25
	s_ashr_i32 s12, s10, 6
	s_load_dwordx2 s[10:11], s[18:19], 0xf0
	s_add_i32 s26, s12, s71
	s_lshl_b32 s12, s12, 14
	v_and_b32_e32 v24, 63, v25
	s_add_i32 s27, s12, 0
	v_and_b32_e32 v17, 7, v25
	s_cmpk_gt_i32 s26, 0x17ff
	v_lshrrev_b32_e32 v31, 5, v24
	v_and_b32_e32 v16, 31, v25
	s_cbranch_scc1 .LBB0_1224
	s_mul_hi_i32 s20, s26, 0x2aaaaaab
	s_lshr_b32 s21, s20, 31
	s_ashr_i32 s20, s20, 5
	s_add_i32 s20, s20, s21
	s_load_dwordx4 s[12:15], s[18:19], 0x98
	s_mul_i32 s21, s20, 0xc0
	s_sub_i32 s21, s26, s21
	s_lshl_b32 s22, s20, 6
	s_lshl_b32 s20, s21, 5
	s_ashr_i32 s21, s20, 31
	s_lshl_b64 s[20:21], s[20:21], 2
	s_waitcnt lgkmcnt(0)
	s_add_u32 s20, s14, s20
	v_mov_b32_e32 v9, 0
	s_addc_u32 s21, s15, s21
	v_lshlrev_b32_e32 v8, 2, v16
	v_or_b32_e32 v22, s22, v31
	v_lshl_add_u64 v[0:1], s[20:21], 0, v[8:9]
	s_movk_i32 s23, 0x6000
	v_mad_i64_i32 v[2:3], s[20:21], v22, s23, v[0:1]
	v_or_b32_e32 v4, 2, v22
	v_or_b32_e32 v6, 4, v22
	v_or_b32_e32 v10, 6, v22
	v_or_b32_e32 v12, 8, v22
	v_or_b32_e32 v14, 10, v22
	v_or_b32_e32 v18, 12, v22
	v_or_b32_e32 v20, 14, v22
	v_mad_i64_i32 v[4:5], s[20:21], v4, s23, v[0:1]
	v_mad_i64_i32 v[6:7], s[20:21], v6, s23, v[0:1]
	v_mad_i64_i32 v[10:11], s[20:21], v10, s23, v[0:1]
	v_mad_i64_i32 v[12:13], s[20:21], v12, s23, v[0:1]
	v_mad_i64_i32 v[14:15], s[20:21], v14, s23, v[0:1]
	v_mad_i64_i32 v[18:19], s[20:21], v18, s23, v[0:1]
	v_mad_i64_i32 v[20:21], s[20:21], v20, s23, v[0:1]
	global_load_dword v33, v[2:3], off nt
	global_load_dword v34, v[4:5], off nt
	global_load_dword v35, v[6:7], off nt
	global_load_dword v36, v[10:11], off nt
	global_load_dword v37, v[12:13], off nt
	global_load_dword v38, v[14:15], off nt
	global_load_dword v39, v[18:19], off nt
	global_load_dword v40, v[20:21], off nt
	v_or_b32_e32 v2, 16, v22
	v_mad_i64_i32 v[2:3], s[20:21], v2, s23, v[0:1]
	v_or_b32_e32 v4, 18, v22
	v_or_b32_e32 v6, 20, v22
	v_or_b32_e32 v10, 22, v22
	v_or_b32_e32 v12, 24, v22
	v_or_b32_e32 v14, 26, v22
	v_or_b32_e32 v18, 28, v22
	v_or_b32_e32 v20, 30, v22
	v_mad_i64_i32 v[4:5], s[20:21], v4, s23, v[0:1]
	v_mad_i64_i32 v[6:7], s[20:21], v6, s23, v[0:1]
	v_mad_i64_i32 v[10:11], s[20:21], v10, s23, v[0:1]
	v_mad_i64_i32 v[12:13], s[20:21], v12, s23, v[0:1]
	v_mad_i64_i32 v[14:15], s[20:21], v14, s23, v[0:1]
	v_mad_i64_i32 v[18:19], s[20:21], v18, s23, v[0:1]
	v_mad_i64_i32 v[20:21], s[20:21], v20, s23, v[0:1]
	global_load_dword v41, v[2:3], off nt
	global_load_dword v42, v[4:5], off nt
	global_load_dword v43, v[6:7], off nt
	global_load_dword v44, v[10:11], off nt
	global_load_dword v45, v[12:13], off nt
	global_load_dword v46, v[14:15], off nt
	global_load_dword v47, v[18:19], off nt
	global_load_dword v56, v[20:21], off nt
	v_or_b32_e32 v2, 32, v22
	v_mad_i64_i32 v[2:3], s[20:21], v2, s23, v[0:1]
	v_or_b32_e32 v4, 34, v22
	v_or_b32_e32 v6, 36, v22
	v_or_b32_e32 v10, 38, v22
	v_or_b32_e32 v12, 40, v22
	v_or_b32_e32 v14, 42, v22
	v_or_b32_e32 v18, 44, v22
	v_or_b32_e32 v20, 46, v22
	v_mad_i64_i32 v[4:5], s[20:21], v4, s23, v[0:1]
	v_mad_i64_i32 v[6:7], s[20:21], v6, s23, v[0:1]
	v_mad_i64_i32 v[10:11], s[20:21], v10, s23, v[0:1]
	v_mad_i64_i32 v[12:13], s[20:21], v12, s23, v[0:1]
	v_mad_i64_i32 v[14:15], s[20:21], v14, s23, v[0:1]
	v_mad_i64_i32 v[18:19], s[20:21], v18, s23, v[0:1]
	v_mad_i64_i32 v[20:21], s[20:21], v20, s23, v[0:1]
	global_load_dword v65, v[2:3], off nt
	global_load_dword v66, v[4:5], off nt
	global_load_dword v67, v[6:7], off nt
	global_load_dword v68, v[10:11], off nt
	global_load_dword v69, v[12:13], off nt
	global_load_dword v70, v[14:15], off nt
	global_load_dword v71, v[18:19], off nt
	global_load_dword v72, v[20:21], off nt
	v_or_b32_e32 v2, 48, v22
	v_mad_i64_i32 v[2:3], s[20:21], v2, s23, v[0:1]
	v_or_b32_e32 v4, 50, v22
	v_or_b32_e32 v6, 52, v22
	v_or_b32_e32 v10, 54, v22
	v_or_b32_e32 v12, 56, v22
	v_or_b32_e32 v14, 58, v22
	v_or_b32_e32 v18, 60, v22
	v_or_b32_e32 v20, 62, v22
	v_mad_i64_i32 v[4:5], s[20:21], v4, s23, v[0:1]
	v_mad_i64_i32 v[6:7], s[20:21], v6, s23, v[0:1]
	v_mad_i64_i32 v[10:11], s[20:21], v10, s23, v[0:1]
	v_mad_i64_i32 v[12:13], s[20:21], v12, s23, v[0:1]
	v_mad_i64_i32 v[14:15], s[20:21], v14, s23, v[0:1]
	v_mad_i64_i32 v[18:19], s[20:21], v18, s23, v[0:1]
	v_mad_i64_i32 v[0:1], s[20:21], v20, s23, v[0:1]
	global_load_dword v81, v[2:3], off nt
	global_load_dword v82, v[4:5], off nt
	global_load_dword v83, v[6:7], off nt
	global_load_dword v84, v[10:11], off nt
	global_load_dword v85, v[12:13], off nt
	global_load_dword v86, v[14:15], off nt
	global_load_dword v87, v[18:19], off nt
	global_load_dword v88, v[0:1], off nt
	s_cmp_lg_u64 s[12:13], 0
	s_cselect_b64 s[20:21], -1, 0
	s_mov_b64 s[24:25], 0
	s_and_b64 vcc, exec, s[20:21]
	s_cbranch_vccz .LBB0_1254
	s_ashr_i32 s23, s22, 31
	s_lshl_b64 s[22:23], s[22:23], 2
	s_add_u32 s22, s12, s22
	s_addc_u32 s23, s13, s23
	v_lshlrev_b32_e32 v10, 5, v17
	global_load_dwordx4 v[0:3], v10, s[22:23] offset:16
	global_load_dwordx4 v[4:7], v10, s[22:23]
	v_lshlrev_b32_e32 v10, 3, v17
	v_mov_b32_e32 v11, v9
	s_andn2_b64 vcc, exec, s[24:25]
	s_cbranch_vccnz .LBB0_1211

; template <int MODE>
; __device__ __forceinline__ void transpose_weight(const float* W, int K, int N, bf16_t* WT, LAS float* scr, int gw, int NGW, int lane, const float* gk = nullptr) {
;     ...
;     while (it < nitems) {
;         const int itn = it + NGW;
;         if (itn < nitems) TW_LOAD(itn, nxt, gn0, gn1);
.LBB0_1213:
	s_add_i32 s29, s30, s69
	s_cmpk_gt_i32 s29, 0x17ff
	s_cselect_b64 s[12:13], -1, 0
	s_and_b64 vcc, exec, s[12:13]
	s_cbranch_vccnz .LBB0_1216
	s_mul_hi_i32 s14, s29, 0x2aaaaaab
	s_lshr_b32 s15, s14, 31
	s_ashr_i32 s14, s14, 5
	s_add_i32 s15, s14, s15
	s_lshl_b32 s14, s15, 6
	s_mulk_i32 s15, 0xe800
	s_add_i32 s31, s23, s22
	s_add_i32 s34, s31, s15
	v_or_b32_e32 v89, s14, v31
	s_ashr_i32 s35, s34, 31
	v_lshl_add_u64 v[90:91], s[34:35], 2, v[18:19]
	v_or_b32_e32 v48, 2, v89
	v_mad_i64_i32 v[60:61], s[34:35], v48, s28, v[90:91]
	v_or_b32_e32 v48, 4, v89
	v_mad_i64_i32 v[62:63], s[34:35], v48, s28, v[90:91]
	v_or_b32_e32 v48, 6, v89
	v_mad_i64_i32 v[74:75], s[34:35], v48, s28, v[90:91]
	v_or_b32_e32 v48, 8, v89
	v_mad_i64_i32 v[76:77], s[34:35], v48, s28, v[90:91]
	v_or_b32_e32 v48, 10, v89
	v_mad_i64_i32 v[78:79], s[34:35], v48, s28, v[90:91]
	v_or_b32_e32 v48, 12, v89
	v_mad_i64_i32 v[58:59], s[34:35], v89, s28, v[90:91]
	v_mad_i64_i32 v[92:93], s[34:35], v48, s28, v[90:91]
	v_or_b32_e32 v48, 14, v89
	v_or_b32_e32 v57, 16, v89
	v_mad_i64_i32 v[94:95], s[34:35], v48, s28, v[90:91]
	global_load_dword v55, v[58:59], off nt
	global_load_dword v54, v[60:61], off nt
	global_load_dword v53, v[62:63], off nt
	global_load_dword v52, v[74:75], off nt
	global_load_dword v51, v[76:77], off nt
	global_load_dword v50, v[78:79], off nt
	global_load_dword v49, v[92:93], off nt
	global_load_dword v48, v[94:95], off nt
	v_mad_i64_i32 v[74:75], s[34:35], v57, s28, v[90:91]
	v_or_b32_e32 v57, 18, v89
	v_mad_i64_i32 v[76:77], s[34:35], v57, s28, v[90:91]
	v_or_b32_e32 v57, 20, v89
	v_mad_i64_i32 v[78:79], s[34:35], v57, s28, v[90:91]
	v_or_b32_e32 v57, 22, v89
	v_mad_i64_i32 v[92:93], s[34:35], v57, s28, v[90:91]
	v_or_b32_e32 v57, 24, v89
	v_mad_i64_i32 v[94:95], s[34:35], v57, s28, v[90:91]
	v_or_b32_e32 v57, 26, v89
	v_mad_i64_i32 v[96:97], s[34:35], v57, s28, v[90:91]
	v_or_b32_e32 v57, 28, v89
	v_mad_i64_i32 v[98:99], s[34:35], v57, s28, v[90:91]
	v_or_b32_e32 v57, 30, v89
	v_or_b32_e32 v73, 32, v89
	v_mad_i64_i32 v[100:101], s[34:35], v57, s28, v[90:91]
	global_load_dword v64, v[74:75], off nt
	global_load_dword v63, v[76:77], off nt
	global_load_dword v62, v[78:79], off nt
	global_load_dword v61, v[92:93], off nt
	global_load_dword v60, v[94:95], off nt
	global_load_dword v59, v[96:97], off nt
	global_load_dword v58, v[98:99], off nt
	global_load_dword v57, v[100:101], off nt
	v_mad_i64_i32 v[92:93], s[34:35], v73, s28, v[90:91]
	v_or_b32_e32 v73, 34, v89
	v_mad_i64_i32 v[94:95], s[34:35], v73, s28, v[90:91]
	v_or_b32_e32 v73, 36, v89
	v_mad_i64_i32 v[96:97], s[34:35], v73, s28, v[90:91]
	v_or_b32_e32 v73, 38, v89
	v_mad_i64_i32 v[98:99], s[34:35], v73, s28, v[90:91]
	v_or_b32_e32 v73, 40, v89
	v_mad_i64_i32 v[100:101], s[34:35], v73, s28, v[90:91]
	v_or_b32_e32 v73, 42, v89
	v_mad_i64_i32 v[102:103], s[34:35], v73, s28, v[90:91]
	v_or_b32_e32 v73, 44, v89
	v_mad_i64_i32 v[104:105], s[34:35], v73, s28, v[90:91]
	v_or_b32_e32 v73, 46, v89
	v_mad_i64_i32 v[106:107], s[34:35], v73, s28, v[90:91]
	global_load_dword v80, v[92:93], off nt
	global_load_dword v79, v[94:95], off nt
	global_load_dword v78, v[96:97], off nt
	global_load_dword v77, v[98:99], off nt
	global_load_dword v76, v[100:101], off nt
	global_load_dword v75, v[102:103], off nt
	global_load_dword v74, v[104:105], off nt
	global_load_dword v73, v[106:107], off nt
	v_or_b32_e32 v92, 48, v89
	v_mad_i64_i32 v[98:99], s[34:35], v92, s28, v[90:91]
	v_or_b32_e32 v92, 50, v89
	v_mad_i64_i32 v[100:101], s[34:35], v92, s28, v[90:91]
	v_or_b32_e32 v92, 52, v89
	v_mad_i64_i32 v[102:103], s[34:35], v92, s28, v[90:91]
	v_or_b32_e32 v92, 54, v89
	v_mad_i64_i32 v[104:105], s[34:35], v92, s28, v[90:91]
	v_or_b32_e32 v92, 56, v89
	v_mad_i64_i32 v[106:107], s[34:35], v92, s28, v[90:91]
	v_or_b32_e32 v92, 58, v89
	v_mad_i64_i32 v[108:109], s[34:35], v92, s28, v[90:91]
	v_or_b32_e32 v92, 60, v89
	v_or_b32_e32 v89, 62, v89
	v_mad_i64_i32 v[110:111], s[34:35], v92, s28, v[90:91]
	v_mad_i64_i32 v[112:113], s[34:35], v89, s28, v[90:91]
	global_load_dword v96, v[98:99], off nt
	global_load_dword v95, v[100:101], off nt
	global_load_dword v94, v[102:103], off nt
	global_load_dword v93, v[104:105], off nt
	global_load_dword v92, v[106:107], off nt
	global_load_dword v91, v[108:109], off nt
	global_load_dword v90, v[110:111], off nt
	global_load_dword v89, v[112:113], off nt
	s_andn2_b64 vcc, exec, s[20:21]
	s_cbranch_vccnz .LBB0_1216
	s_ashr_i32 s15, s14, 31
	v_lshl_add_u64 v[98:99], s[14:15], 2, v[20:21]
	global_load_dwordx4 v[12:15], v[98:99], off offset:16
	global_load_dwordx4 v[8:11], v[98:99], off

; #define LAS __attribute__((address_space(3)))
; template <int MODE>
; __device__ __forceinline__ void transpose_weight(const float* W, int K, int N, bf16_t* WT, LAS float* scr, int gw, int NGW, int lane, const float* gk = nullptr) {
;     const int nblk = N / 32, nitems = (K / 64) * nblk;
;     const int c = lane & 7;
;     float cur[32], nxt[32];
;     f32x4 gc0 = {1.f, 1.f, 1.f, 1.f}, gc1 = gc0, gn0 = gc0, gn1 = gc0;
;     int it = gw;
;     if (it < nitems) TW_LOAD(it, cur, gc0, gc1);
; __global__ void __launch_bounds__(NTHREADS, 2) fwd_megakernel(Args a) {
;     ...
;             transpose_weight<0>(ap->in[22], DM, DM, (bf16_t*)(ws + WS_WCOUT), scr, gw, NGW, lane);
.LBB0_1224:
	s_cmpk_gt_i32 s26, 0x7ff
	v_lshrrev_b32_e32 v92, 3, v24
	v_lshlrev_b32_e32 v8, 4, v17
	s_cbranch_scc1 .LBB0_1229
	s_ashr_i32 s14, s26, 31
	s_lshr_b32 s14, s14, 26
	s_add_i32 s14, s26, s14
	s_load_dwordx2 s[12:13], s[18:19], 0xb0
	s_and_b32 s15, s14, 0xffffffc0
	s_sub_i32 s14, s26, s15
	s_lshl_b32 s14, s14, 5
	v_or_b32_e32 v0, s15, v31
	s_ashr_i32 s15, s14, 31
	s_lshl_b64 s[14:15], s[14:15], 2
	s_waitcnt lgkmcnt(0)
	s_add_u32 s14, s12, s14
	v_lshlrev_b32_e32 v1, 2, v25
	v_or_b32_e32 v10, 2, v0
	s_addc_u32 s15, s13, s15
	v_and_b32_e32 v2, 0x7c, v1
	v_mov_b32_e32 v3, 0
	v_ashrrev_i32_e32 v11, 31, v10
	v_lshl_add_u64 v[4:5], s[14:15], 0, v[2:3]
	v_lshlrev_b64 v[10:11], 13, v[10:11]
	v_lshl_add_u64 v[20:21], v[4:5], 0, v[10:11]
	v_or_b32_e32 v10, 4, v0
	v_ashrrev_i32_e32 v11, 31, v10
	v_lshlrev_b64 v[10:11], 13, v[10:11]
	v_lshl_add_u64 v[22:23], v[4:5], 0, v[10:11]
	v_or_b32_e32 v10, 6, v0
	v_ashrrev_i32_e32 v11, 31, v10
	v_lshlrev_b64 v[10:11], 13, v[10:11]
	v_lshl_add_u64 v[26:27], v[4:5], 0, v[10:11]
	v_or_b32_e32 v10, 8, v0
	v_ashrrev_i32_e32 v11, 31, v10
	v_lshlrev_b64 v[10:11], 13, v[10:11]
	v_lshl_add_u64 v[28:29], v[4:5], 0, v[10:11]
	v_or_b32_e32 v10, 10, v0
	v_ashrrev_i32_e32 v11, 31, v10
	v_lshlrev_b64 v[10:11], 13, v[10:11]
	v_lshl_add_u64 v[32:33], v[4:5], 0, v[10:11]
	v_or_b32_e32 v10, 12, v0
	v_ashrrev_i32_e32 v11, 31, v10
	v_lshlrev_b64 v[10:11], 13, v[10:11]
	v_ashrrev_i32_e32 v1, 31, v0
	v_lshl_add_u64 v[34:35], v[4:5], 0, v[10:11]
	v_or_b32_e32 v10, 14, v0
	v_lshlrev_b64 v[6:7], 13, v[0:1]
	v_ashrrev_i32_e32 v11, 31, v10
	v_lshl_add_u64 v[6:7], v[4:5], 0, v[6:7]
	v_lshlrev_b64 v[10:11], 13, v[10:11]
	v_lshl_add_u64 v[36:37], v[4:5], 0, v[10:11]
	global_load_dword v10, v[6:7], off nt
	global_load_dword v11, v[20:21], off nt
	global_load_dword v12, v[22:23], off nt
	global_load_dword v13, v[26:27], off nt
	global_load_dword v14, v[28:29], off nt
	global_load_dword v15, v[32:33], off nt
	global_load_dword v18, v[34:35], off nt
	global_load_dword v19, v[36:37], off nt
	v_or_b32_e32 v20, 18, v0
	v_ashrrev_i32_e32 v21, 31, v20
	v_lshlrev_b64 v[20:21], 13, v[20:21]
	v_lshl_add_u64 v[32:33], v[4:5], 0, v[20:21]
	v_or_b32_e32 v20, 20, v0
	v_ashrrev_i32_e32 v21, 31, v20
	v_lshlrev_b64 v[20:21], 13, v[20:21]
	v_lshl_add_u64 v[34:35], v[4:5], 0, v[20:21]
	v_or_b32_e32 v20, 22, v0
	v_ashrrev_i32_e32 v21, 31, v20
	v_lshlrev_b64 v[20:21], 13, v[20:21]
	v_lshl_add_u64 v[36:37], v[4:5], 0, v[20:21]
	v_or_b32_e32 v20, 24, v0
	v_ashrrev_i32_e32 v21, 31, v20
	v_lshlrev_b64 v[20:21], 13, v[20:21]
	v_lshl_add_u64 v[38:39], v[4:5], 0, v[20:21]
	v_or_b32_e32 v20, 26, v0
	v_ashrrev_i32_e32 v21, 31, v20
	v_lshlrev_b64 v[20:21], 13, v[20:21]
	v_lshl_add_u64 v[40:41], v[4:5], 0, v[20:21]
	v_or_b32_e32 v20, 28, v0
	v_ashrrev_i32_e32 v21, 31, v20
	v_or_b32_e32 v6, 16, v0
	v_lshlrev_b64 v[20:21], 13, v[20:21]
	v_ashrrev_i32_e32 v7, 31, v6
	v_lshl_add_u64 v[42:43], v[4:5], 0, v[20:21]
	v_or_b32_e32 v20, 30, v0
	v_lshlrev_b64 v[6:7], 13, v[6:7]
	v_ashrrev_i32_e32 v21, 31, v20
	v_lshl_add_u64 v[6:7], v[4:5], 0, v[6:7]
	v_lshlrev_b64 v[20:21], 13, v[20:21]
	v_lshl_add_u64 v[44:45], v[4:5], 0, v[20:21]
	global_load_dword v21, v[6:7], off nt
	global_load_dword v22, v[32:33], off nt
	global_load_dword v23, v[34:35], off nt
	global_load_dword v25, v[36:37], off nt
	global_load_dword v26, v[38:39], off nt
	global_load_dword v27, v[40:41], off nt
	global_load_dword v28, v[42:43], off nt
	global_load_dword v29, v[44:45], off nt
	v_or_b32_e32 v32, 34, v0
	v_ashrrev_i32_e32 v33, 31, v32
	v_lshlrev_b64 v[32:33], 13, v[32:33]
	v_lshl_add_u64 v[40:41], v[4:5], 0, v[32:33]
	v_or_b32_e32 v32, 36, v0
	v_ashrrev_i32_e32 v33, 31, v32
	v_lshlrev_b64 v[32:33], 13, v[32:33]
	v_lshl_add_u64 v[42:43], v[4:5], 0, v[32:33]
	v_or_b32_e32 v32, 38, v0
	v_ashrrev_i32_e32 v33, 31, v32
	v_lshlrev_b64 v[32:33], 13, v[32:33]
	v_lshl_add_u64 v[44:45], v[4:5], 0, v[32:33]
	v_or_b32_e32 v32, 40, v0
	v_ashrrev_i32_e32 v33, 31, v32
	v_lshlrev_b64 v[32:33], 13, v[32:33]
	v_lshl_add_u64 v[46:47], v[4:5], 0, v[32:33]
	v_or_b32_e32 v32, 42, v0
	v_ashrrev_i32_e32 v33, 31, v32
	v_lshlrev_b64 v[32:33], 13, v[32:33]
	v_lshl_add_u64 v[48:49], v[4:5], 0, v[32:33]
	v_or_b32_e32 v32, 44, v0
	v_ashrrev_i32_e32 v33, 31, v32
	v_or_b32_e32 v6, 32, v0
	v_lshlrev_b64 v[32:33], 13, v[32:33]
	v_ashrrev_i32_e32 v7, 31, v6
	v_lshl_add_u64 v[50:51], v[4:5], 0, v[32:33]
	v_or_b32_e32 v32, 46, v0
	v_lshlrev_b64 v[6:7], 13, v[6:7]
	v_ashrrev_i32_e32 v33, 31, v32
	v_lshl_add_u64 v[6:7], v[4:5], 0, v[6:7]
	v_lshlrev_b64 v[32:33], 13, v[32:33]
	v_lshl_add_u64 v[52:53], v[4:5], 0, v[32:33]
	global_load_dword v30, v[6:7], off nt
	global_load_dword v32, v[40:41], off nt
	global_load_dword v33, v[42:43], off nt
	global_load_dword v34, v[44:45], off nt
	global_load_dword v35, v[46:47], off nt
	global_load_dword v36, v[48:49], off nt
	global_load_dword v37, v[50:51], off nt
	global_load_dword v38, v[52:53], off nt
	v_or_b32_e32 v46, 56, v0
	v_ashrrev_i32_e32 v47, 31, v46
	v_lshlrev_b64 v[46:47], 13, v[46:47]
	v_lshl_add_u64 v[54:55], v[4:5], 0, v[46:47]
	v_or_b32_e32 v46, 58, v0
	v_ashrrev_i32_e32 v47, 31, v46
	v_or_b32_e32 v6, 48, v0
	v_lshlrev_b64 v[46:47], 13, v[46:47]
	v_ashrrev_i32_e32 v7, 31, v6
	v_or_b32_e32 v40, 50, v0
	v_or_b32_e32 v42, 52, v0
	v_or_b32_e32 v44, 54, v0
	v_lshl_add_u64 v[56:57], v[4:5], 0, v[46:47]
	v_or_b32_e32 v46, 60, v0
	v_or_b32_e32 v0, 62, v0
	v_lshlrev_b64 v[6:7], 13, v[6:7]
	v_ashrrev_i32_e32 v41, 31, v40
	v_ashrrev_i32_e32 v43, 31, v42
	v_ashrrev_i32_e32 v45, 31, v44
	v_ashrrev_i32_e32 v47, 31, v46
	v_ashrrev_i32_e32 v1, 31, v0
	v_lshl_add_u64 v[6:7], v[4:5], 0, v[6:7]
	v_lshlrev_b64 v[40:41], 13, v[40:41]
	v_lshlrev_b64 v[42:43], 13, v[42:43]
	v_lshlrev_b64 v[44:45], 13, v[44:45]
	v_lshlrev_b64 v[46:47], 13, v[46:47]
	v_lshlrev_b64 v[0:1], 13, v[0:1]
	v_lshl_add_u64 v[40:41], v[4:5], 0, v[40:41]
	v_lshl_add_u64 v[42:43], v[4:5], 0, v[42:43]
	v_lshl_add_u64 v[44:45], v[4:5], 0, v[44:45]
	v_lshl_add_u64 v[58:59], v[4:5], 0, v[46:47]
	v_lshl_add_u64 v[0:1], v[4:5], 0, v[0:1]
	global_load_dword v46, v[6:7], off nt
	global_load_dword v47, v[40:41], off nt
	global_load_dword v48, v[42:43], off nt
	global_load_dword v49, v[44:45], off nt
	global_load_dword v50, v[54:55], off nt
	global_load_dword v51, v[56:57], off nt
	global_load_dword v52, v[58:59], off nt
	global_load_dword v53, v[0:1], off nt
	v_lshrrev_b32_e32 v20, 3, v24
	v_mov_b32_e32 v9, v3
	v_lshl_add_u64 v[0:1], s[12:13], 0, v[2:3]
	v_add_u32_e32 v4, s27, v2
	v_mul_u32_u24_e32 v5, 0x420, v17
	v_lshl_add_u64 v[2:3], s[10:11], 0, v[8:9]
	s_mov_b64 s[12:13], 0x9b00000
	v_mul_u32_u24_e32 v6, 0x84, v31
	v_lshlrev_b32_e32 v7, 2, v20
	s_lshl_b32 s15, s69, 5
	v_lshl_add_u64 v[2:3], v[2:3], 0, s[12:13]
	v_add3_u32 v9, s27, v5, v7
	s_lshl_b32 s14, s26, 5
	v_add_u32_e32 v24, v4, v6
	s_mov_b32 s20, s15
	s_mov_b32 s22, s26
	s_branch .LBB0_1227

; template <int MODE>
; __device__ __forceinline__ void transpose_weight(const float* W, int K, int N, bf16_t* WT, LAS float* scr, int gw, int NGW, int lane, const float* gk = nullptr) {
;     ...
;     while (it < nitems) {
;         const int itn = it + NGW;
;         if (itn < nitems) TW_LOAD(itn, nxt, gn0, gn1);
.LBB0_1227:
	s_add_i32 s21, s22, s69
	s_cmpk_gt_i32 s21, 0x7ff
	s_cselect_b64 s[12:13], -1, 0
	s_and_b64 vcc, exec, s[12:13]
	s_cbranch_vccnz .LBB0_1226
	s_ashr_i32 s23, s21, 31
	s_lshr_b32 s23, s23, 26
	s_add_i32 s23, s21, s23
	s_and_b32 s25, s23, 0xffffffc0
	s_lshl_b32 s23, s23, 5
	s_add_i32 s24, s14, s20
	s_and_b32 s23, s23, 0xfffff800
	s_sub_i32 s24, s24, s23
	v_or_b32_e32 v6, s25, v31
	s_ashr_i32 s25, s24, 31
	v_ashrrev_i32_e32 v7, 31, v6
	v_lshl_add_u64 v[4:5], s[24:25], 2, v[0:1]
	v_lshlrev_b64 v[40:41], 13, v[6:7]
	v_lshl_add_u64 v[54:55], v[4:5], 0, v[40:41]
	v_or_b32_e32 v40, 2, v6
	v_ashrrev_i32_e32 v41, 31, v40
	v_lshlrev_b64 v[40:41], 13, v[40:41]
	v_lshl_add_u64 v[56:57], v[4:5], 0, v[40:41]
	v_or_b32_e32 v40, 4, v6
	v_ashrrev_i32_e32 v41, 31, v40
	v_lshlrev_b64 v[40:41], 13, v[40:41]
	v_lshl_add_u64 v[58:59], v[4:5], 0, v[40:41]
	v_or_b32_e32 v40, 6, v6
	v_ashrrev_i32_e32 v41, 31, v40
	v_lshlrev_b64 v[40:41], 13, v[40:41]
	v_lshl_add_u64 v[60:61], v[4:5], 0, v[40:41]
	v_or_b32_e32 v40, 8, v6
	v_ashrrev_i32_e32 v41, 31, v40
	v_lshlrev_b64 v[40:41], 13, v[40:41]
	v_lshl_add_u64 v[62:63], v[4:5], 0, v[40:41]
	v_or_b32_e32 v40, 10, v6
	v_ashrrev_i32_e32 v41, 31, v40
	v_lshlrev_b64 v[40:41], 13, v[40:41]
	v_lshl_add_u64 v[64:65], v[4:5], 0, v[40:41]
	v_or_b32_e32 v40, 12, v6
	v_ashrrev_i32_e32 v41, 31, v40
	v_lshlrev_b64 v[40:41], 13, v[40:41]
	v_lshl_add_u64 v[66:67], v[4:5], 0, v[40:41]
	v_or_b32_e32 v40, 14, v6
	v_ashrrev_i32_e32 v41, 31, v40
	v_lshlrev_b64 v[40:41], 13, v[40:41]
	v_lshl_add_u64 v[68:69], v[4:5], 0, v[40:41]
	global_load_dword v45, v[54:55], off nt
	global_load_dword v44, v[56:57], off nt
	global_load_dword v43, v[58:59], off nt
	global_load_dword v42, v[60:61], off nt
	global_load_dword v41, v[62:63], off nt
	global_load_dword v40, v[64:65], off nt
	global_load_dword v39, v[66:67], off nt
	global_load_dword v7, v[68:69], off nt
	v_or_b32_e32 v54, 16, v6
	v_ashrrev_i32_e32 v55, 31, v54
	v_lshlrev_b64 v[54:55], 13, v[54:55]
	v_lshl_add_u64 v[62:63], v[4:5], 0, v[54:55]
	v_or_b32_e32 v54, 18, v6
	v_ashrrev_i32_e32 v55, 31, v54
	v_lshlrev_b64 v[54:55], 13, v[54:55]
	v_lshl_add_u64 v[64:65], v[4:5], 0, v[54:55]
	v_or_b32_e32 v54, 20, v6
	v_ashrrev_i32_e32 v55, 31, v54
	v_lshlrev_b64 v[54:55], 13, v[54:55]
	v_lshl_add_u64 v[66:67], v[4:5], 0, v[54:55]
	v_or_b32_e32 v54, 22, v6
	v_ashrrev_i32_e32 v55, 31, v54
	v_lshlrev_b64 v[54:55], 13, v[54:55]
	v_lshl_add_u64 v[68:69], v[4:5], 0, v[54:55]
	v_or_b32_e32 v54, 24, v6
	v_ashrrev_i32_e32 v55, 31, v54
	v_lshlrev_b64 v[54:55], 13, v[54:55]
	v_lshl_add_u64 v[70:71], v[4:5], 0, v[54:55]
	v_or_b32_e32 v54, 26, v6
	v_ashrrev_i32_e32 v55, 31, v54
	v_lshlrev_b64 v[54:55], 13, v[54:55]
	v_lshl_add_u64 v[72:73], v[4:5], 0, v[54:55]
	v_or_b32_e32 v54, 28, v6
	v_ashrrev_i32_e32 v55, 31, v54
	v_lshlrev_b64 v[54:55], 13, v[54:55]
	v_lshl_add_u64 v[74:75], v[4:5], 0, v[54:55]
	v_or_b32_e32 v54, 30, v6
	v_ashrrev_i32_e32 v55, 31, v54
	v_lshlrev_b64 v[54:55], 13, v[54:55]
	v_lshl_add_u64 v[76:77], v[4:5], 0, v[54:55]
	global_load_dword v61, v[62:63], off nt
	global_load_dword v60, v[64:65], off nt
	global_load_dword v59, v[66:67], off nt
	global_load_dword v58, v[68:69], off nt
	global_load_dword v57, v[70:71], off nt
	global_load_dword v56, v[72:73], off nt
	global_load_dword v55, v[74:75], off nt
	global_load_dword v54, v[76:77], off nt
	v_or_b32_e32 v62, 32, v6
	v_ashrrev_i32_e32 v63, 31, v62
	v_lshlrev_b64 v[62:63], 13, v[62:63]
	v_lshl_add_u64 v[70:71], v[4:5], 0, v[62:63]
	v_or_b32_e32 v62, 34, v6
	v_ashrrev_i32_e32 v63, 31, v62
	v_lshlrev_b64 v[62:63], 13, v[62:63]
	v_lshl_add_u64 v[72:73], v[4:5], 0, v[62:63]
	v_or_b32_e32 v62, 36, v6
	v_ashrrev_i32_e32 v63, 31, v62
	v_lshlrev_b64 v[62:63], 13, v[62:63]
	v_lshl_add_u64 v[74:75], v[4:5], 0, v[62:63]
	v_or_b32_e32 v62, 38, v6
	v_ashrrev_i32_e32 v63, 31, v62
	v_lshlrev_b64 v[62:63], 13, v[62:63]
	v_lshl_add_u64 v[76:77], v[4:5], 0, v[62:63]
	v_or_b32_e32 v62, 40, v6
	v_ashrrev_i32_e32 v63, 31, v62
	v_lshlrev_b64 v[62:63], 13, v[62:63]
	v_lshl_add_u64 v[78:79], v[4:5], 0, v[62:63]
	v_or_b32_e32 v62, 42, v6
	v_ashrrev_i32_e32 v63, 31, v62
	v_lshlrev_b64 v[62:63], 13, v[62:63]
	v_lshl_add_u64 v[80:81], v[4:5], 0, v[62:63]
	v_or_b32_e32 v62, 44, v6
	v_ashrrev_i32_e32 v63, 31, v62
	v_lshlrev_b64 v[62:63], 13, v[62:63]
	v_lshl_add_u64 v[82:83], v[4:5], 0, v[62:63]
	v_or_b32_e32 v62, 46, v6
	v_ashrrev_i32_e32 v63, 31, v62
	v_lshlrev_b64 v[62:63], 13, v[62:63]
	v_lshl_add_u64 v[84:85], v[4:5], 0, v[62:63]
	global_load_dword v69, v[70:71], off nt
	global_load_dword v68, v[72:73], off nt
	global_load_dword v67, v[74:75], off nt
	global_load_dword v66, v[76:77], off nt
	global_load_dword v65, v[78:79], off nt
	global_load_dword v64, v[80:81], off nt
	global_load_dword v63, v[82:83], off nt
	global_load_dword v62, v[84:85], off nt
	v_or_b32_e32 v70, 48, v6
	v_ashrrev_i32_e32 v71, 31, v70
	v_lshlrev_b64 v[70:71], 13, v[70:71]
	v_lshl_add_u64 v[76:77], v[4:5], 0, v[70:71]
	v_or_b32_e32 v70, 50, v6
	v_ashrrev_i32_e32 v71, 31, v70
	v_lshlrev_b64 v[70:71], 13, v[70:71]
	v_lshl_add_u64 v[78:79], v[4:5], 0, v[70:71]
	v_or_b32_e32 v70, 52, v6
	v_ashrrev_i32_e32 v71, 31, v70
	v_lshlrev_b64 v[70:71], 13, v[70:71]
	v_lshl_add_u64 v[80:81], v[4:5], 0, v[70:71]
	v_or_b32_e32 v70, 54, v6
	v_ashrrev_i32_e32 v71, 31, v70
	v_lshlrev_b64 v[70:71], 13, v[70:71]
	v_lshl_add_u64 v[82:83], v[4:5], 0, v[70:71]
	v_or_b32_e32 v70, 56, v6
	v_ashrrev_i32_e32 v71, 31, v70
	v_lshlrev_b64 v[70:71], 13, v[70:71]
	v_lshl_add_u64 v[84:85], v[4:5], 0, v[70:71]
	v_or_b32_e32 v70, 58, v6
	v_ashrrev_i32_e32 v71, 31, v70
	v_lshlrev_b64 v[70:71], 13, v[70:71]
	v_lshl_add_u64 v[86:87], v[4:5], 0, v[70:71]
	v_or_b32_e32 v70, 60, v6
	v_ashrrev_i32_e32 v71, 31, v70
	v_lshlrev_b64 v[70:71], 13, v[70:71]
	v_lshl_add_u64 v[88:89], v[4:5], 0, v[70:71]
	v_or_b32_e32 v70, 62, v6
	v_ashrrev_i32_e32 v71, 31, v70
	v_lshlrev_b64 v[70:71], 13, v[70:71]
	v_lshl_add_u64 v[90:91], v[4:5], 0, v[70:71]
	global_load_dword v74, v[76:77], off nt
	global_load_dword v73, v[78:79], off nt
	global_load_dword v72, v[80:81], off nt
	global_load_dword v71, v[82:83], off nt
	global_load_dword v70, v[84:85], off nt
	global_load_dword v6, v[86:87], off nt
	global_load_dword v5, v[88:89], off nt
	global_load_dword v4, v[90:91], off nt
	s_waitcnt vmcnt(32)
	s_branch .Ltw_join_7
; #define LAS __attribute__((address_space(3)))
; template <int MODE>
; __device__ __forceinline__ void transpose_weight(const float* W, int K, int N, bf16_t* WT, LAS float* scr, int gw, int NGW, int lane, const float* gk = nullptr) {
;     const int nblk = N / 32, nitems = (K / 64) * nblk;
;     const int c = lane & 7;
;     float cur[32], nxt[32];
;     f32x4 gc0 = {1.f, 1.f, 1.f, 1.f}, gc1 = gc0, gn0 = gc0, gn1 = gc0;
;     int it = gw;
;     if (it < nitems) TW_LOAD(it, cur, gc0, gc1);
; __global__ void __launch_bounds__(NTHREADS, 2) fwd_megakernel(Args a) {
;     ...
;             transpose_weight<0>(ap->in[24] + (size_t)DM * DFF, DM, DFF, WG, scr, gw, NGW, lane, ap->in[23] + DM);
.LBB0_1229:
	s_cmpk_gt_i32 s26, 0x15ff
	s_cbranch_scc1 .LBB0_1242
	s_load_dwordx4 s[20:23], s[18:19], 0xb8
	s_mul_hi_i32 s12, s26, 0x2e8ba2e9
	v_mov_b32_e32 v11, 0
	v_lshlrev_b32_e32 v10, 2, v16
	s_waitcnt lgkmcnt(0)
	s_add_u32 s14, s20, 0x2000
	s_addc_u32 s15, s21, 0
	s_add_u32 s20, s22, 0x2c00000
	s_addc_u32 s21, s23, 0
	s_lshr_b32 s13, s12, 31
	s_ashr_i32 s12, s12, 5
	s_add_i32 s12, s12, s13
	s_mul_i32 s13, s12, 0xb0
	s_lshl_b32 s22, s12, 6
	s_sub_i32 s12, s26, s13
	s_lshl_b32 s12, s12, 5
	s_ashr_i32 s13, s12, 31
	s_lshl_b64 s[12:13], s[12:13], 2
	s_add_u32 s24, s20, s12
	v_or_b32_e32 v9, s22, v31
	s_addc_u32 s25, s21, s13
	v_lshl_add_u64 v[0:1], s[24:25], 0, v[10:11]
	s_movk_i32 s24, 0x5800
	v_or_b32_e32 v37, 14, v9
	v_mad_i64_i32 v[2:3], s[28:29], v9, s24, v[0:1]
	v_or_b32_e32 v4, 2, v9
	v_or_b32_e32 v6, 4, v9
	v_or_b32_e32 v12, 6, v9
	v_or_b32_e32 v14, 8, v9
	v_or_b32_e32 v30, 10, v9
	v_or_b32_e32 v36, 12, v9
	v_mad_i64_i32 v[34:35], s[28:29], v37, s24, v[0:1]
	v_or_b32_e32 v38, 16, v9
	v_or_b32_e32 v45, 30, v9
	v_mad_i64_i32 v[22:23], s[28:29], v4, s24, 0
	v_mad_i64_i32 v[4:5], s[28:29], v4, s24, v[0:1]
	v_mad_i64_i32 v[24:25], s[28:29], v6, s24, 0
	v_mad_i64_i32 v[6:7], s[28:29], v6, s24, v[0:1]
	v_mad_i64_i32 v[26:27], s[28:29], v12, s24, 0
	v_mad_i64_i32 v[12:13], s[28:29], v12, s24, v[0:1]
	v_mad_i64_i32 v[28:29], s[28:29], v14, s24, 0
	v_mad_i64_i32 v[14:15], s[28:29], v14, s24, v[0:1]
	v_mad_i64_i32 v[18:19], s[28:29], v30, s24, v[0:1]
	v_mad_i64_i32 v[32:33], s[28:29], v36, s24, v[0:1]
	global_load_dword v95, v[2:3], off nt
	global_load_dword v96, v[4:5], off nt
	global_load_dword v97, v[6:7], off nt
	global_load_dword v98, v[12:13], off nt
	global_load_dword v99, v[14:15], off nt
	global_load_dword v100, v[18:19], off nt
	global_load_dword v101, v[32:33], off nt
	global_load_dword v102, v[34:35], off nt
	v_mad_i64_i32 v[2:3], s[28:29], v38, s24, v[0:1]
	v_or_b32_e32 v39, 18, v9
	v_or_b32_e32 v40, 20, v9
	v_or_b32_e32 v41, 22, v9
	v_or_b32_e32 v42, 24, v9
	v_or_b32_e32 v43, 26, v9
	v_or_b32_e32 v44, 28, v9
	v_mad_i64_i32 v[34:35], s[28:29], v45, s24, v[0:1]
	v_or_b32_e32 v46, 32, v9
	v_or_b32_e32 v88, 46, v9
	v_mad_i64_i32 v[4:5], s[28:29], v39, s24, v[0:1]
	v_mad_i64_i32 v[6:7], s[28:29], v40, s24, v[0:1]
	v_mad_i64_i32 v[12:13], s[28:29], v41, s24, v[0:1]
	v_mad_i64_i32 v[14:15], s[28:29], v42, s24, v[0:1]
	v_mad_i64_i32 v[18:19], s[28:29], v43, s24, v[0:1]
	v_mad_i64_i32 v[32:33], s[28:29], v44, s24, v[0:1]
	global_load_dword v103, v[2:3], off nt
	global_load_dword v104, v[4:5], off nt
	global_load_dword v105, v[6:7], off nt
	global_load_dword v106, v[12:13], off nt
	global_load_dword v107, v[14:15], off nt
	global_load_dword v108, v[18:19], off nt
	global_load_dword v109, v[32:33], off nt
	global_load_dword v110, v[34:35], off nt
	v_mad_i64_i32 v[2:3], s[28:29], v46, s24, v[0:1]
	v_or_b32_e32 v47, 34, v9
	v_or_b32_e32 v48, 36, v9
	v_or_b32_e32 v49, 38, v9
	v_or_b32_e32 v50, 40, v9
	v_or_b32_e32 v51, 42, v9
	v_or_b32_e32 v52, 44, v9
	v_mad_i64_i32 v[34:35], s[28:29], v88, s24, v[0:1]
	v_mad_i64_i32 v[4:5], s[28:29], v47, s24, v[0:1]
	v_mad_i64_i32 v[6:7], s[28:29], v48, s24, v[0:1]
	v_mad_i64_i32 v[12:13], s[28:29], v49, s24, v[0:1]
	v_mad_i64_i32 v[14:15], s[28:29], v50, s24, v[0:1]
	v_mad_i64_i32 v[18:19], s[28:29], v51, s24, v[0:1]
	v_mad_i64_i32 v[32:33], s[28:29], v52, s24, v[0:1]
	global_load_dword v127, v[2:3], off nt
	global_load_dword v136, v[4:5], off nt
	global_load_dword v137, v[6:7], off nt
	global_load_dword v138, v[12:13], off nt
	global_load_dword v139, v[14:15], off nt
	global_load_dword v140, v[18:19], off nt
	global_load_dword v141, v[32:33], off nt
	global_load_dword v142, v[34:35], off nt
	v_or_b32_e32 v34, 48, v9
	v_mad_i64_i32 v[20:21], s[28:29], v9, s24, 0
	v_mad_i64_i32 v[2:3], s[28:29], v34, s24, v[0:1]
	v_or_b32_e32 v35, 50, v9
	v_or_b32_e32 v89, 52, v9
	v_or_b32_e32 v90, 54, v9
	v_or_b32_e32 v91, 56, v9
	v_or_b32_e32 v93, 58, v9
	v_or_b32_e32 v94, 60, v9
	v_or_b32_e32 v9, 62, v9
	v_mad_i64_i32 v[4:5], s[28:29], v35, s24, v[0:1]
	v_mad_i64_i32 v[6:7], s[28:29], v89, s24, v[0:1]
	v_mad_i64_i32 v[12:13], s[28:29], v90, s24, v[0:1]
	v_mad_i64_i32 v[14:15], s[28:29], v91, s24, v[0:1]
	v_mad_i64_i32 v[18:19], s[28:29], v93, s24, v[0:1]
	v_mad_i64_i32 v[32:33], s[28:29], v94, s24, v[0:1]
	v_mad_i64_i32 v[0:1], s[28:29], v9, s24, v[0:1]
	global_load_dword v151, v[2:3], off nt
	global_load_dword v152, v[4:5], off nt
	global_load_dword v153, v[6:7], off nt
	global_load_dword v154, v[12:13], off nt
	global_load_dword v155, v[14:15], off nt
	global_load_dword v156, v[18:19], off nt
	global_load_dword v157, v[32:33], off nt
	global_load_dword v158, v[0:1], off nt
	s_ashr_i32 s23, s22, 31
	s_lshl_b64 s[22:23], s[22:23], 2
	s_add_u32 s22, s14, s22
	s_addc_u32 s23, s15, s23
	v_lshlrev_b32_e32 v12, 5, v17
	global_load_dwordx4 v[0:3], v12, s[22:23] offset:16
	global_load_dwordx4 v[4:7], v12, s[22:23]
	v_mad_i64_i32 v[64:65], s[28:29], v46, s24, 0
	v_mad_i64_i32 v[62:63], s[28:29], v47, s24, 0
	v_mad_i64_i32 v[60:61], s[28:29], v48, s24, 0
	v_mad_i64_i32 v[58:59], s[28:29], v49, s24, 0
	v_mad_i64_i32 v[48:49], s[28:29], v34, s24, 0
	v_mad_i64_i32 v[46:47], s[28:29], v35, s24, 0
	v_mad_i64_i32 v[34:35], s[28:29], v9, s24, 0
	v_mov_b32_e32 v13, v11
	v_mov_b32_e32 v9, v11
	v_lshl_add_u64 v[18:19], s[14:15], 0, v[12:13]
	v_lshl_add_u64 v[8:9], s[10:11], 0, v[8:9]
	s_mov_b64 s[14:15], 0x100000
	v_mad_i64_i32 v[76:77], s[28:29], v40, s24, 0
	v_mad_i64_i32 v[74:75], s[28:29], v41, s24, 0
	v_mad_i64_i32 v[72:73], s[28:29], v42, s24, 0
	v_mad_i64_i32 v[70:71], s[28:29], v43, s24, 0
	v_mad_i64_i32 v[42:43], s[28:29], v90, s24, 0
	v_mad_i64_i32 v[40:41], s[28:29], v91, s24, 0
	v_lshl_add_u64 v[90:91], v[8:9], 0, s[14:15]
	v_mul_u32_u24_e32 v8, 0x84, v31
	v_mad_i64_i32 v[80:81], s[28:29], v38, s24, 0
	v_mad_i64_i32 v[78:79], s[28:29], v39, s24, 0
	v_mad_i64_i32 v[38:39], s[28:29], v93, s24, 0
	v_lshl_add_u64 v[32:33], s[22:23], 0, v[12:13]
	v_mul_u32_u24_e32 v12, 0x420, v17
	v_add3_u32 v93, s27, v10, v8
	v_lshlrev_b32_e32 v8, 2, v92
	v_mad_i64_i32 v[84:85], s[28:29], v36, s24, 0
	v_mad_i64_i32 v[82:83], s[28:29], v37, s24, 0
	v_mad_i64_i32 v[36:37], s[28:29], v94, s24, 0
	v_add3_u32 v94, s27, v12, v8
	v_mov_b32_e32 v8, 1.0
	v_mad_i64_i32 v[68:69], s[28:29], v44, s24, 0
	v_mad_i64_i32 v[66:67], s[28:29], v45, s24, 0
	v_mad_i64_i32 v[56:57], s[28:29], v50, s24, 0
	v_mad_i64_i32 v[54:55], s[28:29], v51, s24, 0
	v_mad_i64_i32 v[50:51], s[28:29], v88, s24, 0
	v_mad_i64_i32 v[44:45], s[28:29], v89, s24, 0
	v_lshl_add_u64 v[88:89], s[20:21], 0, v[10:11]
	v_mov_b32_e32 v10, v8
	v_mov_b32_e32 v11, v8
	v_mad_i64_i32 v[86:87], s[28:29], v30, s24, 0
	v_mad_i64_i32 v[52:53], s[28:29], v52, s24, 0
	s_lshl_b32 s22, s69, 5
	v_mov_b32_e32 v9, v8
	v_mov_b64_e32 v[14:15], v[10:11]
	v_lshlrev_b32_e32 v30, 3, v17
	s_lshl_b32 s23, s26, 5
	s_mov_b32 s25, s22
	v_mov_b32_e32 v17, v92
	v_mov_b64_e32 v[12:13], v[8:9]
	s_mov_b32 s28, s26
	s_branch .LBB0_1232

; template <int MODE>
; __device__ __forceinline__ void transpose_weight(const float* W, int K, int N, bf16_t* WT, LAS float* scr, int gw, int NGW, int lane, const float* gk = nullptr) {
;     ...
;     while (it < nitems) {
;         const int itn = it + NGW;
;         if (itn < nitems) TW_LOAD(itn, nxt, gn0, gn1);
.LBB0_1232:
	s_add_i32 s27, s28, s69
	s_cmpk_gt_i32 s27, 0x15ff
	s_cselect_b64 s[14:15], -1, 0
	s_and_b64 vcc, exec, s[14:15]
	s_cbranch_vccnz .LBB0_1231
	s_mul_hi_i32 s20, s27, 0x2e8ba2e9
	s_lshr_b32 s21, s20, 31
	s_ashr_i32 s20, s20, 5
	s_add_i32 s21, s20, s21
	s_lshl_b32 s20, s21, 6
	s_mulk_i32 s21, 0xea00
	s_add_i32 s29, s23, s25
	s_add_i32 s30, s29, s21
	v_or_b32_e32 v143, s20, v31
	s_ashr_i32 s31, s30, 31
	v_lshl_add_u64 v[8:9], s[30:31], 2, v[88:89]
	v_or_b32_e32 v111, 6, v143
	v_mad_i64_i32 v[112:113], s[30:31], v111, s24, v[8:9]
	v_or_b32_e32 v111, 8, v143
	v_mad_i64_i32 v[120:121], s[30:31], v111, s24, v[8:9]
	v_or_b32_e32 v111, 10, v143
	v_mad_i64_i32 v[122:123], s[30:31], v111, s24, v[8:9]
	v_or_b32_e32 v111, 12, v143
	v_mad_i64_i32 v[10:11], s[30:31], v143, s24, v[8:9]
	v_or_b32_e32 v12, 2, v143
	v_or_b32_e32 v14, 4, v143
	v_mad_i64_i32 v[124:125], s[30:31], v111, s24, v[8:9]
	v_or_b32_e32 v111, 14, v143
	v_or_b32_e32 v119, 22, v143
	v_mad_i64_i32 v[12:13], s[30:31], v12, s24, v[8:9]
	v_mad_i64_i32 v[14:15], s[30:31], v14, s24, v[8:9]
	v_mad_i64_i32 v[128:129], s[30:31], v111, s24, v[8:9]
	global_load_dword v118, v[10:11], off nt
	global_load_dword v117, v[12:13], off nt
	global_load_dword v116, v[14:15], off nt
	global_load_dword v115, v[112:113], off nt
	global_load_dword v114, v[120:121], off nt
	s_nop 0
	global_load_dword v113, v[122:123], off nt
	global_load_dword v112, v[124:125], off nt
	global_load_dword v111, v[128:129], off nt
	v_mad_i64_i32 v[120:121], s[30:31], v119, s24, v[8:9]
	v_or_b32_e32 v119, 24, v143
	v_mad_i64_i32 v[128:129], s[30:31], v119, s24, v[8:9]
	v_or_b32_e32 v119, 26, v143
	v_or_b32_e32 v10, 16, v143
	v_mad_i64_i32 v[130:131], s[30:31], v119, s24, v[8:9]
	v_or_b32_e32 v119, 28, v143
	v_mad_i64_i32 v[10:11], s[30:31], v10, s24, v[8:9]
	v_or_b32_e32 v12, 18, v143
	v_or_b32_e32 v14, 20, v143
	v_mad_i64_i32 v[132:133], s[30:31], v119, s24, v[8:9]
	v_or_b32_e32 v119, 30, v143
	v_mad_i64_i32 v[12:13], s[30:31], v12, s24, v[8:9]
	v_mad_i64_i32 v[14:15], s[30:31], v14, s24, v[8:9]
	v_mad_i64_i32 v[134:135], s[30:31], v119, s24, v[8:9]
	global_load_dword v126, v[10:11], off nt
	global_load_dword v125, v[12:13], off nt
	global_load_dword v124, v[14:15], off nt
	global_load_dword v123, v[120:121], off nt
	global_load_dword v122, v[128:129], off nt
	s_nop 0
	global_load_dword v121, v[130:131], off nt
	global_load_dword v120, v[132:133], off nt
	global_load_dword v119, v[134:135], off nt
	v_or_b32_e32 v132, 42, v143
	v_or_b32_e32 v10, 32, v143
	v_or_b32_e32 v128, 38, v143
	v_or_b32_e32 v130, 40, v143
	v_mad_i64_i32 v[144:145], s[30:31], v132, s24, v[8:9]
	v_or_b32_e32 v132, 44, v143
	v_mad_i64_i32 v[10:11], s[30:31], v10, s24, v[8:9]
	v_or_b32_e32 v12, 34, v143
	v_or_b32_e32 v14, 36, v143
	v_mad_i64_i32 v[128:129], s[30:31], v128, s24, v[8:9]
	v_mad_i64_i32 v[130:131], s[30:31], v130, s24, v[8:9]
	v_mad_i64_i32 v[146:147], s[30:31], v132, s24, v[8:9]
	v_or_b32_e32 v132, 46, v143
	v_mad_i64_i32 v[12:13], s[30:31], v12, s24, v[8:9]
	v_mad_i64_i32 v[14:15], s[30:31], v14, s24, v[8:9]
	v_mad_i64_i32 v[148:149], s[30:31], v132, s24, v[8:9]
	global_load_dword v135, v[10:11], off nt
	global_load_dword v134, v[12:13], off nt
	global_load_dword v133, v[14:15], off nt
	global_load_dword v132, v[128:129], off nt
	s_nop 0
	global_load_dword v131, v[130:131], off nt
	s_nop 0
	global_load_dword v130, v[144:145], off nt
	global_load_dword v129, v[146:147], off nt
	global_load_dword v128, v[148:149], off nt
	v_or_b32_e32 v146, 56, v143
	v_or_b32_e32 v10, 48, v143
	v_or_b32_e32 v144, 54, v143
	v_mad_i64_i32 v[160:161], s[30:31], v146, s24, v[8:9]
	v_or_b32_e32 v146, 58, v143
	v_mad_i64_i32 v[10:11], s[30:31], v10, s24, v[8:9]
	v_or_b32_e32 v12, 50, v143
	v_or_b32_e32 v14, 52, v143
	v_mad_i64_i32 v[144:145], s[30:31], v144, s24, v[8:9]
	v_mad_i64_i32 v[162:163], s[30:31], v146, s24, v[8:9]
	v_or_b32_e32 v146, 60, v143
	v_or_b32_e32 v143, 62, v143
	v_mad_i64_i32 v[12:13], s[30:31], v12, s24, v[8:9]
	v_mad_i64_i32 v[14:15], s[30:31], v14, s24, v[8:9]
	v_mad_i64_i32 v[164:165], s[30:31], v146, s24, v[8:9]
	v_mad_i64_i32 v[8:9], s[30:31], v143, s24, v[8:9]
	global_load_dword v150, v[10:11], off nt
	global_load_dword v149, v[12:13], off nt
	global_load_dword v148, v[14:15], off nt
	global_load_dword v147, v[144:145], off nt
	global_load_dword v146, v[160:161], off nt
	s_nop 0
	global_load_dword v145, v[162:163], off nt
	global_load_dword v144, v[164:165], off nt
	global_load_dword v143, v[8:9], off nt
	s_ashr_i32 s21, s20, 31
	v_lshl_add_u64 v[8:9], s[20:21], 2, v[18:19]
	global_load_dwordx4 v[12:15], v[8:9], off offset:16
	s_nop 0
	global_load_dwordx4 v[8:11], v[8:9], off
	s_waitcnt vmcnt(34)
	s_branch .Ltw_join_8
; #define LAS __attribute__((address_space(3)))
; template <int MODE>
; __device__ __forceinline__ void transpose_weight(const float* W, int K, int N, bf16_t* WT, LAS float* scr, int gw, int NGW, int lane, const float* gk = nullptr) {
;     const int nblk = N / 32, nitems = (K / 64) * nblk;
;     const int c = lane & 7;
;     float cur[32], nxt[32];
;     f32x4 gc0 = {1.f, 1.f, 1.f, 1.f}, gc1 = gc0, gn0 = gc0, gn1 = gc0;
;     int it = gw;
;     if (it < nitems) TW_LOAD(it, cur, gc0, gc1);
; __global__ void __launch_bounds__(NTHREADS, 2) fwd_megakernel(Args a) {
;     ...
;             transpose_weight<0>(ap->in[25] + (size_t)DM * DFF, DM, DFF, WU, scr, gw, NGW, lane, ap->in[23] + DM);
.LBB0_1234:
	s_load_dwordx2 s[14:15], s[18:19], 0xc8
	v_lshlrev_b32_e32 v16, 2, v16
	v_mov_b32_e32 v17, 0
	s_movk_i32 s20, 0x5800
	s_mov_b32 s21, s22
	s_waitcnt lgkmcnt(0)
	s_add_u32 s14, s14, 0x2c00000
	s_addc_u32 s15, s15, 0
	s_add_u32 s12, s14, s12
	s_addc_u32 s13, s15, s13
	v_lshl_add_u64 v[0:1], s[12:13], 0, v[16:17]
	v_lshl_add_u64 v[2:3], v[0:1], 0, v[20:21]
	v_lshl_add_u64 v[8:9], v[0:1], 0, v[26:27]
	v_lshl_add_u64 v[4:5], v[0:1], 0, v[22:23]
	v_lshl_add_u64 v[6:7], v[0:1], 0, v[24:25]
	v_lshl_add_u64 v[10:11], v[0:1], 0, v[28:29]
	v_lshl_add_u64 v[12:13], v[0:1], 0, v[86:87]
	v_lshl_add_u64 v[14:15], v[0:1], 0, v[84:85]
	v_lshl_add_u64 v[20:21], v[0:1], 0, v[82:83]
	global_load_dword v82, v[2:3], off nt
	global_load_dword v83, v[4:5], off nt
	global_load_dword v84, v[6:7], off nt
	global_load_dword v85, v[8:9], off nt
	global_load_dword v86, v[10:11], off nt
	global_load_dword v87, v[12:13], off nt
	global_load_dword v88, v[14:15], off nt
	global_load_dword v89, v[20:21], off nt
	v_lshl_add_u64 v[2:3], v[0:1], 0, v[80:81]
	v_lshl_add_u64 v[8:9], v[0:1], 0, v[74:75]
	v_lshl_add_u64 v[4:5], v[0:1], 0, v[78:79]
	v_lshl_add_u64 v[6:7], v[0:1], 0, v[76:77]
	v_lshl_add_u64 v[10:11], v[0:1], 0, v[72:73]
	v_lshl_add_u64 v[12:13], v[0:1], 0, v[70:71]
	v_lshl_add_u64 v[14:15], v[0:1], 0, v[68:69]
	v_lshl_add_u64 v[20:21], v[0:1], 0, v[66:67]
	global_load_dword v66, v[2:3], off nt
	global_load_dword v67, v[4:5], off nt
	global_load_dword v68, v[6:7], off nt
	global_load_dword v69, v[8:9], off nt
	global_load_dword v70, v[10:11], off nt
	global_load_dword v71, v[12:13], off nt
	global_load_dword v72, v[14:15], off nt
	global_load_dword v73, v[20:21], off nt
	v_lshl_add_u64 v[2:3], v[0:1], 0, v[64:65]
	v_lshl_add_u64 v[8:9], v[0:1], 0, v[58:59]
	v_lshl_add_u64 v[4:5], v[0:1], 0, v[62:63]
	v_lshl_add_u64 v[6:7], v[0:1], 0, v[60:61]
	v_lshl_add_u64 v[10:11], v[0:1], 0, v[56:57]
	v_lshl_add_u64 v[12:13], v[0:1], 0, v[54:55]
	v_lshl_add_u64 v[14:15], v[0:1], 0, v[52:53]
	v_lshl_add_u64 v[20:21], v[0:1], 0, v[50:51]
	global_load_dword v58, v[2:3], off nt
	global_load_dword v59, v[4:5], off nt
	global_load_dword v60, v[6:7], off nt
	global_load_dword v61, v[8:9], off nt
	global_load_dword v62, v[10:11], off nt
	global_load_dword v63, v[12:13], off nt
	global_load_dword v64, v[14:15], off nt
	global_load_dword v65, v[20:21], off nt
	v_lshl_add_u64 v[8:9], v[0:1], 0, v[48:49]
	v_lshl_add_u64 v[10:11], v[0:1], 0, v[46:47]
	v_lshl_add_u64 v[12:13], v[0:1], 0, v[44:45]
	v_lshl_add_u64 v[14:15], v[0:1], 0, v[42:43]
	v_lshl_add_u64 v[20:21], v[0:1], 0, v[40:41]
	v_lshl_add_u64 v[22:23], v[0:1], 0, v[38:39]
	v_lshl_add_u64 v[24:25], v[0:1], 0, v[36:37]
	v_lshl_add_u64 v[26:27], v[0:1], 0, v[34:35]
	global_load_dword v74, v[8:9], off nt
	global_load_dword v75, v[10:11], off nt
	global_load_dword v76, v[12:13], off nt
	global_load_dword v77, v[14:15], off nt
	global_load_dword v78, v[20:21], off nt
	global_load_dword v79, v[22:23], off nt
	global_load_dword v80, v[24:25], off nt
	global_load_dword v81, v[26:27], off nt
	global_load_dwordx4 v[0:3], v[32:33], off offset:16
	global_load_dwordx4 v[4:7], v[32:33], off
	v_lshlrev_b32_e32 v20, 1, v30
	v_mov_b32_e32 v21, v17
	v_lshl_add_u64 v[8:9], s[10:11], 0, v[20:21]
	s_mov_b64 s[12:13], 0x1700000
	v_lshl_add_u64 v[24:25], v[8:9], 0, s[12:13]
	v_mov_b32_e32 v8, 1.0
	v_mov_b32_e32 v10, v8
	v_mov_b32_e32 v11, v8
	v_mov_b32_e32 v9, v8
	v_mov_b64_e32 v[14:15], v[10:11]
	v_lshl_add_u64 v[22:23], s[14:15], 0, v[16:17]
	v_mov_b32_e32 v17, v92
	v_mov_b64_e32 v[12:13], v[8:9]
	s_mov_b32 s25, s26
	s_branch .LBB0_1236

; #define LAS __attribute__((address_space(3)))
; #define LDS_WAIT() asm volatile("s_waitcnt lgkmcnt(0)" ::: "memory")
; template <int MODE>
; __device__ __forceinline__ void transpose_weight(const float* W, int K, int N, bf16_t* WT, LAS float* scr, int gw, int NGW, int lane, const float* gk = nullptr) {
;     ...
;     while (it < nitems) {
;         const int itn = it + NGW;
;         if (itn < nitems) TW_LOAD(itn, nxt, gn0, gn1);
;         const int kb = it / nblk, nb = it % nblk, k0 = 64 * kb, n0 = 32 * nb;
;         int drow = n0;
;         if (MODE == 1) { if (n0 < 2048) drow = 4096 + n0; else if (n0 < 4096) { const int cc = n0 - 2048; drow = (cc >> 7) * 256 + (cc & 127); } else { const int cc = n0 - 4096; drow = (cc >> 7) * 256 + 128 + (cc & 127); } }
; #pragma unroll
;         for (int i = 0; i < 32; ++i) { const int kk = 2 * i + (lane >> 5); scr[kk * 33 + (lane & 31)] = cur[i]; }
;         LDS_WAIT(); asm volatile("" ::: "memory");
; #pragma unroll
;         for (int j = 0; j < 4; ++j) { const int n = (lane >> 3) + 8 * j; const LAS float* sp = scr + (8 * c) * 33 + n;
.LBB0_1236:
	s_add_i32 s24, s25, s69
	s_cmpk_gt_i32 s24, 0x15ff
	s_cselect_b64 s[12:13], -1, 0
	s_and_b64 vcc, exec, s[12:13]
	s_cbranch_vccnz .LBB0_1235
	s_mul_hi_i32 s14, s24, 0x2e8ba2e9
	s_lshr_b32 s15, s14, 31
	s_ashr_i32 s14, s14, 5
	s_add_i32 s15, s14, s15
	s_lshl_b32 s14, s15, 6
	s_mulk_i32 s15, 0xea00
	s_add_i32 s27, s23, s21
	s_add_i32 s28, s27, s15
	v_or_b32_e32 v95, s14, v31
	s_ashr_i32 s29, s28, 31
	v_lshl_add_u64 v[8:9], s[28:29], 2, v[22:23]
	v_or_b32_e32 v21, 6, v95
	v_mad_i64_i32 v[34:35], s[28:29], v21, s20, v[8:9]
	v_or_b32_e32 v21, 8, v95
	v_mad_i64_i32 v[36:37], s[28:29], v21, s20, v[8:9]
	v_or_b32_e32 v21, 10, v95
	v_mad_i64_i32 v[38:39], s[28:29], v21, s20, v[8:9]
	v_or_b32_e32 v21, 12, v95
	v_mad_i64_i32 v[10:11], s[28:29], v95, s20, v[8:9]
	v_or_b32_e32 v12, 2, v95
	v_or_b32_e32 v14, 4, v95
	v_mad_i64_i32 v[40:41], s[28:29], v21, s20, v[8:9]
	v_or_b32_e32 v21, 14, v95
	v_mad_i64_i32 v[12:13], s[28:29], v12, s20, v[8:9]
	v_mad_i64_i32 v[14:15], s[28:29], v14, s20, v[8:9]
	v_mad_i64_i32 v[42:43], s[28:29], v21, s20, v[8:9]
	global_load_dword v33, v[10:11], off nt
	global_load_dword v32, v[12:13], off nt
	global_load_dword v30, v[14:15], off nt
	global_load_dword v29, v[34:35], off nt
	global_load_dword v28, v[36:37], off nt
	global_load_dword v27, v[38:39], off nt
	global_load_dword v26, v[40:41], off nt
	global_load_dword v21, v[42:43], off nt
	v_or_b32_e32 v34, 22, v95
	v_mad_i64_i32 v[42:43], s[28:29], v34, s20, v[8:9]
	v_or_b32_e32 v34, 24, v95
	v_mad_i64_i32 v[44:45], s[28:29], v34, s20, v[8:9]
	v_or_b32_e32 v34, 26, v95
	v_or_b32_e32 v10, 16, v95
	v_mad_i64_i32 v[46:47], s[28:29], v34, s20, v[8:9]
	v_or_b32_e32 v34, 28, v95
	v_mad_i64_i32 v[10:11], s[28:29], v10, s20, v[8:9]
	v_or_b32_e32 v12, 18, v95
	v_or_b32_e32 v14, 20, v95
	v_mad_i64_i32 v[48:49], s[28:29], v34, s20, v[8:9]
	v_or_b32_e32 v34, 30, v95
	v_mad_i64_i32 v[12:13], s[28:29], v12, s20, v[8:9]
	v_mad_i64_i32 v[14:15], s[28:29], v14, s20, v[8:9]
	v_mad_i64_i32 v[50:51], s[28:29], v34, s20, v[8:9]
	global_load_dword v41, v[10:11], off nt
	global_load_dword v40, v[12:13], off nt
	global_load_dword v39, v[14:15], off nt
	global_load_dword v38, v[42:43], off nt
	global_load_dword v37, v[44:45], off nt
	global_load_dword v36, v[46:47], off nt
	global_load_dword v35, v[48:49], off nt
	global_load_dword v34, v[50:51], off nt
	v_or_b32_e32 v42, 38, v95
	v_mad_i64_i32 v[50:51], s[28:29], v42, s20, v[8:9]
	v_or_b32_e32 v42, 40, v95
	v_mad_i64_i32 v[52:53], s[28:29], v42, s20, v[8:9]
	v_or_b32_e32 v42, 42, v95
	v_or_b32_e32 v10, 32, v95
	v_mad_i64_i32 v[54:55], s[28:29], v42, s20, v[8:9]
	v_or_b32_e32 v42, 44, v95
	v_mad_i64_i32 v[10:11], s[28:29], v10, s20, v[8:9]
	v_or_b32_e32 v12, 34, v95
	v_or_b32_e32 v14, 36, v95
	v_mad_i64_i32 v[56:57], s[28:29], v42, s20, v[8:9]
	v_or_b32_e32 v42, 46, v95
	v_mad_i64_i32 v[12:13], s[28:29], v12, s20, v[8:9]
	v_mad_i64_i32 v[14:15], s[28:29], v14, s20, v[8:9]
	v_mad_i64_i32 v[90:91], s[28:29], v42, s20, v[8:9]
	global_load_dword v49, v[10:11], off nt
	global_load_dword v48, v[12:13], off nt
	global_load_dword v47, v[14:15], off nt
	global_load_dword v46, v[50:51], off nt
	global_load_dword v45, v[52:53], off nt
	global_load_dword v44, v[54:55], off nt
	global_load_dword v43, v[56:57], off nt
	global_load_dword v42, v[90:91], off nt
	v_or_b32_e32 v50, 54, v95
	v_mad_i64_i32 v[90:91], s[28:29], v50, s20, v[8:9]
	v_or_b32_e32 v50, 56, v95
	v_mad_i64_i32 v[96:97], s[28:29], v50, s20, v[8:9]
	v_or_b32_e32 v50, 58, v95
	v_or_b32_e32 v10, 48, v95
	v_mad_i64_i32 v[98:99], s[28:29], v50, s20, v[8:9]
	v_or_b32_e32 v50, 60, v95
	v_mad_i64_i32 v[10:11], s[28:29], v10, s20, v[8:9]
	v_or_b32_e32 v12, 50, v95
	v_or_b32_e32 v14, 52, v95
	v_mad_i64_i32 v[100:101], s[28:29], v50, s20, v[8:9]
	v_or_b32_e32 v50, 62, v95
	v_mad_i64_i32 v[12:13], s[28:29], v12, s20, v[8:9]
	v_mad_i64_i32 v[14:15], s[28:29], v14, s20, v[8:9]
	v_mad_i64_i32 v[8:9], s[28:29], v50, s20, v[8:9]
	global_load_dword v57, v[10:11], off nt
	global_load_dword v56, v[12:13], off nt
	global_load_dword v55, v[14:15], off nt
	global_load_dword v54, v[90:91], off nt
	global_load_dword v53, v[96:97], off nt
	global_load_dword v52, v[98:99], off nt
	global_load_dword v51, v[100:101], off nt
	global_load_dword v50, v[8:9], off nt
	s_ashr_i32 s15, s14, 31
	v_lshl_add_u64 v[90:91], s[14:15], 2, v[18:19]
	global_load_dwordx4 v[12:15], v[90:91], off offset:16
	global_load_dwordx4 v[8:11], v[90:91], off
	s_waitcnt vmcnt(63)
	ds_write2_b32 v93, v82, v83 offset1:66
	s_waitcnt vmcnt(63)
	ds_write2_b32 v93, v84, v85 offset0:132 offset1:198
	v_add_u32_e32 v82, 0x400, v93
	s_waitcnt vmcnt(62)
	ds_write2_b32 v82, v86, v87 offset0:8 offset1:74
	s_waitcnt vmcnt(60)
	ds_write2_b32 v82, v88, v89 offset0:140 offset1:206
	v_add_u32_e32 v82, 0x800, v93
	s_waitcnt vmcnt(58)
	ds_write2_b32 v82, v66, v67 offset0:16 offset1:82
	s_waitcnt vmcnt(56)
	ds_write2_b32 v82, v68, v69 offset0:148 offset1:214
	v_add_u32_e32 v66, 0xc00, v93
	s_waitcnt vmcnt(54)
	ds_write2_b32 v66, v70, v71 offset0:24 offset1:90
	s_waitcnt vmcnt(52)
	ds_write2_b32 v66, v72, v73 offset0:156 offset1:222
	v_add_u32_e32 v66, 0x1000, v93
	s_waitcnt vmcnt(50)
	ds_write2_b32 v66, v58, v59 offset0:32 offset1:98
	s_waitcnt vmcnt(48)
	ds_write2_b32 v66, v60, v61 offset0:164 offset1:230
	v_add_u32_e32 v58, 0x1400, v93
	s_waitcnt vmcnt(46)
	ds_write2_b32 v58, v62, v63 offset0:40 offset1:106
	s_waitcnt vmcnt(44)
	ds_write2_b32 v58, v64, v65 offset0:172 offset1:238
	v_add_u32_e32 v58, 0x1800, v93
	s_waitcnt vmcnt(42)
	ds_write2_b32 v58, v74, v75 offset0:48 offset1:114
	s_waitcnt vmcnt(40)
	ds_write2_b32 v58, v76, v77 offset0:180 offset1:246
	v_add_u32_e32 v58, 0x1c00, v93
	s_waitcnt vmcnt(38)
	ds_write2_b32 v58, v78, v79 offset0:56 offset1:122
	s_waitcnt vmcnt(36)
	ds_write2_b32 v58, v80, v81 offset0:188 offset1:254
	s_waitcnt lgkmcnt(0)
	ds_read2_b32 v[62:63], v94 offset1:8
	ds_read2_b32 v[64:65], v94 offset0:33 offset1:41
	ds_read2_b32 v[68:69], v94 offset0:66 offset1:74
	ds_read2_b32 v[70:71], v94 offset0:99 offset1:107
	s_mul_hi_i32 s14, s25, 0x2e8ba2e9
	ds_read2_b32 v[72:73], v94 offset0:132 offset1:140
	ds_read2_b32 v[74:75], v94 offset0:165 offset1:173
	ds_read2_b32 v[76:77], v94 offset0:198 offset1:206
	ds_read2_b32 v[78:79], v94 offset0:231 offset1:239
	s_lshr_b32 s15, s14, 31
	s_ashr_i32 s14, s14, 5
	s_add_i32 s25, s14, s15
	s_lshl_b32 s14, s25, 6
	s_waitcnt lgkmcnt(7)
	v_mov_b32_e32 v58, v62
	s_waitcnt lgkmcnt(6)
	v_mov_b32_e32 v59, v64
	s_waitcnt lgkmcnt(5)
	v_mov_b32_e32 v60, v68
	s_waitcnt lgkmcnt(4)
	v_mov_b32_e32 v61, v70
	s_ashr_i32 s15, s14, 31
	s_waitcnt vmcnt(34)
	s_branch .Ltw_join_9
; #define LAS __attribute__((address_space(3)))
; template <int MODE>
; __device__ __forceinline__ void transpose_weight(const float* W, int K, int N, bf16_t* WT, LAS float* scr, int gw, int NGW, int lane, const float* gk = nullptr) {
;     const int nblk = N / 32, nitems = (K / 64) * nblk;
;     const int c = lane & 7;
;     float cur[32], nxt[32];
;     f32x4 gc0 = {1.f, 1.f, 1.f, 1.f}, gc1 = gc0, gn0 = gc0, gn1 = gc0;
;     int it = gw;
;     if (it < nitems) TW_LOAD(it, cur, gc0, gc1);
.LBB0_1238:
	s_load_dwordx2 s[12:13], s[18:19], 0xe0
	v_mov_b32_e32 v17, 0
	v_mov_b32_e32 v21, v17
	s_waitcnt lgkmcnt(0)
	s_add_u32 s12, s12, 0x2c00000
	s_addc_u32 s13, s13, 0
	s_ashr_i32 s14, s26, 31
	s_lshr_b32 s14, s14, 26
	s_add_i32 s14, s26, s14
	s_andn2_b32 s14, s14, 63
	s_sub_i32 s15, s26, s14
	v_or_b32_e32 v0, s14, v31
	s_lshl_b32 s14, s15, 5
	s_ashr_i32 s15, s14, 31
	s_lshl_b64 s[14:15], s[14:15], 2
	s_add_u32 s14, s12, s14
	v_or_b32_e32 v8, 4, v0
	s_addc_u32 s15, s13, s15
	v_ashrrev_i32_e32 v9, 31, v8
	v_lshl_add_u64 v[2:3], s[14:15], 0, v[16:17]
	v_lshlrev_b64 v[8:9], 13, v[8:9]
	v_lshl_add_u64 v[18:19], v[2:3], 0, v[8:9]
	v_or_b32_e32 v8, 6, v0
	v_ashrrev_i32_e32 v9, 31, v8
	v_lshlrev_b64 v[8:9], 13, v[8:9]
	v_lshl_add_u64 v[22:23], v[2:3], 0, v[8:9]
	v_or_b32_e32 v8, 8, v0
	v_ashrrev_i32_e32 v9, 31, v8
	v_lshlrev_b64 v[8:9], 13, v[8:9]
	v_lshl_add_u64 v[24:25], v[2:3], 0, v[8:9]
	v_or_b32_e32 v8, 10, v0
	v_ashrrev_i32_e32 v9, 31, v8
	v_lshlrev_b64 v[8:9], 13, v[8:9]
	v_lshl_add_u64 v[26:27], v[2:3], 0, v[8:9]
	v_or_b32_e32 v8, 12, v0
	v_ashrrev_i32_e32 v9, 31, v8
	v_lshlrev_b64 v[8:9], 13, v[8:9]
	v_ashrrev_i32_e32 v1, 31, v0
	v_or_b32_e32 v6, 2, v0
	v_lshl_add_u64 v[28:29], v[2:3], 0, v[8:9]
	v_or_b32_e32 v8, 14, v0
	v_lshlrev_b64 v[4:5], 13, v[0:1]
	v_ashrrev_i32_e32 v7, 31, v6
	v_ashrrev_i32_e32 v9, 31, v8
	v_lshl_add_u64 v[4:5], v[2:3], 0, v[4:5]
	v_lshlrev_b64 v[6:7], 13, v[6:7]
	v_lshlrev_b64 v[8:9], 13, v[8:9]
	v_lshl_add_u64 v[6:7], v[2:3], 0, v[6:7]
	v_lshl_add_u64 v[32:33], v[2:3], 0, v[8:9]
	global_load_dword v8, v[4:5], off nt
	global_load_dword v9, v[6:7], off nt
	global_load_dword v10, v[18:19], off nt
	global_load_dword v11, v[22:23], off nt
	global_load_dword v12, v[24:25], off nt
	global_load_dword v13, v[26:27], off nt
	global_load_dword v14, v[28:29], off nt
	global_load_dword v15, v[32:33], off nt
	v_or_b32_e32 v18, 20, v0
	v_ashrrev_i32_e32 v19, 31, v18
	v_lshlrev_b64 v[18:19], 13, v[18:19]
	v_lshl_add_u64 v[28:29], v[2:3], 0, v[18:19]
	v_or_b32_e32 v18, 22, v0
	v_ashrrev_i32_e32 v19, 31, v18
	v_lshlrev_b64 v[18:19], 13, v[18:19]
	v_lshl_add_u64 v[32:33], v[2:3], 0, v[18:19]
	v_or_b32_e32 v18, 24, v0
	v_ashrrev_i32_e32 v19, 31, v18
	v_lshlrev_b64 v[18:19], 13, v[18:19]
	v_lshl_add_u64 v[34:35], v[2:3], 0, v[18:19]
	v_or_b32_e32 v18, 26, v0
	v_ashrrev_i32_e32 v19, 31, v18
	v_lshlrev_b64 v[18:19], 13, v[18:19]
	v_lshl_add_u64 v[36:37], v[2:3], 0, v[18:19]
	v_or_b32_e32 v18, 28, v0
	v_ashrrev_i32_e32 v19, 31, v18
	v_or_b32_e32 v4, 16, v0
	v_lshlrev_b64 v[18:19], 13, v[18:19]
	v_ashrrev_i32_e32 v5, 31, v4
	v_or_b32_e32 v6, 18, v0
	v_lshl_add_u64 v[38:39], v[2:3], 0, v[18:19]
	v_or_b32_e32 v18, 30, v0
	v_lshlrev_b64 v[4:5], 13, v[4:5]
	v_ashrrev_i32_e32 v7, 31, v6
	v_ashrrev_i32_e32 v19, 31, v18
	v_lshl_add_u64 v[4:5], v[2:3], 0, v[4:5]
	v_lshlrev_b64 v[6:7], 13, v[6:7]
	v_lshlrev_b64 v[18:19], 13, v[18:19]
	v_lshl_add_u64 v[6:7], v[2:3], 0, v[6:7]
	v_lshl_add_u64 v[40:41], v[2:3], 0, v[18:19]
	global_load_dword v18, v[4:5], off nt
	global_load_dword v19, v[6:7], off nt
	global_load_dword v22, v[28:29], off nt
	global_load_dword v23, v[32:33], off nt
	global_load_dword v24, v[34:35], off nt
	global_load_dword v25, v[36:37], off nt
	global_load_dword v26, v[38:39], off nt
	global_load_dword v27, v[40:41], off nt
	v_or_b32_e32 v28, 36, v0
	v_ashrrev_i32_e32 v29, 31, v28
	v_lshlrev_b64 v[28:29], 13, v[28:29]
	v_lshl_add_u64 v[38:39], v[2:3], 0, v[28:29]
	v_or_b32_e32 v28, 38, v0
	v_ashrrev_i32_e32 v29, 31, v28
	v_lshlrev_b64 v[28:29], 13, v[28:29]
	v_lshl_add_u64 v[40:41], v[2:3], 0, v[28:29]
	v_or_b32_e32 v28, 40, v0
	v_ashrrev_i32_e32 v29, 31, v28
	v_lshlrev_b64 v[28:29], 13, v[28:29]
	v_lshl_add_u64 v[42:43], v[2:3], 0, v[28:29]
	v_or_b32_e32 v28, 42, v0
	v_ashrrev_i32_e32 v29, 31, v28
	v_lshlrev_b64 v[28:29], 13, v[28:29]
	v_lshl_add_u64 v[44:45], v[2:3], 0, v[28:29]
	v_or_b32_e32 v28, 44, v0
	v_ashrrev_i32_e32 v29, 31, v28
	v_or_b32_e32 v4, 32, v0
	v_lshlrev_b64 v[28:29], 13, v[28:29]
	v_ashrrev_i32_e32 v5, 31, v4
	v_or_b32_e32 v6, 34, v0
	v_lshl_add_u64 v[46:47], v[2:3], 0, v[28:29]
	v_or_b32_e32 v28, 46, v0
	v_lshlrev_b64 v[4:5], 13, v[4:5]
	v_ashrrev_i32_e32 v7, 31, v6
	v_ashrrev_i32_e32 v29, 31, v28
	v_lshl_add_u64 v[4:5], v[2:3], 0, v[4:5]
	v_lshlrev_b64 v[6:7], 13, v[6:7]
	v_lshlrev_b64 v[28:29], 13, v[28:29]
	v_lshl_add_u64 v[6:7], v[2:3], 0, v[6:7]
	v_lshl_add_u64 v[48:49], v[2:3], 0, v[28:29]
	global_load_dword v28, v[4:5], off nt
	global_load_dword v29, v[6:7], off nt
	global_load_dword v30, v[38:39], off nt
	global_load_dword v32, v[40:41], off nt
	global_load_dword v33, v[42:43], off nt
	global_load_dword v34, v[44:45], off nt
	global_load_dword v35, v[46:47], off nt
	global_load_dword v36, v[48:49], off nt
	v_or_b32_e32 v40, 54, v0
	v_ashrrev_i32_e32 v41, 31, v40
	v_lshlrev_b64 v[40:41], 13, v[40:41]
	v_lshl_add_u64 v[50:51], v[2:3], 0, v[40:41]
	v_or_b32_e32 v40, 56, v0
	v_ashrrev_i32_e32 v41, 31, v40
	v_lshlrev_b64 v[40:41], 13, v[40:41]
	v_lshl_add_u64 v[52:53], v[2:3], 0, v[40:41]
	v_or_b32_e32 v40, 58, v0
	v_ashrrev_i32_e32 v41, 31, v40
	v_or_b32_e32 v4, 48, v0
	v_lshlrev_b64 v[40:41], 13, v[40:41]
	v_ashrrev_i32_e32 v5, 31, v4
	v_or_b32_e32 v6, 50, v0
	v_or_b32_e32 v38, 52, v0
	v_lshl_add_u64 v[54:55], v[2:3], 0, v[40:41]
	v_or_b32_e32 v40, 60, v0
	v_or_b32_e32 v0, 62, v0
	v_lshlrev_b64 v[4:5], 13, v[4:5]
	v_ashrrev_i32_e32 v7, 31, v6
	v_ashrrev_i32_e32 v39, 31, v38
	v_ashrrev_i32_e32 v41, 31, v40
	v_ashrrev_i32_e32 v1, 31, v0
	v_lshl_add_u64 v[4:5], v[2:3], 0, v[4:5]
	v_lshlrev_b64 v[6:7], 13, v[6:7]
	v_lshlrev_b64 v[38:39], 13, v[38:39]
	v_lshlrev_b64 v[40:41], 13, v[40:41]
	v_lshlrev_b64 v[0:1], 13, v[0:1]
	v_lshl_add_u64 v[6:7], v[2:3], 0, v[6:7]
	v_lshl_add_u64 v[38:39], v[2:3], 0, v[38:39]
	v_lshl_add_u64 v[56:57], v[2:3], 0, v[40:41]
	v_lshl_add_u64 v[0:1], v[2:3], 0, v[0:1]
	global_load_dword v41, v[4:5], off nt
	global_load_dword v42, v[6:7], off nt
	global_load_dword v43, v[38:39], off nt
	global_load_dword v44, v[50:51], off nt
	global_load_dword v45, v[52:53], off nt
	global_load_dword v46, v[54:55], off nt
	global_load_dword v47, v[56:57], off nt
	global_load_dword v48, v[0:1], off nt
	v_lshl_add_u64 v[2:3], s[10:11], 0, v[20:21]
	s_mov_b64 s[10:11], 0x2d00000
	v_lshl_add_u64 v[2:3], v[2:3], 0, s[10:11]
	s_mul_i32 s10, s26, 0x2c000
	s_movk_i32 s11, 0x1600
	v_mov_b32_e32 v4, s10
	s_add_i32 s10, s69, s26
	v_lshl_add_u64 v[0:1], s[12:13], 0, v[16:17]
	v_mad_u32_u24 v16, v92, s11, v4
	s_lshl_b32 s12, s10, 5
	s_branch .LBB0_1240

; template <int MODE>
; __device__ __forceinline__ void transpose_weight(const float* W, int K, int N, bf16_t* WT, LAS float* scr, int gw, int NGW, int lane, const float* gk = nullptr) {
;     ...
;     while (it < nitems) {
;         const int itn = it + NGW;
;         if (itn < nitems) TW_LOAD(itn, nxt, gn0, gn1);
.LBB0_1240:
	s_add_i32 s13, s26, s69
	s_cmpk_gt_i32 s13, 0x15ff
	s_cselect_b64 s[10:11], -1, 0
	s_and_b64 vcc, exec, s[10:11]
	s_cbranch_vccnz .LBB0_1239
	s_ashr_i32 s14, s13, 31
	s_lshr_b32 s14, s14, 26
	s_add_i32 s14, s13, s14
	s_and_b32 s15, s14, 0xffffffc0
	s_lshl_b32 s14, s14, 5
	s_and_b32 s14, s14, 0xfffff800
	s_sub_i32 s14, s12, s14
	v_or_b32_e32 v6, s15, v31
	s_ashr_i32 s15, s14, 31
	v_ashrrev_i32_e32 v7, 31, v6
	v_lshl_add_u64 v[4:5], s[14:15], 2, v[0:1]
	v_lshlrev_b64 v[20:21], 13, v[6:7]
	v_lshl_add_u64 v[50:51], v[4:5], 0, v[20:21]
	v_or_b32_e32 v20, 2, v6
	v_ashrrev_i32_e32 v21, 31, v20
	v_lshlrev_b64 v[20:21], 13, v[20:21]
	v_lshl_add_u64 v[52:53], v[4:5], 0, v[20:21]
	v_or_b32_e32 v20, 4, v6
	v_ashrrev_i32_e32 v21, 31, v20
	v_lshlrev_b64 v[20:21], 13, v[20:21]
	v_lshl_add_u64 v[54:55], v[4:5], 0, v[20:21]
	v_or_b32_e32 v20, 6, v6
	v_ashrrev_i32_e32 v21, 31, v20
	v_lshlrev_b64 v[20:21], 13, v[20:21]
	v_lshl_add_u64 v[56:57], v[4:5], 0, v[20:21]
	v_or_b32_e32 v20, 8, v6
	v_ashrrev_i32_e32 v21, 31, v20
	v_lshlrev_b64 v[20:21], 13, v[20:21]
	v_lshl_add_u64 v[58:59], v[4:5], 0, v[20:21]
	v_or_b32_e32 v20, 10, v6
	v_ashrrev_i32_e32 v21, 31, v20
	v_lshlrev_b64 v[20:21], 13, v[20:21]
	v_lshl_add_u64 v[60:61], v[4:5], 0, v[20:21]
	v_or_b32_e32 v20, 12, v6
	v_ashrrev_i32_e32 v21, 31, v20
	v_lshlrev_b64 v[20:21], 13, v[20:21]
	v_lshl_add_u64 v[62:63], v[4:5], 0, v[20:21]
	v_or_b32_e32 v20, 14, v6
	v_ashrrev_i32_e32 v21, 31, v20
	v_lshlrev_b64 v[20:21], 13, v[20:21]
	v_lshl_add_u64 v[64:65], v[4:5], 0, v[20:21]
	global_load_dword v40, v[50:51], off nt
	global_load_dword v39, v[52:53], off nt
	global_load_dword v38, v[54:55], off nt
	global_load_dword v37, v[56:57], off nt
	global_load_dword v21, v[58:59], off nt
	global_load_dword v20, v[60:61], off nt
	global_load_dword v17, v[62:63], off nt
	global_load_dword v7, v[64:65], off nt
	v_or_b32_e32 v50, 16, v6
	v_ashrrev_i32_e32 v51, 31, v50
	v_lshlrev_b64 v[50:51], 13, v[50:51]
	v_lshl_add_u64 v[58:59], v[4:5], 0, v[50:51]
	v_or_b32_e32 v50, 18, v6
	v_ashrrev_i32_e32 v51, 31, v50
	v_lshlrev_b64 v[50:51], 13, v[50:51]
	v_lshl_add_u64 v[60:61], v[4:5], 0, v[50:51]
	v_or_b32_e32 v50, 20, v6
	v_ashrrev_i32_e32 v51, 31, v50
	v_lshlrev_b64 v[50:51], 13, v[50:51]
	v_lshl_add_u64 v[62:63], v[4:5], 0, v[50:51]
	v_or_b32_e32 v50, 22, v6
	v_ashrrev_i32_e32 v51, 31, v50
	v_lshlrev_b64 v[50:51], 13, v[50:51]
	v_lshl_add_u64 v[64:65], v[4:5], 0, v[50:51]
	v_or_b32_e32 v50, 24, v6
	v_ashrrev_i32_e32 v51, 31, v50
	v_lshlrev_b64 v[50:51], 13, v[50:51]
	v_lshl_add_u64 v[66:67], v[4:5], 0, v[50:51]
	v_or_b32_e32 v50, 26, v6
	v_ashrrev_i32_e32 v51, 31, v50
	v_lshlrev_b64 v[50:51], 13, v[50:51]
	v_lshl_add_u64 v[68:69], v[4:5], 0, v[50:51]
	v_or_b32_e32 v50, 28, v6
	v_ashrrev_i32_e32 v51, 31, v50
	v_lshlrev_b64 v[50:51], 13, v[50:51]
	v_lshl_add_u64 v[70:71], v[4:5], 0, v[50:51]
	v_or_b32_e32 v50, 30, v6
	v_ashrrev_i32_e32 v51, 31, v50
	v_lshlrev_b64 v[50:51], 13, v[50:51]
	v_lshl_add_u64 v[72:73], v[4:5], 0, v[50:51]
	global_load_dword v56, v[58:59], off nt
	global_load_dword v55, v[60:61], off nt
	global_load_dword v54, v[62:63], off nt
	global_load_dword v53, v[64:65], off nt
	global_load_dword v52, v[66:67], off nt
	global_load_dword v51, v[68:69], off nt
	global_load_dword v50, v[70:71], off nt
	global_load_dword v49, v[72:73], off nt
	v_or_b32_e32 v58, 32, v6
	v_ashrrev_i32_e32 v59, 31, v58
	v_lshlrev_b64 v[58:59], 13, v[58:59]
	v_lshl_add_u64 v[66:67], v[4:5], 0, v[58:59]
	v_or_b32_e32 v58, 34, v6
	v_ashrrev_i32_e32 v59, 31, v58
	v_lshlrev_b64 v[58:59], 13, v[58:59]
	v_lshl_add_u64 v[68:69], v[4:5], 0, v[58:59]
	v_or_b32_e32 v58, 36, v6
	v_ashrrev_i32_e32 v59, 31, v58
	v_lshlrev_b64 v[58:59], 13, v[58:59]
	v_lshl_add_u64 v[70:71], v[4:5], 0, v[58:59]
	v_or_b32_e32 v58, 38, v6
	v_ashrrev_i32_e32 v59, 31, v58
	v_lshlrev_b64 v[58:59], 13, v[58:59]
	v_lshl_add_u64 v[72:73], v[4:5], 0, v[58:59]
	v_or_b32_e32 v58, 40, v6
	v_ashrrev_i32_e32 v59, 31, v58
	v_lshlrev_b64 v[58:59], 13, v[58:59]
	v_lshl_add_u64 v[74:75], v[4:5], 0, v[58:59]
	v_or_b32_e32 v58, 42, v6
	v_ashrrev_i32_e32 v59, 31, v58
	v_lshlrev_b64 v[58:59], 13, v[58:59]
	v_lshl_add_u64 v[76:77], v[4:5], 0, v[58:59]
	v_or_b32_e32 v58, 44, v6
	v_ashrrev_i32_e32 v59, 31, v58
	v_lshlrev_b64 v[58:59], 13, v[58:59]
	v_lshl_add_u64 v[78:79], v[4:5], 0, v[58:59]
	v_or_b32_e32 v58, 46, v6
	v_ashrrev_i32_e32 v59, 31, v58
	v_lshlrev_b64 v[58:59], 13, v[58:59]
	v_lshl_add_u64 v[80:81], v[4:5], 0, v[58:59]
	global_load_dword v64, v[66:67], off nt
	global_load_dword v63, v[68:69], off nt
	global_load_dword v62, v[70:71], off nt
	global_load_dword v61, v[72:73], off nt
	global_load_dword v60, v[74:75], off nt
	global_load_dword v59, v[76:77], off nt
	global_load_dword v58, v[78:79], off nt
	global_load_dword v57, v[80:81], off nt
	v_or_b32_e32 v66, 48, v6
	v_ashrrev_i32_e32 v67, 31, v66
	v_lshlrev_b64 v[66:67], 13, v[66:67]
	v_lshl_add_u64 v[70:71], v[4:5], 0, v[66:67]
	v_or_b32_e32 v66, 50, v6
	v_ashrrev_i32_e32 v67, 31, v66
	v_lshlrev_b64 v[66:67], 13, v[66:67]
	v_lshl_add_u64 v[72:73], v[4:5], 0, v[66:67]
	v_or_b32_e32 v66, 52, v6
	v_ashrrev_i32_e32 v67, 31, v66
	v_lshlrev_b64 v[66:67], 13, v[66:67]
	v_lshl_add_u64 v[74:75], v[4:5], 0, v[66:67]
	v_or_b32_e32 v66, 54, v6
	v_ashrrev_i32_e32 v67, 31, v66
	v_lshlrev_b64 v[66:67], 13, v[66:67]
	v_lshl_add_u64 v[76:77], v[4:5], 0, v[66:67]
	v_or_b32_e32 v66, 56, v6
	v_ashrrev_i32_e32 v67, 31, v66
	v_lshlrev_b64 v[66:67], 13, v[66:67]
	v_lshl_add_u64 v[78:79], v[4:5], 0, v[66:67]
	v_or_b32_e32 v66, 58, v6
	v_ashrrev_i32_e32 v67, 31, v66
	v_lshlrev_b64 v[66:67], 13, v[66:67]
	v_lshl_add_u64 v[80:81], v[4:5], 0, v[66:67]
	v_or_b32_e32 v66, 60, v6
	v_ashrrev_i32_e32 v67, 31, v66
	v_lshlrev_b64 v[66:67], 13, v[66:67]
	v_lshl_add_u64 v[82:83], v[4:5], 0, v[66:67]
	v_or_b32_e32 v66, 62, v6
	v_ashrrev_i32_e32 v67, 31, v66
	v_lshlrev_b64 v[66:67], 13, v[66:67]
	v_lshl_add_u64 v[84:85], v[4:5], 0, v[66:67]
	global_load_dword v69, v[70:71], off nt
	global_load_dword v68, v[72:73], off nt
	global_load_dword v67, v[74:75], off nt
	global_load_dword v66, v[76:77], off nt
	global_load_dword v65, v[78:79], off nt
	global_load_dword v6, v[80:81], off nt
	global_load_dword v5, v[82:83], off nt
	global_load_dword v4, v[84:85], off nt
	s_waitcnt vmcnt(62)
; #define LDS_WAIT() asm volatile("s_waitcnt lgkmcnt(0)" ::: "memory")
; template <int MODE>
; __device__ __forceinline__ void transpose_weight(const float* W, int K, int N, bf16_t* WT, LAS float* scr, int gw, int NGW, int lane, const float* gk = nullptr) {
;     ...
; #pragma unroll
;         for (int i = 0; i < 32; ++i) { const int kk = 2 * i + (lane >> 5); scr[kk * 33 + (lane & 31)] = cur[i]; }
;         LDS_WAIT(); asm volatile("" ::: "memory");
	ds_write2_b32 v93, v8, v9 offset1:66
	s_waitcnt vmcnt(60)
	ds_write2_b32 v93, v10, v11 offset0:132 offset1:198
	v_add_u32_e32 v8, 0x400, v93
	s_waitcnt vmcnt(58)
	ds_write2_b32 v8, v12, v13 offset0:8 offset1:74
	s_waitcnt vmcnt(56)
	ds_write2_b32 v8, v14, v15 offset0:140 offset1:206
	v_add_u32_e32 v8, 0x800, v93
	s_waitcnt vmcnt(54)
	ds_write2_b32 v8, v18, v19 offset0:16 offset1:82
	s_waitcnt vmcnt(52)
	ds_write2_b32 v8, v22, v23 offset0:148 offset1:214
	v_add_u32_e32 v8, 0xc00, v93
	s_waitcnt vmcnt(50)
	ds_write2_b32 v8, v24, v25 offset0:24 offset1:90
	s_waitcnt vmcnt(48)
	ds_write2_b32 v8, v26, v27 offset0:156 offset1:222
	v_add_u32_e32 v8, 0x1000, v93
	s_waitcnt vmcnt(46)
	ds_write2_b32 v8, v28, v29 offset0:32 offset1:98
	s_waitcnt vmcnt(44)
	ds_write2_b32 v8, v30, v32 offset0:164 offset1:230
	v_add_u32_e32 v8, 0x1400, v93
	s_waitcnt vmcnt(42)
	ds_write2_b32 v8, v33, v34 offset0:40 offset1:106
	s_waitcnt vmcnt(40)
	ds_write2_b32 v8, v35, v36 offset0:172 offset1:238
	v_add_u32_e32 v8, 0x1800, v93
	s_waitcnt vmcnt(38)
	ds_write2_b32 v8, v41, v42 offset0:48 offset1:114
	s_waitcnt vmcnt(36)
	ds_write2_b32 v8, v43, v44 offset0:180 offset1:246
	v_add_u32_e32 v8, 0x1c00, v93
	s_waitcnt vmcnt(34)
	ds_write2_b32 v8, v45, v46 offset0:56 offset1:122
	s_waitcnt vmcnt(32)
	s_branch .Ltw_join_10
